# early-DMA software-pipelined K-loops extended to half-width FFN-in tiles and runtime-K mixer-out GEMM (all 9 GEMM loops)
# speedup vs baseline: 1.0709x; 1.0037x over previous
; DI f32x16 zero16() { f32x16 z; for (int i = 0; i < 16; ++i) z[i] = 0.f; return z; }
; DI int launder(int x) { asm volatile("" : "+v"(x)); return x; }
; DI void wait_vm0() { asm volatile("s_waitcnt vmcnt(0)" ::: "memory"); }
;   DI void pre(int grow0, int gcol0, int lane, int w, char* lds) { xpass(0, grow0, gcol0, lane, w, lds); }
;     ...
;   const int tid = launder(threadIdx.x), lane = tid & 63, w = tid >> 6, wm = w % WM, wn = w / WM;
;   const int l31 = lane & 31, hh = lane >> 5;
;   f32x16 acc[2][NTW];
; #pragma unroll
;   for (int a = 0; a < 2; ++a)
; #pragma unroll
;     for (int b = 0; b < NTW; ++b) acc[a][b] = zero16();
;   const bf16_t* Ag = A + (size_t)row0 * lda; const bf16_t* Bg = Bt + (size_t)col0 * ldb;
;   const int wv = __builtin_amdgcn_readfirstlane(tid >> 6);
;   __syncthreads();
;   if (!pre) { stage_tile<BM, BK>(Ag, lda, lds, tid); stage_tile<BN, BK>(Bg, ldb, lds + ABYTES, tid); }
;   wait_vm0();
;   __syncthreads();
;   const int nk = K / BK;
; __global__ void __launch_bounds__(NT) fwd_megakernel(Params p) {
;     ...
;             for (int t = vb; t < 256; t += gridDim.x) {
;               const int x = t & 7, L = t >> 3; const int pm = 8 * x + (L & 7), pnh = L >> 3;
;               gemm_tile<4, 64, EpiSwiglu, 2>(p.Xb, D_, p.win[i * 2 + f], D_, D_, pm * 256, 5120 + pnh * 128, lds, e1);
.LBB0_387:
	s_bfe_u32 s6, s36, 0x30003
	s_lshl_b32 s3, s35, 19
	s_lshl_b32 s2, s6, 19
	s_and_b32 s3, s3, 0x1c00000
	s_or_b32 s37, s3, s2
	s_and_b32 s2, s34, 0xffffff80
	s_addk_i32 s2, 0x1400
	s_ashr_i32 s3, s2, 31
	s_lshl_b64 s[30:31], s[2:3], 11
	s_lshl_b32 s2, s36, 3
	s_and_b32 s2, s2, 56
	v_mov_b32_e32 v4, v216
	s_or_b32 s2, s2, s6
	s_lshl_b32 s6, s36, 1
	s_and_b32 s6, s6, 0xffffff80
	v_ashrrev_i32_e32 v0, 6, v4
	v_lshrrev_b32_e32 v2, 30, v0
	s_addk_i32 s6, 0x1400
	v_add_u32_e32 v6, v0, v2
	s_lshl_b32 s7, s2, 19
	v_ashrrev_i32_e32 v7, 2, v6
	s_add_u32 s42, s12, s7
	v_mul_i32_i24_e32 v2, 4, v7
	s_addc_u32 s43, s13, 0
	s_ashr_i32 s7, s6, 31
	v_sub_u32_e32 v9, v0, v2
	s_lshl_b64 s[44:45], s[6:7], 11
	v_readfirstlane_b32 s7, v0
	v_ashrrev_i32_e32 v0, 31, v4
	v_lshrrev_b32_e32 v2, 29, v0
	v_lshrrev_b32_e32 v0, 28, v0
	v_add_u32_e32 v0, v4, v0
	v_ashrrev_i32_e32 v0, 4, v0
	v_lshrrev_b32_e32 v5, 29, v0
	v_add_u32_e32 v2, v4, v2
	v_add_u32_e32 v5, v0, v5
	v_and_b32_e32 v3, 0xffffff8, v2
	v_and_b32_e32 v5, 0xffffff8, v5
	s_waitcnt lgkmcnt(0)
	s_add_u32 s44, s40, s44
	v_sub_u32_e32 v3, v4, v3
	v_sub_u32_e32 v0, v0, v5
	v_lshlrev_b32_e32 v2, 8, v2
	v_readfirstlane_b32 s46, v4
	s_addc_u32 s45, s41, s45
	v_xor_b32_e32 v0, v0, v3
	v_and_b32_e32 v2, 0xfffff800, v2
	s_lshl_b32 s46, s46, 4
	v_lshl_add_u32 v0, v0, 4, v2
	s_and_b32 s46, s46, 0xfffffc00
	v_lshl_add_u64 v[2:3], s[42:43], 0, v[0:1]
	s_mov_b32 m0, s46
	v_lshrrev_b32_e32 v8, 5, v4
	v_and_b32_e32 v10, 31, v4
	v_bfe_u32 v11, v4, 5, 1
	s_waitcnt vmcnt(0)
	s_barrier
	global_load_lds_dwordx4 v0, s[42:43]
	v_lshl_add_u64 v[4:5], v[2:3], 0, s[58:59]
	s_add_i32 m0, s46, 0x2000
	s_lshl_b32 s7, s7, 10
	global_load_lds_dwordx4 v[4:5], off
	v_lshl_add_u64 v[4:5], v[2:3], 0, s[48:49]
	s_add_i32 m0, s46, 0x4000
	v_lshl_add_u64 v[2:3], v[2:3], 0, s[50:51]
	global_load_lds_dwordx4 v[4:5], off
	s_add_i32 m0, s46, 0x6000
	v_bfe_u32 v4, v9, 25, 1
	global_load_lds_dwordx4 v[2:3], off
	v_lshl_add_u64 v[2:3], s[44:45], 0, v[0:1]
	s_add_i32 m0, s46, 0x8000
	v_lshl_add_u64 v[2:3], v[2:3], 0, s[58:59]
	global_load_lds_dwordx4 v0, s[44:45]
	s_add_i32 m0, s46, 0xa000
	s_add_u32 s42, s12, s37
	global_load_lds_dwordx4 v[2:3], off
	v_lshlrev_b32_e32 v2, 6, v9
	v_or_b32_e32 v2, v2, v10
	v_lshlrev_b32_e32 v70, 7, v2
	v_add_u32_e32 v5, v2, v4
	v_or_b32_e32 v2, 32, v2
	v_lshlrev_b32_e32 v71, 7, v2
	v_add_u32_e32 v2, v2, v4
	v_ashrrev_i32_e32 v4, 1, v2
	v_ashrrev_i32_e32 v2, 31, v2
	v_lshrrev_b32_e32 v2, 29, v2
	v_add_u32_e32 v2, v4, v2
	v_and_b32_e32 v2, -8, v2
	v_sub_u32_e32 v2, v4, v2
	v_bitop3_b32 v4, v2, v8, 1 bitop3:0x78
	v_lshl_or_b32 v3, v7, 6, v10
	v_ashrrev_i32_e32 v7, 1, v5
	v_ashrrev_i32_e32 v5, 31, v5
	v_lshlrev_b32_e32 v80, 4, v4
	v_lshrrev_b32_e32 v4, 31, v6
	v_lshrrev_b32_e32 v5, 29, v5
	v_lshlrev_b32_e32 v77, 7, v3
	v_add_u32_e32 v6, v3, v4
	v_or_b32_e32 v3, 32, v3
	v_add_u32_e32 v5, v7, v5
	v_lshlrev_b32_e32 v84, 7, v3
	v_add_u32_e32 v3, v3, v4
	v_and_b32_e32 v5, -8, v5
	v_ashrrev_i32_e32 v4, 1, v3
	v_ashrrev_i32_e32 v3, 31, v3
	v_sub_u32_e32 v5, v7, v5
	v_lshrrev_b32_e32 v3, 29, v3
	v_bitop3_b32 v7, v5, v8, 1 bitop3:0x78
	v_add_u32_e32 v3, v4, v3
	v_lshlrev_b32_e32 v76, 4, v7
	v_ashrrev_i32_e32 v7, 1, v6
	v_ashrrev_i32_e32 v6, 31, v6
	v_and_b32_e32 v3, -8, v3
	v_lshrrev_b32_e32 v6, 29, v6
	v_sub_u32_e32 v3, v4, v3
	v_add_u32_e32 v6, v7, v6
	v_bitop3_b32 v4, v3, v8, 1 bitop3:0x78
	v_and_b32_e32 v6, -8, v6
	v_lshlrev_b32_e32 v89, 4, v4
	v_bitop3_b32 v4, v5, v11, 2 bitop3:0x1e
	v_sub_u32_e32 v6, v7, v6
	v_lshlrev_b32_e32 v87, 4, v4
	v_bitop3_b32 v4, v2, v11, 2 bitop3:0x1e
	v_lshlrev_b32_e32 v88, 4, v4
	v_bitop3_b32 v4, v6, v11, 2 bitop3:0x1e
	v_lshlrev_b32_e32 v85, 4, v4
	v_bitop3_b32 v4, v3, v11, 2 bitop3:0x1e
	v_lshlrev_b32_e32 v86, 4, v4
	v_bitop3_b32 v4, v5, v11, 4 bitop3:0x1e
	v_lshlrev_b32_e32 v81, 4, v4
	v_bitop3_b32 v4, v2, v11, 4 bitop3:0x1e
	v_bitop3_b32 v2, v2, v11, 6 bitop3:0x1e
	v_lshlrev_b32_e32 v82, 4, v4
	v_bitop3_b32 v4, v6, v11, 4 bitop3:0x1e
	v_lshlrev_b32_e32 v75, 4, v2
	v_bitop3_b32 v2, v6, v11, 6 bitop3:0x1e
	s_addc_u32 s43, s13, 0
	s_waitcnt vmcnt(0)
	v_lshlrev_b32_e32 v78, 4, v4
	v_bitop3_b32 v4, v3, v11, 4 bitop3:0x1e
	v_lshlrev_b32_e32 v72, 4, v2
	v_bitop3_b32 v2, v3, v11, 6 bitop3:0x1e
	s_add_u32 s30, s40, s30
	v_bitop3_b32 v7, v6, v8, 1 bitop3:0x78
	v_lshlrev_b32_e32 v79, 4, v4
	v_bitop3_b32 v4, v5, v11, 6 bitop3:0x1e
	v_lshlrev_b32_e32 v73, 4, v2
	s_addc_u32 s31, s41, s31
	v_mov_b32_e32 v2, 0
	s_mov_b32 s3, 1
	v_lshlrev_b32_e32 v83, 4, v7
	v_lshlrev_b32_e32 v74, 4, v4
	v_lshl_add_u64 v[66:67], s[42:43], 0, v[0:1]
	v_lshl_add_u64 v[68:69], s[30:31], 0, v[0:1]
	s_mov_b64 s[30:31], 0
	v_mov_b32_e32 v3, v2
	v_mov_b32_e32 v4, v2
	v_mov_b32_e32 v5, v2
	v_mov_b32_e32 v6, v2
	v_mov_b32_e32 v7, v2
	v_mov_b32_e32 v8, v2
	v_mov_b32_e32 v9, v2
	v_mov_b32_e32 v10, v2
	v_mov_b32_e32 v11, v2
	v_mov_b32_e32 v12, v2
	v_mov_b32_e32 v13, v2
	v_mov_b32_e32 v14, v2
	v_mov_b32_e32 v15, v2
	v_mov_b32_e32 v16, v2
	v_mov_b32_e32 v17, v2
	v_mov_b32_e32 v18, v2
	v_mov_b32_e32 v19, v2
	v_mov_b32_e32 v20, v2
	v_mov_b32_e32 v21, v2
	v_mov_b32_e32 v22, v2
	v_mov_b32_e32 v23, v2
	v_mov_b32_e32 v24, v2
	v_mov_b32_e32 v25, v2
	v_mov_b32_e32 v26, v2
	v_mov_b32_e32 v27, v2
	v_mov_b32_e32 v28, v2
	v_mov_b32_e32 v29, v2
	v_mov_b32_e32 v30, v2
	v_mov_b32_e32 v31, v2
	v_mov_b32_e32 v32, v2
	v_mov_b32_e32 v33, v2
	v_mov_b32_e32 v34, v2
	v_mov_b32_e32 v35, v2
	v_mov_b32_e32 v36, v2
	v_mov_b32_e32 v37, v2
	v_mov_b32_e32 v38, v2
	v_mov_b32_e32 v39, v2
	v_mov_b32_e32 v40, v2
	v_mov_b32_e32 v41, v2
	v_mov_b32_e32 v42, v2
	v_mov_b32_e32 v43, v2
	v_mov_b32_e32 v44, v2
	v_mov_b32_e32 v45, v2
	v_mov_b32_e32 v46, v2
	v_mov_b32_e32 v47, v2
	v_mov_b32_e32 v48, v2
	v_mov_b32_e32 v49, v2
	v_mov_b32_e32 v50, v2
	v_mov_b32_e32 v51, v2
	v_mov_b32_e32 v52, v2
	v_mov_b32_e32 v53, v2
	v_mov_b32_e32 v54, v2
	v_mov_b32_e32 v55, v2
	v_mov_b32_e32 v56, v2
	v_mov_b32_e32 v57, v2
	v_mov_b32_e32 v58, v2
	v_mov_b32_e32 v59, v2
	v_mov_b32_e32 v60, v2
	v_mov_b32_e32 v61, v2
	v_mov_b32_e32 v62, v2
	v_mov_b32_e32 v63, v2
	v_mov_b32_e32 v64, v2
	v_mov_b32_e32 v65, v2
	s_waitcnt vmcnt(0) lgkmcnt(0)
	s_barrier
; DI f32x16 mfma(bf16x8 a, bf16x8 b, f32x16 c) { return __builtin_amdgcn_mfma_f32_32x32x16_bf16(a, b, c, 0, 0, 0); }
; template <int BK> DI int swz(int row) { constexpr int CPR = BK / 8; return (row / (16 / CPR)) % CPR; }
; DI void wait_vm0() { asm volatile("s_waitcnt vmcnt(0)" ::: "memory"); }
;   DI void pre(int grow0, int gcol0, int lane, int w, char* lds) { xpass(0, grow0, gcol0, lane, w, lds); }
;     ...
;   for (int kt = 0; kt < nk; ++kt) {
;     char* cur = lds + (kt & 1) * STG; char* nxt = lds + ((kt + 1) & 1) * STG;
;     const bool more = kt + 1 < nk;
;     const bf16_t* An = Ag + (kt + 1) * BK; const bf16_t* Bn = Bg + (kt + 1) * BK;
;     if (!more) epi.pre(row0 + wm * 64, col0 + wn * (32 * NTW), lane, w, lds);
;     bf16x8 fa[2][2], fb[2][NTW];
; #pragma unroll
;     for (int mt = 0; mt < 2; ++mt) { int row = wm * 64 + mt * 32 + l31; fa[0][mt] = *(const bf16x8*)(cur + row * (BK * 2) + ((hh ^ swz<BK>(row)) << 4)); }
; #pragma unroll
;     for (int nt = 0; nt < NTW; ++nt) { int row = wn * (32 * NTW) + nt * 32 + l31; fb[0][nt] = *(const bf16x8*)(cur + ABYTES + row * (BK * 2) + ((hh ^ swz<BK>(row)) << 4)); }
; #pragma unroll
;     for (int kk = 0; kk < NKK; ++kk) {
;       if (kk + 1 < NKK) {
;         const int ch = (kk + 1) * 2 + hh;
; #pragma unroll
;         for (int mt = 0; mt < 2; ++mt) { int row = wm * 64 + mt * 32 + l31; fa[(kk + 1) & 1][mt] = *(const bf16x8*)(cur + row * (BK * 2) + ((ch ^ swz<BK>(row)) << 4)); }
; #pragma unroll
;         for (int nt = 0; nt < NTW; ++nt) { int row = wn * (32 * NTW) + nt * 32 + l31; fb[(kk + 1) & 1][nt] = *(const bf16x8*)(cur + ABYTES + row * (BK * 2) + ((ch ^ swz<BK>(row)) << 4)); }
;       }
;       if (more) {
; #pragma unroll
;         for (int q = 0; q < PPK; ++q) {
;           const int pi = kk * PPK + q;
;           if (pi < NPA) stage_piece<BM, BK>(An, lda, nxt, tid, pi, wv);
;           else if (pi < NP) stage_piece<BN, BK>(Bn, ldb, nxt + ABYTES, tid, pi - NPA, wv);
;         }
;       }
;       __builtin_amdgcn_s_setprio(1);
; #pragma unroll
;       for (int mt = 0; mt < 2; ++mt)
; #pragma unroll
;         for (int nt = 0; nt < NTW; ++nt) acc[mt][nt] = mfma(fa[kk & 1][mt], fb[kk & 1][nt], acc[mt][nt]);
;       __builtin_amdgcn_s_setprio(0);
;       __builtin_amdgcn_sched_barrier(0);
;     }
;     wait_vm0();
;     __syncthreads();
	v_add_u32_e32 v90, v70, v76
	v_add_u32_e32 v94, v71, v80
	ds_read_b128 v[90:93], v90
	v_add_u32_e32 v98, v77, v83
	ds_read_b128 v[94:97], v94
	v_add_u32_e32 v102, v84, v89
	ds_read_b128 v[98:101], v98 offset:32768
	ds_read_b128 v[102:105], v102 offset:32768
	s_bitcmp1_b32 s3, 0
	s_cselect_b32 s42, 0xc000, 0
	s_add_i32 s37, s7, s42
	v_lshl_add_u64 v[122:123], v[66:67], 0, s[30:31]
	v_lshl_add_u64 v[124:125], v[68:69], 0, s[30:31]
	s_mov_b32 m0, s37
	v_lshl_add_u64 v[126:127], v[122:123], 0, s[28:29]
	global_load_lds_dwordx4 v[126:127], off
	s_add_i32 m0, s37, 0x2000
	v_lshl_add_u64 v[126:127], v[122:123], 0, s[24:25]
	global_load_lds_dwordx4 v[126:127], off
	s_add_i32 m0, s37, 0x4000
	v_lshl_add_u64 v[126:127], v[122:123], 0, s[26:27]
	global_load_lds_dwordx4 v[126:127], off
	s_add_i32 m0, s37, 0x6000
	v_lshl_add_u64 v[126:127], v[122:123], 0, s[38:39]
	global_load_lds_dwordx4 v[126:127], off
	s_add_i32 m0, s37, 0x8000
	v_lshl_add_u64 v[126:127], v[124:125], 0, s[28:29]
	global_load_lds_dwordx4 v[126:127], off
	s_add_i32 m0, s37, 0xa000
	v_lshl_add_u64 v[126:127], v[124:125], 0, s[24:25]
	global_load_lds_dwordx4 v[126:127], off
.LBB0_388:
	s_bitcmp1_b32 s3, 0
	s_cselect_b32 s100, 0, 0xc000
	s_cselect_b32 s42, 0xc000, 0
	v_add3_u32 v106, s100, v70, v87
	v_add3_u32 v110, s100, v71, v88
	ds_read_b128 v[106:109], v106
	v_add3_u32 v114, s100, v77, v85
	ds_read_b128 v[110:113], v110
	v_add3_u32 v118, s100, v84, v86
	ds_read_b128 v[114:117], v114 offset:32768
	ds_read_b128 v[118:121], v118 offset:32768
	s_waitcnt lgkmcnt(4)
	v_mfma_f32_32x32x16_bf16 v[50:65], v[90:93], v[98:101], v[50:65]
	v_mfma_f32_32x32x16_bf16 v[34:49], v[90:93], v[102:105], v[34:49]
	v_mfma_f32_32x32x16_bf16 v[18:33], v[94:97], v[98:101], v[18:33]
	v_mfma_f32_32x32x16_bf16 v[2:17], v[94:97], v[102:105], v[2:17]
	v_add3_u32 v90, s100, v70, v81
	v_add3_u32 v94, s100, v71, v82
	ds_read_b128 v[90:93], v90
	v_add3_u32 v98, s100, v77, v78
	ds_read_b128 v[94:97], v94
	v_add3_u32 v102, s100, v84, v79
	ds_read_b128 v[98:101], v98 offset:32768
	ds_read_b128 v[102:105], v102 offset:32768
	s_waitcnt lgkmcnt(4)
	v_mfma_f32_32x32x16_bf16 v[50:65], v[106:109], v[114:117], v[50:65]
	v_mfma_f32_32x32x16_bf16 v[34:49], v[106:109], v[118:121], v[34:49]
	v_mfma_f32_32x32x16_bf16 v[18:33], v[110:113], v[114:117], v[18:33]
	v_mfma_f32_32x32x16_bf16 v[2:17], v[110:113], v[118:121], v[2:17]
	v_add3_u32 v106, s100, v70, v74
	v_add3_u32 v110, s100, v71, v75
	ds_read_b128 v[106:109], v106
	v_add3_u32 v114, s100, v77, v72
	ds_read_b128 v[110:113], v110
	v_add3_u32 v118, s100, v84, v73
	ds_read_b128 v[114:117], v114 offset:32768
	ds_read_b128 v[118:121], v118 offset:32768
	s_waitcnt lgkmcnt(4)
	v_mfma_f32_32x32x16_bf16 v[50:65], v[90:93], v[98:101], v[50:65]
	v_mfma_f32_32x32x16_bf16 v[34:49], v[90:93], v[102:105], v[34:49]
	v_mfma_f32_32x32x16_bf16 v[18:33], v[94:97], v[98:101], v[18:33]
	v_mfma_f32_32x32x16_bf16 v[2:17], v[94:97], v[102:105], v[2:17]
	s_add_u32 s30, s30, 0x80
	s_addc_u32 s31, s31, 0
	s_add_i32 s3, s3, 1
	s_waitcnt vmcnt(0) lgkmcnt(0)
	s_barrier
	v_add3_u32 v90, s42, v70, v76
	v_add3_u32 v94, s42, v71, v80
	ds_read_b128 v[90:93], v90
	v_add3_u32 v98, s42, v77, v83
	ds_read_b128 v[94:97], v94
	v_add3_u32 v102, s42, v84, v89
	ds_read_b128 v[98:101], v98 offset:32768
	ds_read_b128 v[102:105], v102 offset:32768
	s_cmpk_lg_i32 s30, 0x780
	s_cbranch_scc0 .Lk388_exit
	s_add_i32 s37, s7, s100
	v_lshl_add_u64 v[122:123], v[66:67], 0, s[30:31]
	v_lshl_add_u64 v[124:125], v[68:69], 0, s[30:31]
	s_mov_b32 m0, s37
	v_lshl_add_u64 v[126:127], v[122:123], 0, s[28:29]
	v_mfma_f32_32x32x16_bf16 v[50:65], v[106:109], v[114:117], v[50:65]
	global_load_lds_dwordx4 v[126:127], off
	v_lshl_add_u64 v[126:127], v[122:123], 0, s[24:25]
	s_add_i32 m0, s37, 0x2000
	v_mfma_f32_32x32x16_bf16 v[34:49], v[106:109], v[118:121], v[34:49]
	global_load_lds_dwordx4 v[126:127], off
	v_lshl_add_u64 v[126:127], v[122:123], 0, s[26:27]
	s_add_i32 m0, s37, 0x4000
	v_mfma_f32_32x32x16_bf16 v[18:33], v[110:113], v[114:117], v[18:33]
	global_load_lds_dwordx4 v[126:127], off
	v_lshl_add_u64 v[126:127], v[122:123], 0, s[38:39]
	s_add_i32 m0, s37, 0x6000
	v_mfma_f32_32x32x16_bf16 v[2:17], v[110:113], v[118:121], v[2:17]
	global_load_lds_dwordx4 v[126:127], off
	s_add_i32 m0, s37, 0x8000
	v_lshl_add_u64 v[126:127], v[124:125], 0, s[28:29]
	global_load_lds_dwordx4 v[126:127], off
	s_add_i32 m0, s37, 0xa000
	v_lshl_add_u64 v[126:127], v[124:125], 0, s[24:25]
	global_load_lds_dwordx4 v[126:127], off
	s_branch .LBB0_388
; DI f32x16 mfma(bf16x8 a, bf16x8 b, f32x16 c) { return __builtin_amdgcn_mfma_f32_32x32x16_bf16(a, b, c, 0, 0, 0); }
;     ...
;   for (int kt = 0; kt < nk; ++kt) {
;     char* cur = lds + (kt & 1) * STG; char* nxt = lds + ((kt + 1) & 1) * STG;
;     const bool more = kt + 1 < nk;
;     const bf16_t* An = Ag + (kt + 1) * BK; const bf16_t* Bn = Bg + (kt + 1) * BK;
;     if (!more) epi.pre(row0 + wm * 64, col0 + wn * (32 * NTW), lane, w, lds);
;     bf16x8 fa[2][2], fb[2][NTW];
; #pragma unroll
;     for (int mt = 0; mt < 2; ++mt) { int row = wm * 64 + mt * 32 + l31; fa[0][mt] = *(const bf16x8*)(cur + row * (BK * 2) + ((hh ^ swz<BK>(row)) << 4)); }
; #pragma unroll
;     for (int nt = 0; nt < NTW; ++nt) { int row = wn * (32 * NTW) + nt * 32 + l31; fb[0][nt] = *(const bf16x8*)(cur + ABYTES + row * (BK * 2) + ((hh ^ swz<BK>(row)) << 4)); }
; #pragma unroll
;     for (int kk = 0; kk < NKK; ++kk) {
;       if (kk + 1 < NKK) {
;         const int ch = (kk + 1) * 2 + hh;
; #pragma unroll
;         for (int mt = 0; mt < 2; ++mt) { int row = wm * 64 + mt * 32 + l31; fa[(kk + 1) & 1][mt] = *(const bf16x8*)(cur + row * (BK * 2) + ((ch ^ swz<BK>(row)) << 4)); }
; #pragma unroll
;         for (int nt = 0; nt < NTW; ++nt) { int row = wn * (32 * NTW) + nt * 32 + l31; fb[(kk + 1) & 1][nt] = *(const bf16x8*)(cur + ABYTES + row * (BK * 2) + ((ch ^ swz<BK>(row)) << 4)); }
;       }
;       if (more) {
; #pragma unroll
;         for (int q = 0; q < PPK; ++q) {
;           const int pi = kk * PPK + q;
;           if (pi < NPA) stage_piece<BM, BK>(An, lda, nxt, tid, pi, wv);
;           else if (pi < NP) stage_piece<BN, BK>(Bn, ldb, nxt + ABYTES, tid, pi - NPA, wv);
;         }
;       }
;       __builtin_amdgcn_s_setprio(1);
; #pragma unroll
;       for (int mt = 0; mt < 2; ++mt)
; #pragma unroll
;         for (int nt = 0; nt < NTW; ++nt) acc[mt][nt] = mfma(fa[kk & 1][mt], fb[kk & 1][nt], acc[mt][nt]);
;       __builtin_amdgcn_s_setprio(0);
;       __builtin_amdgcn_sched_barrier(0);
;     }
;     wait_vm0();
;     __syncthreads();
;   }
;   if (has_next) { const int tid3 = launder(threadIdx.x); stage_tile<BM, BK>(A + (size_t)row0n * lda, lda, lds, tid3); stage_tile<BN, BK>(Bt + (size_t)col0n * ldb, ldb, lds + ABYTES, tid3); }
;   { const int tid2 = launder(threadIdx.x); epi(acc, row0 + (((tid2 >> 6) % WM) * 64), col0 + (((tid2 >> 6) / WM) * (32 * NTW)), tid2 & 63, tid2 >> 6, lds); }
.Lk388_exit:
	v_mfma_f32_32x32x16_bf16 v[50:65], v[106:109], v[114:117], v[50:65]
	v_mfma_f32_32x32x16_bf16 v[34:49], v[106:109], v[118:121], v[34:49]
	v_mfma_f32_32x32x16_bf16 v[18:33], v[110:113], v[114:117], v[18:33]
	v_mfma_f32_32x32x16_bf16 v[2:17], v[110:113], v[118:121], v[2:17]
	s_waitcnt lgkmcnt(0)
	v_add_u32_e32 v0, v70, v76
	v_add_u32_e32 v76, v71, v80
	ds_read_b128 v[66:69], v0 offset:49152
	ds_read_b128 v[90:93], v76 offset:49152
	v_add_u32_e32 v0, 0x14000, v77
	v_add_u32_e32 v76, v0, v83
	v_add_u32_e32 v114, 0x14000, v84
	v_add_u32_e32 v77, v114, v89
	ds_read_b128 v[94:97], v76
	ds_read_b128 v[98:101], v77
	v_add_u32_e32 v76, v70, v87
	v_add_u32_e32 v77, v71, v88
	ds_read_b128 v[102:105], v76 offset:49152
	ds_read_b128 v[106:109], v77 offset:49152
	v_add_u32_e32 v76, v0, v85
	v_add_u32_e32 v77, v114, v86
	ds_read_b128 v[84:87], v76
	ds_read_b128 v[110:113], v77
	s_lshl_b32 s2, s2, 8
	s_setprio 1
	s_waitcnt lgkmcnt(5)
	v_mfma_f32_32x32x16_bf16 v[50:65], v[66:69], v[94:97], v[50:65]
	s_waitcnt lgkmcnt(4)
	v_mfma_f32_32x32x16_bf16 v[34:49], v[66:69], v[98:101], v[34:49]
	v_mfma_f32_32x32x16_bf16 v[18:33], v[90:93], v[94:97], v[18:33]
	v_mfma_f32_32x32x16_bf16 v[2:17], v[90:93], v[98:101], v[2:17]
	s_setprio 0
	v_add_u32_e32 v66, v70, v81
	v_add_u32_e32 v76, v71, v82
	ds_read_b128 v[66:69], v66 offset:49152
	ds_read_b128 v[80:83], v76 offset:49152
	v_add_u32_e32 v76, v0, v78
	v_add_u32_e32 v88, v114, v79
	ds_read_b128 v[76:79], v76
	ds_read_b128 v[88:91], v88
	s_setprio 1
	s_waitcnt lgkmcnt(5)
	v_mfma_f32_32x32x16_bf16 v[50:65], v[102:105], v[84:87], v[50:65]
	s_waitcnt lgkmcnt(4)
	v_mfma_f32_32x32x16_bf16 v[34:49], v[102:105], v[110:113], v[34:49]
	v_mfma_f32_32x32x16_bf16 v[18:33], v[106:109], v[84:87], v[18:33]
	v_mfma_f32_32x32x16_bf16 v[2:17], v[106:109], v[110:113], v[2:17]
	s_setprio 0
	v_add_u32_e32 v70, v70, v74
	v_add_u32_e32 v71, v71, v75
	v_add_u32_e32 v0, v0, v72
	ds_read_b128 v[84:87], v70 offset:49152
	ds_read_b128 v[92:95], v71 offset:49152
	v_add_u32_e32 v74, v114, v73
	ds_read_b128 v[70:73], v0
	ds_read_b128 v[96:99], v74
	s_setprio 1
	s_waitcnt lgkmcnt(5)
	v_mfma_f32_32x32x16_bf16 v[50:65], v[66:69], v[76:79], v[50:65]
	s_waitcnt lgkmcnt(4)
	v_mfma_f32_32x32x16_bf16 v[34:49], v[66:69], v[88:91], v[34:49]
	v_mfma_f32_32x32x16_bf16 v[18:33], v[80:83], v[76:79], v[18:33]
	v_mfma_f32_32x32x16_bf16 v[2:17], v[80:83], v[88:91], v[2:17]
	s_setprio 0
	s_setprio 1
	s_waitcnt lgkmcnt(1)
	v_mfma_f32_32x32x16_bf16 v[50:65], v[84:87], v[70:73], v[50:65]
	s_waitcnt lgkmcnt(0)
	v_mfma_f32_32x32x16_bf16 v[34:49], v[84:87], v[96:99], v[34:49]
	v_mfma_f32_32x32x16_bf16 v[18:33], v[92:95], v[70:73], v[18:33]
	v_mfma_f32_32x32x16_bf16 v[2:17], v[92:95], v[96:99], v[2:17]
	s_setprio 0
	v_mov_b32_e32 v0, v216
	s_waitcnt vmcnt(0)
	s_barrier
	s_add_i32 s36, s36, s94
	v_ashrrev_i32_e32 v66, 6, v0
	v_lshrrev_b32_e32 v67, 30, v66
	v_add_u32_e32 v67, v66, v67
	v_ashrrev_i32_e32 v67, 2, v67
	v_mul_i32_i24_e32 v68, 4, v67
	v_sub_u32_e32 v68, v66, v68
	v_lshl_add_u32 v66, v67, 6, s6
	v_ashrrev_i32_e32 v66, 1, v66
	v_and_or_b32 v66, v0, 31, v66
	v_lshrrev_b32_e32 v0, 3, v0
	v_and_or_b32 v0, v0, 4, s2
	v_lshl_add_u32 v0, v68, 6, v0
	v_mul_f32_e32 v68, 0xbfb8aa3b, v50
	v_exp_f32_e32 v68, v68
	s_movk_i32 s2, 0x1600
	v_ashrrev_i32_e32 v67, 31, v66
	v_lshl_add_u64 v[66:67], v[66:67], 1, s[76:77]
	v_add_f32_e32 v68, 1.0, v68
	v_rcp_f32_e32 v68, v68
	s_add_i32 s35, s35, s63
	v_mul_f32_e32 v50, v50, v68
	v_mul_lo_u32 v68, v0, s2
	v_mul_f32_e32 v0, 0xbfb8aa3b, v51
	v_exp_f32_e32 v0, v0
	v_mul_f32_e32 v34, v34, v50
	v_ashrrev_i32_e32 v69, 31, v68
	v_cvt_pk_bf16_f32 v34, v34, s0
	v_add_f32_e32 v0, 1.0, v0
	v_rcp_f32_e32 v0, v0
	v_lshl_add_u64 v[66:67], v[66:67], 0, v[68:69]
	s_movk_i32 s2, 0x1000
	global_store_short v[66:67], v34, off
	v_mul_f32_e32 v0, v51, v0
	v_mul_f32_e32 v0, v35, v0
	v_add_co_u32_e32 v34, vcc, s2, v66
	v_cvt_pk_bf16_f32 v0, v0, s0
	s_nop 0
	v_addc_co_u32_e32 v35, vcc, 0, v67, vcc
	global_store_short v[34:35], v0, off offset:1536
	v_mul_f32_e32 v0, 0xbfb8aa3b, v52
	v_exp_f32_e32 v0, v0
	s_movk_i32 s2, 0x2000
	v_add_co_u32_e32 v34, vcc, s2, v66
	v_add_f32_e32 v0, 1.0, v0
	v_rcp_f32_e32 v0, v0
	v_addc_co_u32_e32 v35, vcc, 0, v67, vcc
	s_mov_b32 s2, 0xb000
	v_mul_f32_e32 v0, v52, v0
	v_mul_f32_e32 v0, v36, v0
	v_cvt_pk_bf16_f32 v0, v0, s0
	global_store_short v[34:35], v0, off offset:3072
	v_mul_f32_e32 v0, 0xbfb8aa3b, v53
	v_exp_f32_e32 v0, v0
	v_add_co_u32_e32 v34, vcc, s91, v66
	v_add_f32_e32 v0, 1.0, v0
	v_rcp_f32_e32 v0, v0
	v_addc_co_u32_e32 v35, vcc, 0, v67, vcc
	v_mul_f32_e32 v0, v53, v0
	v_mul_f32_e32 v0, v37, v0
	v_cvt_pk_bf16_f32 v0, v0, s0
	global_store_short v[34:35], v0, off offset:512
	v_mul_f32_e32 v0, 0xbfb8aa3b, v54
	v_exp_f32_e32 v0, v0
	v_add_co_u32_e32 v34, vcc, s2, v66
	s_mov_b32 s2, 0xc000
	v_add_f32_e32 v0, 1.0, v0
	v_rcp_f32_e32 v0, v0
	v_addc_co_u32_e32 v35, vcc, 0, v67, vcc
	v_mul_f32_e32 v0, v54, v0
	v_mul_f32_e32 v0, v38, v0
	v_cvt_pk_bf16_f32 v0, v0, s0
	global_store_short v[34:35], v0, off
	v_mul_f32_e32 v0, 0xbfb8aa3b, v55
	v_exp_f32_e32 v0, v0
	v_add_co_u32_e32 v34, vcc, s2, v66
	s_mov_b32 s2, 0xd000
	v_add_f32_e32 v0, 1.0, v0
	v_rcp_f32_e32 v0, v0
	v_addc_co_u32_e32 v35, vcc, 0, v67, vcc
	v_mul_f32_e32 v0, v55, v0
	v_mul_f32_e32 v0, v39, v0
	v_cvt_pk_bf16_f32 v0, v0, s0
	global_store_short v[34:35], v0, off offset:1536
	v_mul_f32_e32 v0, 0xbfb8aa3b, v56
	v_exp_f32_e32 v0, v0
	v_add_co_u32_e32 v34, vcc, s2, v66
	s_mov_b32 s2, 0xf000
	v_add_f32_e32 v0, 1.0, v0
	v_rcp_f32_e32 v0, v0
	v_addc_co_u32_e32 v35, vcc, 0, v67, vcc
	v_mul_f32_e32 v0, v56, v0
	v_mul_f32_e32 v0, v40, v0
	v_cvt_pk_bf16_f32 v0, v0, s0
; DI bf16_t f2bf(float x) { return (bf16_t)(pack2(x, 0.f) & 0xffffu); }
; DI int crow(int i, int hh) { return (i & 3) + 8 * (i >> 2) + 4 * hh; }
;   template <int NTW>
;   DI void operator()(f32x16 (&acc)[2][NTW], int grow0, int gcol0, int lane, int w, char* lds) {
;     const int l31 = lane & 31, hh = lane >> 5;
; #pragma unroll
;     for (int mt = 0; mt < 2; ++mt)
; #pragma unroll
;       for (int pr = 0; pr < NTW / 2; ++pr) {
;         const int col = (gcol0 / 64 + pr) * 32 + l31;
; #pragma unroll
;         for (int i = 0; i < 16; ++i) {
;           float g = acc[mt][2 * pr][i], u = acc[mt][2 * pr + 1][i];
;           float v = g * __builtin_amdgcn_rcpf(1.f + __expf(-g)) * u;
;           int row = grow0 + mt * 32 + crow(i, hh);
;           H[(size_t)row * F_ + col] = f2bf(v);
;         }
	global_store_short v[34:35], v0, off offset:3072
	v_mul_f32_e32 v0, 0xbfb8aa3b, v57
	v_exp_f32_e32 v0, v0
	v_add_co_u32_e32 v34, vcc, s2, v66
	s_mov_b32 s2, 0x16000
	v_add_f32_e32 v0, 1.0, v0
	v_rcp_f32_e32 v0, v0
	v_addc_co_u32_e32 v35, vcc, 0, v67, vcc
	v_mul_f32_e32 v0, v57, v0
	v_mul_f32_e32 v0, v41, v0
	v_cvt_pk_bf16_f32 v0, v0, s0
	global_store_short v[34:35], v0, off offset:512
	v_mul_f32_e32 v0, 0xbfb8aa3b, v58
	v_exp_f32_e32 v0, v0
	v_add_co_u32_e32 v34, vcc, s2, v66
	s_mov_b32 s2, 0x17000
	v_add_f32_e32 v0, 1.0, v0
	v_rcp_f32_e32 v0, v0
	v_addc_co_u32_e32 v35, vcc, 0, v67, vcc
	v_mul_f32_e32 v0, v58, v0
	v_mul_f32_e32 v0, v42, v0
	v_cvt_pk_bf16_f32 v0, v0, s0
	global_store_short v[34:35], v0, off
	v_mul_f32_e32 v0, 0xbfb8aa3b, v59
	v_exp_f32_e32 v0, v0
	v_add_co_u32_e32 v34, vcc, s2, v66
	s_mov_b32 s2, 0x18000
	v_add_f32_e32 v0, 1.0, v0
	v_rcp_f32_e32 v0, v0
	v_addc_co_u32_e32 v35, vcc, 0, v67, vcc
	v_mul_f32_e32 v0, v59, v0
	v_mul_f32_e32 v0, v43, v0
	v_cvt_pk_bf16_f32 v0, v0, s0
	global_store_short v[34:35], v0, off offset:1536
	v_mul_f32_e32 v0, 0xbfb8aa3b, v60
	v_exp_f32_e32 v0, v0
	v_add_co_u32_e32 v34, vcc, s2, v66
	s_mov_b32 s2, 0x1a000
	v_add_f32_e32 v0, 1.0, v0
	v_rcp_f32_e32 v0, v0
	v_addc_co_u32_e32 v35, vcc, 0, v67, vcc
	v_mul_f32_e32 v0, v60, v0
	v_mul_f32_e32 v0, v44, v0
	v_cvt_pk_bf16_f32 v0, v0, s0
	global_store_short v[34:35], v0, off offset:3072
	v_mul_f32_e32 v0, 0xbfb8aa3b, v61
	v_exp_f32_e32 v0, v0
	v_add_co_u32_e32 v34, vcc, s2, v66
	s_mov_b32 s2, 0x21000
	v_add_f32_e32 v0, 1.0, v0
	v_rcp_f32_e32 v0, v0
	v_addc_co_u32_e32 v35, vcc, 0, v67, vcc
	v_mul_f32_e32 v0, v61, v0
	v_mul_f32_e32 v0, v45, v0
	v_cvt_pk_bf16_f32 v0, v0, s0
	global_store_short v[34:35], v0, off offset:512
	v_mul_f32_e32 v0, 0xbfb8aa3b, v62
	v_exp_f32_e32 v0, v0
	v_add_co_u32_e32 v34, vcc, s2, v66
	s_mov_b32 s2, 0x22000
	v_add_f32_e32 v0, 1.0, v0
	v_rcp_f32_e32 v0, v0
	v_addc_co_u32_e32 v35, vcc, 0, v67, vcc
	v_mul_f32_e32 v0, v62, v0
	v_mul_f32_e32 v0, v46, v0
	v_cvt_pk_bf16_f32 v0, v0, s0
	global_store_short v[34:35], v0, off
	v_mul_f32_e32 v0, 0xbfb8aa3b, v63
	v_exp_f32_e32 v0, v0
	v_add_co_u32_e32 v34, vcc, s2, v66
	s_mov_b32 s2, 0x23000
	v_add_f32_e32 v0, 1.0, v0
	v_rcp_f32_e32 v0, v0
	v_addc_co_u32_e32 v35, vcc, 0, v67, vcc
	v_mul_f32_e32 v0, v63, v0
	v_mul_f32_e32 v0, v47, v0
	v_cvt_pk_bf16_f32 v0, v0, s0
	global_store_short v[34:35], v0, off offset:1536
	v_mul_f32_e32 v0, 0xbfb8aa3b, v64
	v_exp_f32_e32 v0, v0
	v_add_co_u32_e32 v34, vcc, s2, v66
	s_mov_b32 s2, 0x25000
	v_add_f32_e32 v0, 1.0, v0
	v_rcp_f32_e32 v0, v0
	v_addc_co_u32_e32 v35, vcc, 0, v67, vcc
	v_mul_f32_e32 v0, v64, v0
	v_mul_f32_e32 v0, v48, v0
	v_cvt_pk_bf16_f32 v0, v0, s0
	global_store_short v[34:35], v0, off offset:3072
	v_mul_f32_e32 v0, 0xbfb8aa3b, v65
	v_exp_f32_e32 v0, v0
	v_add_co_u32_e32 v34, vcc, s2, v66
	s_mov_b32 s2, 0x2c000
	v_add_f32_e32 v0, 1.0, v0
	v_rcp_f32_e32 v0, v0
	v_addc_co_u32_e32 v35, vcc, 0, v67, vcc
	v_mul_f32_e32 v0, v65, v0
	v_mul_f32_e32 v0, v49, v0
	v_cvt_pk_bf16_f32 v0, v0, s0
	global_store_short v[34:35], v0, off offset:512
	v_mul_f32_e32 v0, 0xbfb8aa3b, v18
	v_exp_f32_e32 v0, v0
	v_add_co_u32_e32 v34, vcc, s2, v66
	s_mov_b32 s2, 0x2d000
	v_add_f32_e32 v0, 1.0, v0
	v_rcp_f32_e32 v0, v0
	v_addc_co_u32_e32 v35, vcc, 0, v67, vcc
	v_mul_f32_e32 v0, v18, v0
	v_mul_f32_e32 v0, v2, v0
	v_cvt_pk_bf16_f32 v0, v0, s0
	global_store_short v[34:35], v0, off
	v_mul_f32_e32 v0, 0xbfb8aa3b, v19
	v_exp_f32_e32 v0, v0
	v_add_co_u32_e32 v2, vcc, s2, v66
	s_mov_b32 s2, 0x2e000
	v_add_f32_e32 v0, 1.0, v0
	v_rcp_f32_e32 v0, v0
	s_nop 0
	v_mul_f32_e32 v0, v19, v0
	v_mul_f32_e32 v0, v3, v0
	v_cvt_pk_bf16_f32 v0, v0, s0
	v_addc_co_u32_e32 v3, vcc, 0, v67, vcc
	global_store_short v[2:3], v0, off offset:1536
	v_mul_f32_e32 v0, 0xbfb8aa3b, v20
	v_exp_f32_e32 v0, v0
	v_add_co_u32_e32 v2, vcc, s2, v66
	s_mov_b32 s2, 0x30000
	v_add_f32_e32 v0, 1.0, v0
	v_rcp_f32_e32 v0, v0
	v_addc_co_u32_e32 v3, vcc, 0, v67, vcc
	v_mul_f32_e32 v0, v20, v0
	v_mul_f32_e32 v0, v4, v0
	v_cvt_pk_bf16_f32 v0, v0, s0
	global_store_short v[2:3], v0, off offset:3072
	v_mul_f32_e32 v0, 0xbfb8aa3b, v21
	v_exp_f32_e32 v0, v0
	v_add_co_u32_e32 v2, vcc, s2, v66
	s_mov_b32 s2, 0x37000
	v_add_f32_e32 v0, 1.0, v0
; DI bf16_t f2bf(float x) { return (bf16_t)(pack2(x, 0.f) & 0xffffu); }
; DI int crow(int i, int hh) { return (i & 3) + 8 * (i >> 2) + 4 * hh; }
;   template <int NTW>
;   DI void operator()(f32x16 (&acc)[2][NTW], int grow0, int gcol0, int lane, int w, char* lds) {
;     const int l31 = lane & 31, hh = lane >> 5;
; #pragma unroll
;     for (int mt = 0; mt < 2; ++mt)
; #pragma unroll
;       for (int pr = 0; pr < NTW / 2; ++pr) {
;         const int col = (gcol0 / 64 + pr) * 32 + l31;
; #pragma unroll
;         for (int i = 0; i < 16; ++i) {
;           float g = acc[mt][2 * pr][i], u = acc[mt][2 * pr + 1][i];
;           float v = g * __builtin_amdgcn_rcpf(1.f + __expf(-g)) * u;
;           int row = grow0 + mt * 32 + crow(i, hh);
;           H[(size_t)row * F_ + col] = f2bf(v);
;         }
; __global__ void __launch_bounds__(NT) fwd_megakernel(Params p) {
;     ...
;             for (int t = vb; t < 256; t += gridDim.x) {
;               const int x = t & 7, L = t >> 3; const int pm = 8 * x + (L & 7), pnh = L >> 3;
;               gemm_tile<4, 64, EpiSwiglu, 2>(p.Xb, D_, p.win[i * 2 + f], D_, D_, pm * 256, 5120 + pnh * 128, lds, e1);
	v_rcp_f32_e32 v0, v0
	v_addc_co_u32_e32 v3, vcc, 0, v67, vcc
	v_mul_f32_e32 v0, v21, v0
	v_mul_f32_e32 v0, v5, v0
	v_cvt_pk_bf16_f32 v0, v0, s0
	global_store_short v[2:3], v0, off offset:512
	v_mul_f32_e32 v0, 0xbfb8aa3b, v22
	v_exp_f32_e32 v0, v0
	v_add_co_u32_e32 v2, vcc, s2, v66
	s_mov_b32 s2, 0x38000
	v_add_f32_e32 v0, 1.0, v0
	v_rcp_f32_e32 v0, v0
	v_addc_co_u32_e32 v3, vcc, 0, v67, vcc
	v_mul_f32_e32 v0, v22, v0
	v_mul_f32_e32 v0, v6, v0
	v_cvt_pk_bf16_f32 v0, v0, s0
	global_store_short v[2:3], v0, off
	v_mul_f32_e32 v0, 0xbfb8aa3b, v23
	v_exp_f32_e32 v0, v0
	v_add_co_u32_e32 v2, vcc, s2, v66
	s_mov_b32 s2, 0x39000
	v_add_f32_e32 v0, 1.0, v0
	v_rcp_f32_e32 v0, v0
	v_addc_co_u32_e32 v3, vcc, 0, v67, vcc
	v_mul_f32_e32 v0, v23, v0
	v_mul_f32_e32 v0, v7, v0
	v_cvt_pk_bf16_f32 v0, v0, s0
	global_store_short v[2:3], v0, off offset:1536
	v_mul_f32_e32 v0, 0xbfb8aa3b, v24
	v_exp_f32_e32 v0, v0
	v_add_co_u32_e32 v2, vcc, s2, v66
	s_mov_b32 s2, 0x3b000
	v_add_f32_e32 v0, 1.0, v0
	v_rcp_f32_e32 v0, v0
	v_addc_co_u32_e32 v3, vcc, 0, v67, vcc
	v_mul_f32_e32 v0, v24, v0
	v_mul_f32_e32 v0, v8, v0
	v_cvt_pk_bf16_f32 v0, v0, s0
	global_store_short v[2:3], v0, off offset:3072
	v_mul_f32_e32 v0, 0xbfb8aa3b, v25
	v_exp_f32_e32 v0, v0
	v_add_co_u32_e32 v2, vcc, s2, v66
	s_mov_b32 s2, 0x42000
	v_add_f32_e32 v0, 1.0, v0
	v_rcp_f32_e32 v0, v0
	v_addc_co_u32_e32 v3, vcc, 0, v67, vcc
	v_mul_f32_e32 v0, v25, v0
	v_mul_f32_e32 v0, v9, v0
	v_cvt_pk_bf16_f32 v0, v0, s0
	global_store_short v[2:3], v0, off offset:512
	v_mul_f32_e32 v0, 0xbfb8aa3b, v26
	v_exp_f32_e32 v0, v0
	v_add_co_u32_e32 v2, vcc, s2, v66
	s_mov_b32 s2, 0x43000
	v_add_f32_e32 v0, 1.0, v0
	v_rcp_f32_e32 v0, v0
	v_addc_co_u32_e32 v3, vcc, 0, v67, vcc
	v_mul_f32_e32 v0, v26, v0
	v_mul_f32_e32 v0, v10, v0
	v_cvt_pk_bf16_f32 v0, v0, s0
	global_store_short v[2:3], v0, off
	v_mul_f32_e32 v0, 0xbfb8aa3b, v27
	v_exp_f32_e32 v0, v0
	v_add_co_u32_e32 v2, vcc, s2, v66
	s_mov_b32 s2, 0x44000
	v_add_f32_e32 v0, 1.0, v0
	v_rcp_f32_e32 v0, v0
	v_addc_co_u32_e32 v3, vcc, 0, v67, vcc
	v_mul_f32_e32 v0, v27, v0
	v_mul_f32_e32 v0, v11, v0
	v_cvt_pk_bf16_f32 v0, v0, s0
	global_store_short v[2:3], v0, off offset:1536
	v_mul_f32_e32 v0, 0xbfb8aa3b, v28
	v_exp_f32_e32 v0, v0
	v_add_co_u32_e32 v2, vcc, s2, v66
	s_mov_b32 s2, 0x46000
	v_add_f32_e32 v0, 1.0, v0
	v_rcp_f32_e32 v0, v0
	v_addc_co_u32_e32 v3, vcc, 0, v67, vcc
	v_mul_f32_e32 v0, v28, v0
	v_mul_f32_e32 v0, v12, v0
	v_cvt_pk_bf16_f32 v0, v0, s0
	global_store_short v[2:3], v0, off offset:3072
	v_mul_f32_e32 v0, 0xbfb8aa3b, v29
	v_exp_f32_e32 v0, v0
	v_add_co_u32_e32 v2, vcc, s2, v66
	s_mov_b32 s2, 0x4d000
	v_add_f32_e32 v0, 1.0, v0
	v_rcp_f32_e32 v0, v0
	v_addc_co_u32_e32 v3, vcc, 0, v67, vcc
	v_mul_f32_e32 v0, v29, v0
	v_mul_f32_e32 v0, v13, v0
	v_cvt_pk_bf16_f32 v0, v0, s0
	global_store_short v[2:3], v0, off offset:512
	v_mul_f32_e32 v0, 0xbfb8aa3b, v30
	v_exp_f32_e32 v0, v0
	v_add_co_u32_e32 v2, vcc, s2, v66
	s_mov_b32 s2, 0x4e000
	v_add_f32_e32 v0, 1.0, v0
	v_rcp_f32_e32 v0, v0
	v_addc_co_u32_e32 v3, vcc, 0, v67, vcc
	v_mul_f32_e32 v0, v30, v0
	v_mul_f32_e32 v0, v14, v0
	v_cvt_pk_bf16_f32 v0, v0, s0
	global_store_short v[2:3], v0, off
	v_mul_f32_e32 v0, 0xbfb8aa3b, v31
	v_exp_f32_e32 v0, v0
	v_add_co_u32_e32 v2, vcc, s2, v66
	s_mov_b32 s2, 0x4f000
	v_add_f32_e32 v0, 1.0, v0
	v_rcp_f32_e32 v0, v0
	v_addc_co_u32_e32 v3, vcc, 0, v67, vcc
	v_mul_f32_e32 v0, v31, v0
	v_mul_f32_e32 v0, v15, v0
	v_cvt_pk_bf16_f32 v0, v0, s0
	global_store_short v[2:3], v0, off offset:1536
	v_mul_f32_e32 v0, 0xbfb8aa3b, v32
	v_exp_f32_e32 v0, v0
	v_add_co_u32_e32 v2, vcc, s2, v66
	v_readlane_b32 s2, v254, 39
	v_add_f32_e32 v0, 1.0, v0
	v_rcp_f32_e32 v0, v0
	v_addc_co_u32_e32 v3, vcc, 0, v67, vcc
	s_add_i32 s34, s34, s2
	v_mul_f32_e32 v0, v32, v0
	v_mul_f32_e32 v0, v16, v0
	v_cvt_pk_bf16_f32 v0, v0, s0
	global_store_short v[2:3], v0, off offset:3072
	v_mul_f32_e32 v0, 0xbfb8aa3b, v33
	v_exp_f32_e32 v0, v0
	v_add_co_u32_e32 v2, vcc, 0x51000, v66
	s_cmpk_gt_i32 s36, 0xff
	v_add_f32_e32 v0, 1.0, v0
	v_rcp_f32_e32 v0, v0
	v_addc_co_u32_e32 v3, vcc, 0, v67, vcc
	v_mul_f32_e32 v0, v33, v0
	v_mul_f32_e32 v0, v17, v0
	v_cvt_pk_bf16_f32 v0, v0, s0
	global_store_short v[2:3], v0, off offset:512
	s_cbranch_scc0 .LBB0_387

; DI f32x16 zero16() { f32x16 z; for (int i = 0; i < 16; ++i) z[i] = 0.f; return z; }
; DI int launder(int x) { asm volatile("" : "+v"(x)); return x; }
;   DI void pre(int grow0, int gcol0, int lane, int w, char* lds) { xpass(0, grow0, gcol0, lane, w, lds); }
; template <int BK> DI int swz(int row) { constexpr int CPR = BK / 8; return (row / (16 / CPR)) % CPR; }
; template <int ROWS, int BK>
; DI void stage_tile(const bf16_t* g, int ld, char* l, int tid) {
;   constexpr int CPR = BK / 8, TOT = ROWS * CPR, N = (TOT + NT - 1) / NT;
;   const int row0 = tid / CPR, pc = tid % CPR; const int c = pc ^ swz<BK>(row0);
;   const unsigned voff = (unsigned)(row0 * ld + c * 8) * 2u;
; #pragma unroll
;   for (int i = 0; i < N; ++i) {
;     if (TOT % NT == 0 || tid + i * NT < TOT) {
;       const char* gb = (const char*)g + (size_t)i * (NT / CPR) * ld * 2;
;       __builtin_amdgcn_global_load_lds((const unsigned*)(gb + voff), (__attribute__((address_space(3))) unsigned*)(l + i * NT * 16 + __builtin_amdgcn_readfirstlane(tid >> 6) * 1024), 16, 0, 0);
;     }
;   }
; }
; DI void wait_vm0() { asm volatile("s_waitcnt vmcnt(0)" ::: "memory"); }
; template <int ROWS, int BK>
; DI void stage_piece(const bf16_t* g, int ld, char* l, int tid, int i, int wv) {
;   constexpr int CPR = BK / 8, TOT = ROWS * CPR;
;   const int row0 = tid / CPR, pc = tid % CPR; const int c = pc ^ swz<BK>(row0);
;   const unsigned voff = (unsigned)(row0 * ld + c * 8) * 2u;
;   if (TOT % NT == 0 || tid + i * NT < TOT) {
;     const char* gb = (const char*)g + (size_t)i * (NT / CPR) * ld * 2;
;     __builtin_amdgcn_global_load_lds((const unsigned*)(gb + voff), (__attribute__((address_space(3))) unsigned*)(l + i * NT * 16 + wv * 1024), 16, 0, 0);
;   }
;     ...
;   const int tid = launder(threadIdx.x), lane = tid & 63, w = tid >> 6, wm = w % WM, wn = w / WM;
;   const int l31 = lane & 31, hh = lane >> 5;
;   f32x16 acc[2][NTW];
; #pragma unroll
;   for (int a = 0; a < 2; ++a)
; #pragma unroll
;     for (int b = 0; b < NTW; ++b) acc[a][b] = zero16();
;   const bf16_t* Ag = A + (size_t)row0 * lda; const bf16_t* Bg = Bt + (size_t)col0 * ldb;
;   const int wv = __builtin_amdgcn_readfirstlane(tid >> 6);
;   __syncthreads();
;   if (!pre) { stage_tile<BM, BK>(Ag, lda, lds, tid); stage_tile<BN, BK>(Bg, ldb, lds + ABYTES, tid); }
;   wait_vm0();
;   __syncthreads();
.LBB0_530:
	v_readlane_b32 s2, v255, 17
	v_readlane_b32 s3, v255, 18
	s_mov_b64 s[6:7], -1
	s_and_b64 vcc, exec, s[2:3]
	s_cbranch_vccz .LBB0_615
	s_waitcnt lgkmcnt(0)
	v_mov_b32_e32 v6, v216
	v_readlane_b32 s2, v255, 46
	v_ashrrev_i32_e32 v2, 31, v6
	v_lshrrev_b32_e32 v3, 29, v2
	v_lshrrev_b32_e32 v2, 28, v2
	v_add_u32_e32 v2, v6, v2
	v_ashrrev_i32_e32 v2, 4, v2
	v_lshrrev_b32_e32 v5, 29, v2
	v_add_u32_e32 v3, v6, v3
	v_add_u32_e32 v5, v2, v5
	v_ashrrev_i32_e32 v4, 3, v3
	v_and_b32_e32 v3, 0xffffff8, v3
	v_and_b32_e32 v5, 0xffffff8, v5
	v_sub_u32_e32 v3, v6, v3
	v_sub_u32_e32 v2, v2, v5
	v_readlane_b32 s7, v255, 26
	v_readlane_b32 s3, v255, 47
	s_add_u32 s2, s42, s2
	v_xor_b32_e32 v2, v2, v3
	v_lshlrev_b32_e32 v3, s7, v4
	v_readfirstlane_b32 s7, v6
	s_addc_u32 s3, s43, s3
	v_readlane_b32 s30, v255, 27
	s_lshl_b32 s7, s7, 4
	v_lshl_add_u32 v2, v2, 4, v3
	v_mov_b32_e32 v3, v1
	v_readlane_b32 s31, v255, 28
	s_and_b32 s7, s7, 0xfffffc00
	v_readlane_b32 s36, v255, 41
	s_waitcnt vmcnt(0)
	v_lshl_add_u64 v[130:131], s[30:31], 0, v[2:3]
	s_mov_b32 m0, s7
	v_readlane_b32 s37, v255, 42
	v_readlane_b32 s40, v255, 43
	s_barrier
	global_load_lds_dwordx4 v2, s[30:31]
	v_lshl_add_u64 v[4:5], v[130:131], 0, s[36:37]
	s_add_i32 m0, s7, 0x2000
	v_readlane_b32 s41, v255, 44
	v_readlane_b32 s34, v255, 48
	global_load_lds_dwordx4 v[4:5], off
	v_lshl_add_u64 v[4:5], v[130:131], 0, s[40:41]
	s_add_i32 m0, s7, 0x4000
	v_readlane_b32 s35, v255, 49
	global_load_lds_dwordx4 v[4:5], off
	s_nop 0
	v_lshl_add_u64 v[4:5], v[130:131], 0, s[34:35]
	s_add_i32 m0, s7, 0x6000
	v_lshl_add_u64 v[132:133], s[2:3], 0, v[2:3]
	global_load_lds_dwordx4 v[4:5], off
	s_add_i32 m0, s7, 0x8000
	v_ashrrev_i32_e32 v134, 6, v6
	global_load_lds_dwordx4 v2, s[2:3]
	v_lshl_add_u64 v[2:3], v[132:133], 0, s[36:37]
	s_add_i32 m0, s7, 0xa000
	v_and_b32_e32 v4, 31, v6
	global_load_lds_dwordx4 v[2:3], off
	v_lshl_add_u64 v[2:3], v[132:133], 0, s[40:41]
	s_add_i32 m0, s7, 0xc000
	v_and_b32_e32 v0, 63, v6
	global_load_lds_dwordx4 v[2:3], off
	v_lshl_add_u64 v[2:3], v[132:133], 0, s[34:35]
	s_add_i32 m0, s7, 0xe000
	v_bfe_u32 v135, v6, 5, 1
	global_load_lds_dwordx4 v[2:3], off
	v_lshrrev_b32_e32 v2, 30, v134
	v_add_u32_e32 v2, v134, v2
	v_ashrrev_i32_e32 v3, 2, v2
	v_mul_i32_i24_e32 v5, 4, v3
	v_sub_u32_e32 v5, v134, v5
	v_lshlrev_b32_e32 v169, 6, v5
	v_lshlrev_b32_e32 v161, 7, v3
	v_or_b32_e32 v3, v169, v4
	v_bfe_u32 v5, v5, 25, 1
	v_lshlrev_b32_e32 v136, 7, v3
	v_add_u32_e32 v6, v3, v5
	v_or_b32_e32 v3, 32, v3
	v_lshlrev_b32_e32 v144, 7, v3
	v_add_u32_e32 v3, v3, v5
	v_ashrrev_i32_e32 v5, 1, v3
	v_ashrrev_i32_e32 v3, 31, v3
	v_ashrrev_i32_e32 v7, 1, v6
	v_ashrrev_i32_e32 v6, 31, v6
	v_lshrrev_b32_e32 v3, 29, v3
	v_lshrrev_b32_e32 v6, 29, v6
	v_add_u32_e32 v3, v5, v3
	v_add_u32_e32 v6, v7, v6
	v_and_b32_e32 v3, -8, v3
	v_and_b32_e32 v6, -8, v6
	v_sub_u32_e32 v3, v5, v3
	v_or_b32_e32 v4, v161, v4
	v_sub_u32_e32 v6, v7, v6
	v_xor_b32_e32 v5, v3, v135
	v_lshrrev_b32_e32 v2, 31, v2
	v_xor_b32_e32 v7, v6, v135
	v_lshlrev_b32_e32 v146, 4, v5
	v_add_u32_e32 v5, v4, v2
	v_lshlrev_b32_e32 v143, 4, v7
	v_ashrrev_i32_e32 v7, 1, v5
	v_ashrrev_i32_e32 v5, 31, v5
	v_lshrrev_b32_e32 v5, 29, v5
	v_add_u32_e32 v5, v7, v5
	v_and_b32_e32 v5, -8, v5
	v_sub_u32_e32 v5, v7, v5
	v_xor_b32_e32 v7, v5, v135
	v_lshlrev_b32_e32 v149, 4, v7
	v_or_b32_e32 v7, 32, v4
	v_lshlrev_b32_e32 v150, 7, v7
	v_add_u32_e32 v7, v7, v2
	v_ashrrev_i32_e32 v8, 1, v7
	v_ashrrev_i32_e32 v7, 31, v7
	v_lshrrev_b32_e32 v7, 29, v7
	v_add_u32_e32 v7, v8, v7
	v_and_b32_e32 v7, -8, v7
	v_sub_u32_e32 v7, v8, v7
	v_xor_b32_e32 v8, v7, v135
	v_lshlrev_b32_e32 v145, 7, v4
	v_lshlrev_b32_e32 v155, 4, v8
	v_or_b32_e32 v8, 64, v4
	v_or_b32_e32 v4, 0x60, v4
	v_lshlrev_b32_e32 v156, 7, v8
	v_add_u32_e32 v8, v8, v2
	v_add_u32_e32 v2, v4, v2
	v_lshlrev_b32_e32 v158, 7, v4
	v_ashrrev_i32_e32 v4, 1, v2
	v_ashrrev_i32_e32 v2, 31, v2
	v_lshrrev_b32_e32 v2, 29, v2
	v_add_u32_e32 v2, v4, v2
	v_and_b32_e32 v2, -8, v2
	v_sub_u32_e32 v2, v4, v2
	v_ashrrev_i32_e32 v9, 1, v8
	v_ashrrev_i32_e32 v8, 31, v8
	v_xor_b32_e32 v4, v2, v135
	v_lshrrev_b32_e32 v8, 29, v8
	v_lshlrev_b32_e32 v168, 4, v4
	v_bitop3_b32 v4, v6, v135, 2 bitop3:0x1e
	v_add_u32_e32 v8, v9, v8
	v_lshlrev_b32_e32 v166, 4, v4
	v_bitop3_b32 v4, v3, v135, 2 bitop3:0x1e
	v_and_b32_e32 v8, -8, v8
	v_lshlrev_b32_e32 v167, 4, v4
	v_bitop3_b32 v4, v5, v135, 2 bitop3:0x1e
	v_sub_u32_e32 v8, v9, v8
	v_lshlrev_b32_e32 v163, 4, v4
	v_bitop3_b32 v4, v7, v135, 2 bitop3:0x1e
	v_lshlrev_b32_e32 v164, 4, v4
	v_bitop3_b32 v4, v8, v135, 2 bitop3:0x1e
	v_lshlrev_b32_e32 v159, 4, v4
	v_bitop3_b32 v4, v2, v135, 2 bitop3:0x1e
	v_lshlrev_b32_e32 v160, 4, v4
	v_bitop3_b32 v4, v6, v135, 4 bitop3:0x1e
	v_lshlrev_b32_e32 v153, 4, v4
	v_bitop3_b32 v4, v3, v135, 4 bitop3:0x1e
	v_lshlrev_b32_e32 v154, 4, v4
	v_bitop3_b32 v4, v5, v135, 4 bitop3:0x1e
	v_lshlrev_b32_e32 v151, 4, v4
	v_bitop3_b32 v4, v7, v135, 4 bitop3:0x1e
	v_bitop3_b32 v3, v3, v135, 6 bitop3:0x1e
	v_lshlrev_b32_e32 v152, 4, v4
	v_bitop3_b32 v4, v8, v135, 4 bitop3:0x1e
	v_lshlrev_b32_e32 v142, 4, v3
	v_bitop3_b32 v3, v5, v135, 6 bitop3:0x1e
	s_waitcnt vmcnt(0)
; DI f32x16 zero16() { f32x16 z; for (int i = 0; i < 16; ++i) z[i] = 0.f; return z; }
; template <int BK> DI int swz(int row) { constexpr int CPR = BK / 8; return (row / (16 / CPR)) % CPR; }
; DI void wait_vm0() { asm volatile("s_waitcnt vmcnt(0)" ::: "memory"); }
;   DI void pre(int grow0, int gcol0, int lane, int w, char* lds) { xpass(0, grow0, gcol0, lane, w, lds); }
;     ...
;   f32x16 acc[2][NTW];
; #pragma unroll
;   for (int a = 0; a < 2; ++a)
; #pragma unroll
;     for (int b = 0; b < NTW; ++b) acc[a][b] = zero16();
;   const bf16_t* Ag = A + (size_t)row0 * lda; const bf16_t* Bg = Bt + (size_t)col0 * ldb;
;   const int wv = __builtin_amdgcn_readfirstlane(tid >> 6);
;   __syncthreads();
;   if (!pre) { stage_tile<BM, BK>(Ag, lda, lds, tid); stage_tile<BN, BK>(Bg, ldb, lds + ABYTES, tid); }
;   wait_vm0();
;   __syncthreads();
;   const int nk = K / BK;
;   for (int kt = 0; kt < nk; ++kt) {
;     char* cur = lds + (kt & 1) * STG; char* nxt = lds + ((kt + 1) & 1) * STG;
;     const bool more = kt + 1 < nk;
;     const bf16_t* An = Ag + (kt + 1) * BK; const bf16_t* Bn = Bg + (kt + 1) * BK;
;     if (!more) epi.pre(row0 + wm * 64, col0 + wn * (32 * NTW), lane, w, lds);
;     bf16x8 fa[2][2], fb[2][NTW];
; #pragma unroll
;     for (int mt = 0; mt < 2; ++mt) { int row = wm * 64 + mt * 32 + l31; fa[0][mt] = *(const bf16x8*)(cur + row * (BK * 2) + ((hh ^ swz<BK>(row)) << 4)); }
; #pragma unroll
;     for (int nt = 0; nt < NTW; ++nt) { int row = wn * (32 * NTW) + nt * 32 + l31; fb[0][nt] = *(const bf16x8*)(cur + ABYTES + row * (BK * 2) + ((hh ^ swz<BK>(row)) << 4)); }
	v_lshlrev_b32_e32 v147, 4, v4
	v_bitop3_b32 v4, v2, v135, 4 bitop3:0x1e
	v_lshlrev_b32_e32 v139, 4, v3
	v_bitop3_b32 v3, v7, v135, 6 bitop3:0x1e
	v_bitop3_b32 v2, v2, v135, 6 bitop3:0x1e
	v_readfirstlane_b32 s6, v134
	v_xor_b32_e32 v9, v8, v135
	v_lshlrev_b32_e32 v148, 4, v4
	v_bitop3_b32 v4, v6, v135, 6 bitop3:0x1e
	v_lshlrev_b32_e32 v140, 4, v3
	v_bitop3_b32 v3, v8, v135, 6 bitop3:0x1e
	v_lshlrev_b32_e32 v138, 4, v2
	v_mov_b32_e32 v2, 0
	s_lshl_b32 s2, s6, 10
	s_mov_b32 s92, 64
	v_lshlrev_b32_e32 v157, 4, v9
	v_lshlrev_b32_e32 v141, 4, v4
	v_lshlrev_b32_e32 v137, 4, v3
	s_mov_b32 s3, 0x10000
	v_readlane_b32 s6, v255, 45
	v_mov_b32_e32 v3, v2
	v_mov_b32_e32 v4, v2
	v_mov_b32_e32 v5, v2
	v_mov_b32_e32 v6, v2
	v_mov_b32_e32 v7, v2
	v_mov_b32_e32 v8, v2
	v_mov_b32_e32 v9, v2
	v_mov_b32_e32 v10, v2
	v_mov_b32_e32 v11, v2
	v_mov_b32_e32 v12, v2
	v_mov_b32_e32 v13, v2
	v_mov_b32_e32 v14, v2
	v_mov_b32_e32 v15, v2
	v_mov_b32_e32 v16, v2
	v_mov_b32_e32 v17, v2
	v_mov_b32_e32 v18, v2
	v_mov_b32_e32 v19, v2
	v_mov_b32_e32 v20, v2
	v_mov_b32_e32 v21, v2
	v_mov_b32_e32 v22, v2
	v_mov_b32_e32 v23, v2
	v_mov_b32_e32 v24, v2
	v_mov_b32_e32 v25, v2
	v_mov_b32_e32 v26, v2
	v_mov_b32_e32 v27, v2
	v_mov_b32_e32 v28, v2
	v_mov_b32_e32 v29, v2
	v_mov_b32_e32 v30, v2
	v_mov_b32_e32 v31, v2
	v_mov_b32_e32 v32, v2
	v_mov_b32_e32 v33, v2
	v_mov_b32_e32 v34, v2
	v_mov_b32_e32 v35, v2
	v_mov_b32_e32 v36, v2
	v_mov_b32_e32 v37, v2
	v_mov_b32_e32 v38, v2
	v_mov_b32_e32 v39, v2
	v_mov_b32_e32 v40, v2
	v_mov_b32_e32 v41, v2
	v_mov_b32_e32 v42, v2
	v_mov_b32_e32 v43, v2
	v_mov_b32_e32 v44, v2
	v_mov_b32_e32 v45, v2
	v_mov_b32_e32 v46, v2
	v_mov_b32_e32 v47, v2
	v_mov_b32_e32 v48, v2
	v_mov_b32_e32 v49, v2
	v_mov_b32_e32 v50, v2
	v_mov_b32_e32 v51, v2
	v_mov_b32_e32 v52, v2
	v_mov_b32_e32 v53, v2
	v_mov_b32_e32 v54, v2
	v_mov_b32_e32 v55, v2
	v_mov_b32_e32 v56, v2
	v_mov_b32_e32 v57, v2
	v_mov_b32_e32 v58, v2
	v_mov_b32_e32 v59, v2
	v_mov_b32_e32 v60, v2
	v_mov_b32_e32 v61, v2
	v_mov_b32_e32 v62, v2
	v_mov_b32_e32 v63, v2
	v_mov_b32_e32 v64, v2
	v_mov_b32_e32 v65, v2
	v_mov_b32_e32 v66, v2
	v_mov_b32_e32 v67, v2
	v_mov_b32_e32 v68, v2
	v_mov_b32_e32 v69, v2
	v_mov_b32_e32 v70, v2
	v_mov_b32_e32 v71, v2
	v_mov_b32_e32 v72, v2
	v_mov_b32_e32 v73, v2
	v_mov_b32_e32 v74, v2
	v_mov_b32_e32 v75, v2
	v_mov_b32_e32 v76, v2
	v_mov_b32_e32 v77, v2
	v_mov_b32_e32 v78, v2
	v_mov_b32_e32 v79, v2
	v_mov_b32_e32 v80, v2
	v_mov_b32_e32 v81, v2
	v_mov_b32_e32 v82, v2
	v_mov_b32_e32 v83, v2
	v_mov_b32_e32 v84, v2
	v_mov_b32_e32 v85, v2
	v_mov_b32_e32 v86, v2
	v_mov_b32_e32 v87, v2
	v_mov_b32_e32 v88, v2
	v_mov_b32_e32 v89, v2
	v_mov_b32_e32 v90, v2
	v_mov_b32_e32 v91, v2
	v_mov_b32_e32 v92, v2
	v_mov_b32_e32 v93, v2
	v_mov_b32_e32 v94, v2
	v_mov_b32_e32 v95, v2
	v_mov_b32_e32 v96, v2
	v_mov_b32_e32 v97, v2
	v_mov_b32_e32 v98, v2
	v_mov_b32_e32 v99, v2
	v_mov_b32_e32 v100, v2
	v_mov_b32_e32 v101, v2
	v_mov_b32_e32 v102, v2
	v_mov_b32_e32 v103, v2
	v_mov_b32_e32 v104, v2
	v_mov_b32_e32 v105, v2
	v_mov_b32_e32 v106, v2
	v_mov_b32_e32 v107, v2
	v_mov_b32_e32 v108, v2
	v_mov_b32_e32 v109, v2
	v_mov_b32_e32 v110, v2
	v_mov_b32_e32 v111, v2
	v_mov_b32_e32 v112, v2
	v_mov_b32_e32 v113, v2
	v_mov_b32_e32 v114, v2
	v_mov_b32_e32 v115, v2
	v_mov_b32_e32 v116, v2
	v_mov_b32_e32 v117, v2
	v_mov_b32_e32 v118, v2
	v_mov_b32_e32 v119, v2
	v_mov_b32_e32 v120, v2
	v_mov_b32_e32 v121, v2
	v_mov_b32_e32 v122, v2
	v_mov_b32_e32 v123, v2
	v_mov_b32_e32 v124, v2
	v_mov_b32_e32 v125, v2
	v_mov_b32_e32 v126, v2
	v_mov_b32_e32 v127, v2
	v_mov_b32_e32 v128, v2
	v_mov_b32_e32 v129, v2
	s_waitcnt vmcnt(0) lgkmcnt(0)
	s_barrier
	v_add_u32_e32 v170, v136, v143
	v_add_u32_e32 v174, v144, v146
	ds_read_b128 v[170:173], v170
	v_add_u32_e32 v178, v145, v149
	ds_read_b128 v[174:177], v174
	v_add_u32_e32 v182, v150, v155
	ds_read_b128 v[178:181], v178 offset:32768
	v_add_u32_e32 v186, v156, v157
	ds_read_b128 v[182:185], v182 offset:32768
	v_add_u32_e32 v190, v158, v168
	ds_read_b128 v[186:189], v186 offset:32768
	ds_read_b128 v[190:193], v190 offset:32768
	s_and_b32 s7, s3, 0x10000
	s_add_i32 s7, s7, s2
	s_lshl_b64 s[30:31], s[92:93], 1
	v_lshl_add_u64 v[230:231], v[130:131], 0, s[30:31]
	v_lshl_add_u64 v[214:215], v[132:133], 0, s[30:31]
	s_mov_b32 m0, s7
	v_mov_b64_e32 v[232:233], v[230:231]
	global_load_lds_dwordx4 v[232:233], off
	s_add_i32 m0, s7, 0x2000
	v_lshl_add_u64 v[232:233], v[230:231], 0, s[36:37]
	global_load_lds_dwordx4 v[232:233], off
	s_add_i32 m0, s7, 0x4000
	v_lshl_add_u64 v[232:233], v[230:231], 0, s[40:41]
	global_load_lds_dwordx4 v[232:233], off
	s_add_i32 m0, s7, 0x6000
	v_lshl_add_u64 v[232:233], v[230:231], 0, s[34:35]
	global_load_lds_dwordx4 v[232:233], off
	s_add_i32 m0, s7, 0x8000
	v_mov_b64_e32 v[232:233], v[214:215]
	global_load_lds_dwordx4 v[232:233], off
	s_add_i32 m0, s7, 0xa000
	v_lshl_add_u64 v[232:233], v[214:215], 0, s[36:37]
	global_load_lds_dwordx4 v[232:233], off
	s_add_i32 m0, s7, 0xc000
	v_lshl_add_u64 v[232:233], v[214:215], 0, s[40:41]
	global_load_lds_dwordx4 v[232:233], off
	s_add_i32 m0, s7, 0xe000
	v_lshl_add_u64 v[232:233], v[214:215], 0, s[34:35]
	global_load_lds_dwordx4 v[232:233], off
; DI f32x16 mfma(bf16x8 a, bf16x8 b, f32x16 c) { return __builtin_amdgcn_mfma_f32_32x32x16_bf16(a, b, c, 0, 0, 0); }
; template <int BK> DI int swz(int row) { constexpr int CPR = BK / 8; return (row / (16 / CPR)) % CPR; }
; DI void wait_vm0() { asm volatile("s_waitcnt vmcnt(0)" ::: "memory"); }
;   DI void pre(int grow0, int gcol0, int lane, int w, char* lds) { xpass(0, grow0, gcol0, lane, w, lds); }
;     ...
;   for (int kt = 0; kt < nk; ++kt) {
;     char* cur = lds + (kt & 1) * STG; char* nxt = lds + ((kt + 1) & 1) * STG;
;     const bool more = kt + 1 < nk;
;     const bf16_t* An = Ag + (kt + 1) * BK; const bf16_t* Bn = Bg + (kt + 1) * BK;
;     if (!more) epi.pre(row0 + wm * 64, col0 + wn * (32 * NTW), lane, w, lds);
;     bf16x8 fa[2][2], fb[2][NTW];
; #pragma unroll
;     for (int mt = 0; mt < 2; ++mt) { int row = wm * 64 + mt * 32 + l31; fa[0][mt] = *(const bf16x8*)(cur + row * (BK * 2) + ((hh ^ swz<BK>(row)) << 4)); }
; #pragma unroll
;     for (int nt = 0; nt < NTW; ++nt) { int row = wn * (32 * NTW) + nt * 32 + l31; fb[0][nt] = *(const bf16x8*)(cur + ABYTES + row * (BK * 2) + ((hh ^ swz<BK>(row)) << 4)); }
; #pragma unroll
;     for (int kk = 0; kk < NKK; ++kk) {
;       if (kk + 1 < NKK) {
;         const int ch = (kk + 1) * 2 + hh;
; #pragma unroll
;         for (int mt = 0; mt < 2; ++mt) { int row = wm * 64 + mt * 32 + l31; fa[(kk + 1) & 1][mt] = *(const bf16x8*)(cur + row * (BK * 2) + ((ch ^ swz<BK>(row)) << 4)); }
; #pragma unroll
;         for (int nt = 0; nt < NTW; ++nt) { int row = wn * (32 * NTW) + nt * 32 + l31; fb[(kk + 1) & 1][nt] = *(const bf16x8*)(cur + ABYTES + row * (BK * 2) + ((ch ^ swz<BK>(row)) << 4)); }
;       }
;       if (more) {
; #pragma unroll
;         for (int q = 0; q < PPK; ++q) {
;           const int pi = kk * PPK + q;
;           if (pi < NPA) stage_piece<BM, BK>(An, lda, nxt, tid, pi, wv);
;           else if (pi < NP) stage_piece<BN, BK>(Bn, ldb, nxt + ABYTES, tid, pi - NPA, wv);
;         }
;       }
;       __builtin_amdgcn_s_setprio(1);
; #pragma unroll
;       for (int mt = 0; mt < 2; ++mt)
; #pragma unroll
;         for (int nt = 0; nt < NTW; ++nt) acc[mt][nt] = mfma(fa[kk & 1][mt], fb[kk & 1][nt], acc[mt][nt]);
;       __builtin_amdgcn_s_setprio(0);
;       __builtin_amdgcn_sched_barrier(0);
;     }
;     wait_vm0();
;     __syncthreads();
.LBB0_532:
	s_and_b32 s7, s3, 0x10000
	s_xor_b32 s100, s7, 0x10000
	v_add3_u32 v194, s100, v136, v166
	v_add3_u32 v198, s100, v144, v167
	ds_read_b128 v[194:197], v194
	v_add3_u32 v202, s100, v145, v163
	ds_read_b128 v[198:201], v198
	v_add3_u32 v206, s100, v150, v164
	ds_read_b128 v[202:205], v202 offset:32768
	v_add3_u32 v210, s100, v156, v159
	ds_read_b128 v[206:209], v206 offset:32768
	v_add3_u32 v226, s100, v158, v160
	ds_read_b128 v[210:213], v210 offset:32768
	ds_read_b128 v[226:229], v226 offset:32768
	s_waitcnt lgkmcnt(6)
	v_mfma_f32_32x32x16_bf16 v[114:129], v[170:173], v[178:181], v[114:129]
	v_mfma_f32_32x32x16_bf16 v[98:113], v[170:173], v[182:185], v[98:113]
	v_mfma_f32_32x32x16_bf16 v[82:97], v[170:173], v[186:189], v[82:97]
	v_mfma_f32_32x32x16_bf16 v[66:81], v[170:173], v[190:193], v[66:81]
	v_mfma_f32_32x32x16_bf16 v[50:65], v[174:177], v[178:181], v[50:65]
	v_mfma_f32_32x32x16_bf16 v[34:49], v[174:177], v[182:185], v[34:49]
	v_mfma_f32_32x32x16_bf16 v[18:33], v[174:177], v[186:189], v[18:33]
	v_mfma_f32_32x32x16_bf16 v[2:17], v[174:177], v[190:193], v[2:17]
	v_add3_u32 v170, s100, v136, v153
	v_add3_u32 v174, s100, v144, v154
	ds_read_b128 v[170:173], v170
	v_add3_u32 v178, s100, v145, v151
	ds_read_b128 v[174:177], v174
	v_add3_u32 v182, s100, v150, v152
	ds_read_b128 v[178:181], v178 offset:32768
	v_add3_u32 v186, s100, v156, v147
	ds_read_b128 v[182:185], v182 offset:32768
	v_add3_u32 v190, s100, v158, v148
	ds_read_b128 v[186:189], v186 offset:32768
	ds_read_b128 v[190:193], v190 offset:32768
	s_waitcnt lgkmcnt(6)
	v_mfma_f32_32x32x16_bf16 v[114:129], v[194:197], v[202:205], v[114:129]
	v_mfma_f32_32x32x16_bf16 v[98:113], v[194:197], v[206:209], v[98:113]
	v_mfma_f32_32x32x16_bf16 v[82:97], v[194:197], v[210:213], v[82:97]
	v_mfma_f32_32x32x16_bf16 v[66:81], v[194:197], v[226:229], v[66:81]
	v_mfma_f32_32x32x16_bf16 v[50:65], v[198:201], v[202:205], v[50:65]
	v_mfma_f32_32x32x16_bf16 v[34:49], v[198:201], v[206:209], v[34:49]
	v_mfma_f32_32x32x16_bf16 v[18:33], v[198:201], v[210:213], v[18:33]
	v_mfma_f32_32x32x16_bf16 v[2:17], v[198:201], v[226:229], v[2:17]
	v_add3_u32 v194, s100, v136, v141
	v_add3_u32 v198, s100, v144, v142
	ds_read_b128 v[194:197], v194
	v_add3_u32 v202, s100, v145, v139
	ds_read_b128 v[198:201], v198
	v_add3_u32 v206, s100, v150, v140
	ds_read_b128 v[202:205], v202 offset:32768
	v_add3_u32 v210, s100, v156, v137
	ds_read_b128 v[206:209], v206 offset:32768
	v_add3_u32 v226, s100, v158, v138
	ds_read_b128 v[210:213], v210 offset:32768
	ds_read_b128 v[226:229], v226 offset:32768
	s_waitcnt lgkmcnt(6)
	v_mfma_f32_32x32x16_bf16 v[114:129], v[170:173], v[178:181], v[114:129]
	v_mfma_f32_32x32x16_bf16 v[98:113], v[170:173], v[182:185], v[98:113]
	v_mfma_f32_32x32x16_bf16 v[82:97], v[170:173], v[186:189], v[82:97]
	v_mfma_f32_32x32x16_bf16 v[66:81], v[170:173], v[190:193], v[66:81]
	v_mfma_f32_32x32x16_bf16 v[50:65], v[174:177], v[178:181], v[50:65]
	v_mfma_f32_32x32x16_bf16 v[34:49], v[174:177], v[182:185], v[34:49]
	v_mfma_f32_32x32x16_bf16 v[18:33], v[174:177], v[186:189], v[18:33]
	v_mfma_f32_32x32x16_bf16 v[2:17], v[174:177], v[190:193], v[2:17]
	s_add_i32 s6, s6, -1
	s_add_i32 s92, s92, 64
	s_add_i32 s3, s3, 0x10000
	s_waitcnt vmcnt(0) lgkmcnt(0)
	s_barrier
	v_add3_u32 v170, s7, v136, v143
	v_add3_u32 v174, s7, v144, v146
	ds_read_b128 v[170:173], v170
	v_add3_u32 v178, s7, v145, v149
	ds_read_b128 v[174:177], v174
	v_add3_u32 v182, s7, v150, v155
	ds_read_b128 v[178:181], v178 offset:32768
	v_add3_u32 v186, s7, v156, v157
	ds_read_b128 v[182:185], v182 offset:32768
	v_add3_u32 v190, s7, v158, v168
	ds_read_b128 v[186:189], v186 offset:32768
	ds_read_b128 v[190:193], v190 offset:32768
	s_cmp_lg_u32 s6, 0
	s_cbranch_scc0 .Lk532_exit
	s_add_i32 s7, s100, s2
	s_lshl_b64 s[30:31], s[92:93], 1
	v_lshl_add_u64 v[230:231], v[130:131], 0, s[30:31]
	v_lshl_add_u64 v[214:215], v[132:133], 0, s[30:31]
	s_mov_b32 m0, s7
	v_mov_b64_e32 v[232:233], v[230:231]
	v_mfma_f32_32x32x16_bf16 v[114:129], v[194:197], v[202:205], v[114:129]
	global_load_lds_dwordx4 v[232:233], off
	v_lshl_add_u64 v[232:233], v[230:231], 0, s[36:37]
	s_add_i32 m0, s7, 0x2000
	v_mfma_f32_32x32x16_bf16 v[98:113], v[194:197], v[206:209], v[98:113]
	global_load_lds_dwordx4 v[232:233], off
	v_lshl_add_u64 v[232:233], v[230:231], 0, s[40:41]
	s_add_i32 m0, s7, 0x4000
	v_mfma_f32_32x32x16_bf16 v[82:97], v[194:197], v[210:213], v[82:97]
	global_load_lds_dwordx4 v[232:233], off
	v_lshl_add_u64 v[232:233], v[230:231], 0, s[34:35]
	s_add_i32 m0, s7, 0x6000
	v_mfma_f32_32x32x16_bf16 v[66:81], v[194:197], v[226:229], v[66:81]
	global_load_lds_dwordx4 v[232:233], off
	v_mov_b64_e32 v[232:233], v[214:215]
	s_add_i32 m0, s7, 0x8000
	v_mfma_f32_32x32x16_bf16 v[50:65], v[198:201], v[202:205], v[50:65]
	global_load_lds_dwordx4 v[232:233], off
	v_lshl_add_u64 v[232:233], v[214:215], 0, s[36:37]
	s_add_i32 m0, s7, 0xa000
	v_mfma_f32_32x32x16_bf16 v[34:49], v[198:201], v[206:209], v[34:49]
	global_load_lds_dwordx4 v[232:233], off
	v_lshl_add_u64 v[232:233], v[214:215], 0, s[40:41]
	s_add_i32 m0, s7, 0xc000
	v_mfma_f32_32x32x16_bf16 v[18:33], v[198:201], v[210:213], v[18:33]
	global_load_lds_dwordx4 v[232:233], off
	v_lshl_add_u64 v[232:233], v[214:215], 0, s[34:35]
	s_add_i32 m0, s7, 0xe000
	v_mfma_f32_32x32x16_bf16 v[2:17], v[198:201], v[226:229], v[2:17]
	global_load_lds_dwordx4 v[232:233], off
	s_branch .LBB0_532
;     ...
;   for (int kt = 0; kt < nk; ++kt) {
;     char* cur = lds + (kt & 1) * STG; char* nxt = lds + ((kt + 1) & 1) * STG;
;     const bool more = kt + 1 < nk;
;     const bf16_t* An = Ag + (kt + 1) * BK; const bf16_t* Bn = Bg + (kt + 1) * BK;
;     if (!more) epi.pre(row0 + wm * 64, col0 + wn * (32 * NTW), lane, w, lds);
;     bf16x8 fa[2][2], fb[2][NTW];
; #pragma unroll
;     for (int mt = 0; mt < 2; ++mt) { int row = wm * 64 + mt * 32 + l31; fa[0][mt] = *(const bf16x8*)(cur + row * (BK * 2) + ((hh ^ swz<BK>(row)) << 4)); }
; #pragma unroll
;     for (int nt = 0; nt < NTW; ++nt) { int row = wn * (32 * NTW) + nt * 32 + l31; fb[0][nt] = *(const bf16x8*)(cur + ABYTES + row * (BK * 2) + ((hh ^ swz<BK>(row)) << 4)); }
; #pragma unroll
;     for (int kk = 0; kk < NKK; ++kk) {
;       if (kk + 1 < NKK) {
;         const int ch = (kk + 1) * 2 + hh;
; #pragma unroll
;         for (int mt = 0; mt < 2; ++mt) { int row = wm * 64 + mt * 32 + l31; fa[(kk + 1) & 1][mt] = *(const bf16x8*)(cur + row * (BK * 2) + ((ch ^ swz<BK>(row)) << 4)); }
; #pragma unroll
;         for (int nt = 0; nt < NTW; ++nt) { int row = wn * (32 * NTW) + nt * 32 + l31; fb[(kk + 1) & 1][nt] = *(const bf16x8*)(cur + ABYTES + row * (BK * 2) + ((ch ^ swz<BK>(row)) << 4)); }
;       }
;       if (more) {
; #pragma unroll
;         for (int q = 0; q < PPK; ++q) {
;           const int pi = kk * PPK + q;
;           if (pi < NPA) stage_piece<BM, BK>(An, lda, nxt, tid, pi, wv);
;           else if (pi < NP) stage_piece<BN, BK>(Bn, ldb, nxt + ABYTES, tid, pi - NPA, wv);
;         }
;       }
;       __builtin_amdgcn_s_setprio(1);
; #pragma unroll
;       for (int mt = 0; mt < 2; ++mt)
; #pragma unroll
;         for (int nt = 0; nt < NTW; ++nt) acc[mt][nt] = mfma(fa[kk & 1][mt], fb[kk & 1][nt], acc[mt][nt]);
;       __builtin_amdgcn_s_setprio(0);
;       __builtin_amdgcn_sched_barrier(0);
;     }
;     wait_vm0();
;     __syncthreads();
;   }
;   if (has_next) { const int tid3 = launder(threadIdx.x); stage_tile<BM, BK>(A + (size_t)row0n * lda, lda, lds, tid3); stage_tile<BN, BK>(Bt + (size_t)col0n * ldb, ldb, lds + ABYTES, tid3); }
;   { const int tid2 = launder(threadIdx.x); epi(acc, row0 + (((tid2 >> 6) % WM) * 64), col0 + (((tid2 >> 6) / WM) * (32 * NTW)), tid2 & 63, tid2 >> 6, lds); }
;   DI void xpass(int ps, int grow0, int gcol0, int lane, int w, char* lds) const {
.Lk532_exit:
	v_mfma_f32_32x32x16_bf16 v[114:129], v[194:197], v[202:205], v[114:129]
	v_mfma_f32_32x32x16_bf16 v[98:113], v[194:197], v[206:209], v[98:113]
	v_mfma_f32_32x32x16_bf16 v[82:97], v[194:197], v[210:213], v[82:97]
	v_mfma_f32_32x32x16_bf16 v[66:81], v[194:197], v[226:229], v[66:81]
	v_mfma_f32_32x32x16_bf16 v[50:65], v[198:201], v[202:205], v[50:65]
	v_mfma_f32_32x32x16_bf16 v[34:49], v[198:201], v[206:209], v[34:49]
	v_mfma_f32_32x32x16_bf16 v[18:33], v[198:201], v[210:213], v[18:33]
	v_mfma_f32_32x32x16_bf16 v[2:17], v[198:201], v[226:229], v[2:17]
	s_waitcnt lgkmcnt(0)
	v_readlane_b32 s3, v253, 9
	v_readlane_b32 s30, v253, 27
	v_readfirstlane_b32 s2, v134
	v_or_b32_e32 v130, s3, v135
	v_add_u32_e32 v130, v130, v169
	v_ashrrev_i32_e32 v131, 31, v130
	v_lshlrev_b64 v[130:131], 12, v[130:131]
	v_add_u32_e32 v132, s30, v161
	v_ashrrev_i32_e32 v133, 31, v132
	v_lshl_add_u64 v[130:131], s[10:11], 0, v[130:131]
	v_lshlrev_b32_e32 v0, 4, v0
	s_lshl_b32 s2, s2, 13
	v_lshl_add_u64 v[130:131], v[132:133], 2, v[130:131]
	v_and_b32_e32 v132, 0x1f0, v0
	v_mov_b32_e32 v133, v1
	v_lshl_add_u64 v[130:131], v[130:131], 0, v[132:133]
	s_mov_b32 m0, s2
	s_mov_b64 s[34:35], 0x2000
	global_load_lds_dwordx4 v[130:131], off
	v_lshl_add_u64 v[132:133], v[130:131], 0, s[34:35]
	s_or_b32 m0, s2, 0x400
	s_mov_b64 s[36:37], 0x4000
	global_load_lds_dwordx4 v[132:133], off
	v_lshl_add_u64 v[132:133], v[130:131], 0, s[36:37]
	s_or_b32 m0, s2, 0x800
	s_mov_b64 s[40:41], 0x6000
	global_load_lds_dwordx4 v[132:133], off
	v_lshl_add_u64 v[132:133], v[130:131], 0, s[40:41]
	s_or_b32 m0, s2, 0xc00
	s_mov_b64 s[44:45], 0x8000
	global_load_lds_dwordx4 v[132:133], off
	v_lshl_add_u64 v[132:133], v[130:131], 0, s[44:45]
	s_or_b32 m0, s2, 0x1000
	s_mov_b64 s[46:47], 0xa000
	global_load_lds_dwordx4 v[132:133], off
	v_lshl_add_u64 v[132:133], v[130:131], 0, s[46:47]
	s_or_b32 m0, s2, 0x1400
	s_mov_b64 s[52:53], 0xc000
	global_load_lds_dwordx4 v[132:133], off
	v_lshl_add_u64 v[132:133], v[130:131], 0, s[52:53]
	s_or_b32 m0, s2, 0x1800
	s_mov_b64 s[54:55], 0xe000
	global_load_lds_dwordx4 v[132:133], off
	v_lshl_add_u64 v[130:131], v[130:131], 0, s[54:55]
	s_or_b32 m0, s2, 0x1c00
	v_add_u32_e32 v0, s7, v136
	global_load_lds_dwordx4 v[130:131], off
	v_add_u32_e32 v134, s7, v144
	v_add_u32_e32 v130, v0, v143
	v_add_u32_e32 v135, v134, v146
	ds_read_b128 v[130:133], v130
	ds_read_b128 v[170:173], v135
	v_add_u32_e32 v135, s7, v145
	v_add_u32_e32 v136, v135, v149
	v_add_u32_e32 v143, s7, v150
	v_add_u32_e32 v144, v143, v155
	ds_read_b128 v[174:177], v136 offset:32768
	ds_read_b128 v[178:181], v144 offset:32768
	v_add_u32_e32 v136, s7, v156
	v_add_u32_e32 v144, v136, v157
	v_add_u32_e32 v149, s7, v158
	v_add_u32_e32 v145, v149, v168
	ds_read_b128 v[182:185], v144 offset:32768
	ds_read_b128 v[186:189], v145 offset:32768
	v_add_u32_e32 v144, v0, v166
	v_add_u32_e32 v145, v134, v167
	ds_read_b128 v[166:169], v144
	ds_read_b128 v[190:193], v145
	v_add_u32_e32 v144, v135, v163
	v_add_u32_e32 v145, v143, v164
	ds_read_b128 v[194:197], v144 offset:32768
	ds_read_b128 v[198:201], v145 offset:32768
	v_add_u32_e32 v144, v136, v159
	v_add_u32_e32 v145, v149, v160
	ds_read_b128 v[156:159], v144 offset:32768
	ds_read_b128 v[202:205], v145 offset:32768
	v_readlane_b32 s31, v253, 28
	s_setprio 1
	s_waitcnt lgkmcnt(0)
	v_mfma_f32_32x32x16_bf16 v[114:129], v[130:133], v[174:177], v[114:129]
	v_mfma_f32_32x32x16_bf16 v[98:113], v[130:133], v[178:181], v[98:113]
	v_mfma_f32_32x32x16_bf16 v[82:97], v[130:133], v[182:185], v[82:97]
	v_mfma_f32_32x32x16_bf16 v[66:81], v[130:133], v[186:189], v[66:81]
	v_mfma_f32_32x32x16_bf16 v[50:65], v[170:173], v[174:177], v[50:65]
	v_mfma_f32_32x32x16_bf16 v[34:49], v[170:173], v[178:181], v[34:49]
	v_mfma_f32_32x32x16_bf16 v[18:33], v[170:173], v[182:185], v[18:33]
	v_mfma_f32_32x32x16_bf16 v[2:17], v[170:173], v[186:189], v[2:17]
	s_setprio 0
	v_add_u32_e32 v130, v0, v153
	v_add_u32_e32 v144, v134, v154
	ds_read_b128 v[130:133], v130
	ds_read_b128 v[170:173], v144
	v_add_u32_e32 v144, v135, v151
	v_add_u32_e32 v145, v143, v152
	ds_read_b128 v[150:153], v144 offset:32768
	ds_read_b128 v[174:177], v145 offset:32768
	v_add_u32_e32 v144, v136, v147
	v_add_u32_e32 v148, v149, v148
	ds_read_b128 v[144:147], v144 offset:32768
	ds_read_b128 v[178:181], v148 offset:32768
	s_setprio 1
	v_mfma_f32_32x32x16_bf16 v[114:129], v[166:169], v[194:197], v[114:129]
	v_mfma_f32_32x32x16_bf16 v[98:113], v[166:169], v[198:201], v[98:113]
	v_mfma_f32_32x32x16_bf16 v[82:97], v[166:169], v[156:159], v[82:97]
	v_mfma_f32_32x32x16_bf16 v[66:81], v[166:169], v[202:205], v[66:81]
	v_mfma_f32_32x32x16_bf16 v[50:65], v[190:193], v[194:197], v[50:65]
	v_mfma_f32_32x32x16_bf16 v[34:49], v[190:193], v[198:201], v[34:49]
	v_mfma_f32_32x32x16_bf16 v[18:33], v[190:193], v[156:159], v[18:33]
	v_mfma_f32_32x32x16_bf16 v[2:17], v[190:193], v[202:205], v[2:17]
	s_setprio 0
	v_add_u32_e32 v0, v0, v141
	v_add_u32_e32 v134, v134, v142
	ds_read_b128 v[154:157], v0
	ds_read_b128 v[158:161], v134
	v_add_u32_e32 v0, v135, v139
	v_add_u32_e32 v134, v143, v140
	ds_read_b128 v[140:143], v0 offset:32768
	ds_read_b128 v[166:169], v134 offset:32768
	v_add_u32_e32 v0, v136, v137
	v_add_u32_e32 v138, v149, v138
	ds_read_b128 v[134:137], v0 offset:32768
	ds_read_b128 v[182:185], v138 offset:32768
	s_setprio 1
	s_waitcnt lgkmcnt(9)
	v_mfma_f32_32x32x16_bf16 v[114:129], v[130:133], v[150:153], v[114:129]
	s_waitcnt lgkmcnt(8)
	v_mfma_f32_32x32x16_bf16 v[98:113], v[130:133], v[174:177], v[98:113]
	s_waitcnt lgkmcnt(7)
	v_mfma_f32_32x32x16_bf16 v[82:97], v[130:133], v[144:147], v[82:97]
	s_waitcnt lgkmcnt(6)
	v_mfma_f32_32x32x16_bf16 v[66:81], v[130:133], v[178:181], v[66:81]
	v_mfma_f32_32x32x16_bf16 v[50:65], v[170:173], v[150:153], v[50:65]
	v_mfma_f32_32x32x16_bf16 v[34:49], v[170:173], v[174:177], v[34:49]
	v_mfma_f32_32x32x16_bf16 v[18:33], v[170:173], v[144:147], v[18:33]
	v_mfma_f32_32x32x16_bf16 v[2:17], v[170:173], v[178:181], v[2:17]
	s_setprio 0
	s_setprio 1
	s_waitcnt lgkmcnt(3)
	v_mfma_f32_32x32x16_bf16 v[114:129], v[154:157], v[140:143], v[114:129]
	s_waitcnt lgkmcnt(2)
	v_mfma_f32_32x32x16_bf16 v[98:113], v[154:157], v[166:169], v[98:113]
	s_waitcnt lgkmcnt(1)
	v_mfma_f32_32x32x16_bf16 v[82:97], v[154:157], v[134:137], v[82:97]
	s_waitcnt lgkmcnt(0)
	v_mfma_f32_32x32x16_bf16 v[66:81], v[154:157], v[182:185], v[66:81]
	v_mfma_f32_32x32x16_bf16 v[50:65], v[158:161], v[140:143], v[50:65]
	v_mfma_f32_32x32x16_bf16 v[34:49], v[158:161], v[166:169], v[34:49]
	v_mfma_f32_32x32x16_bf16 v[18:33], v[158:161], v[134:137], v[18:33]
	v_mfma_f32_32x32x16_bf16 v[2:17], v[158:161], v[182:185], v[2:17]
	s_setprio 0
	v_mov_b32_e32 v164, v216
	s_waitcnt vmcnt(0)
	s_barrier
;   DI void xpass(int ps, int grow0, int gcol0, int lane, int w, char* lds) const {
;     char* xs = lds + (ps & 1) * 65536 + __builtin_amdgcn_readfirstlane(w) * 8192;
;     const float* xsrc = Xin + (size_t)(grow0 + (ps >> 1) * 32 + (ps & 1) * 16 + (lane >> 5)) * D_ + gcol0 + (lane & 31) * 4;
; #pragma unroll
;     for (int pc = 0; pc < 8; ++pc)
;       __builtin_amdgcn_global_load_lds((const unsigned*)(xsrc + (size_t)(2 * pc) * D_), (__attribute__((address_space(3))) unsigned*)(xs + pc * 1024), 16, 0, 0);
;   }
;   DI void operator()(f32x16 (&acc)[2][4], int grow0, int gcol0, int lane, int w, char* lds) {
;     float* red = (float*)(lds + 131072); float* stat = (float*)lds;
;     const int l31 = lane & 31, hh = lane >> 5, tid = w * 64 + lane;
;     const int pm = grow0 >> 8, pn = gcol0 >> 8, wn = (gcol0 >> 7) & 1, lrow0 = grow0 & 255;
;     float bia[4], csc[4];
; #pragma unroll
;     for (int nt = 0; nt < 4; ++nt) { int c = gcol0 + nt * 32 + l31; bia[nt] = bias ? bias[c] : 0.f; csc[nt] = cscale ? cscale[c] : 1.f; }
;     float* redw = red + ((wn * 2 + ((lane >> 4) & 1)) * 256 + lrow0 + 4 * hh) * 2;
; #pragma unroll
;     for (int ps = 0; ps < 4; ++ps) {
;       const int mt = ps >> 1;
;       if (ps + 1 < 4) {
;         if (ps >= 1) asm volatile("s_waitcnt lgkmcnt(0)" ::: "memory");
;         xpass(ps + 1, grow0, gcol0, lane, w, lds);
;         if (ps >= 1) asm volatile("s_waitcnt vmcnt(8)" ::: "memory");
;       } else asm volatile("s_waitcnt vmcnt(0)" ::: "memory");
;       const char* xs = lds + (ps & 1) * 65536 + w * 8192;
; #pragma unroll
;       for (int qq = 0; qq < 2; ++qq)
; #pragma unroll
;         for (int e = 0; e < 4; ++e) {
;           const int i = 4 * (2 * (ps & 1) + qq) + e;
;           const float* xr = (const float*)(xs + (8 * qq + 4 * hh + e) * 512) + l31;
;           float s1 = 0.f, s2 = 0.f;
; #pragma unroll
;           for (int nt = 0; nt < 4; ++nt) {
;             float v = (acc[mt][nt][i] + bia[nt]) * csc[nt];
;             float z = ALPHA * xr[nt * 32] + hs * v;
;             acc[mt][nt][i] = z; s1 += z; s2 += z * z;
;           }
;           s1 = row16_sum(s1); s2 = row16_sum(s2);
;           if ((lane & 15) == 0) { f32x2 sv = {s1, s2}; *(f32x2*)(redw + (mt * 32 + (i & 3) + 8 * (i >> 2)) * 2) = sv; }
;         }
	v_mov_b32_e32 v133, v1
	v_ashrrev_i32_e32 v158, 6, v164
	v_lshrrev_b32_e32 v0, 30, v158
	v_add_u32_e32 v0, v158, v0
	v_ashrrev_i32_e32 v134, 2, v0
	v_mul_i32_i24_e32 v0, 4, v134
	v_sub_u32_e32 v0, v158, v0
	v_lshlrev_b32_e32 v135, 6, v0
	v_add_u32_e32 v163, s3, v135
	v_bfe_u32 v0, v164, 5, 1
	v_or_b32_e32 v159, v163, v0
	v_or_b32_e32 v130, 16, v159
	v_lshlrev_b32_e32 v200, 2, v164
	v_ashrrev_i32_e32 v131, 31, v130
	v_lshl_add_u32 v182, v134, 7, s30
	v_and_b32_e32 v0, 0x7c, v200
	v_lshlrev_b64 v[130:131], 12, v[130:131]
	v_ashrrev_i32_e32 v183, 31, v182
	v_readfirstlane_b32 s2, v158
	v_lshl_add_u64 v[130:131], s[10:11], 0, v[130:131]
	v_lshlrev_b32_e32 v0, 2, v0
	s_lshl_b32 s2, s2, 13
	v_lshl_add_u64 v[130:131], v[182:183], 2, v[130:131]
	v_mov_b32_e32 v132, v0
	s_add_i32 m0, s2, 0x10000
	v_lshl_add_u64 v[130:131], v[130:131], 0, v[132:133]
	global_load_lds_dwordx4 v[130:131], off
	v_lshl_add_u64 v[132:133], v[130:131], 0, s[34:35]
	s_add_i32 m0, s2, 0x10400
	v_and_b32_e32 v210, 0xc0, v135
	global_load_lds_dwordx4 v[132:133], off
	v_lshl_add_u64 v[132:133], v[130:131], 0, s[36:37]
	s_add_i32 m0, s2, 0x10800
	v_mov_b32_e32 v136, v114
	global_load_lds_dwordx4 v[132:133], off
	v_lshl_add_u64 v[132:133], v[130:131], 0, s[40:41]
	s_add_i32 m0, s2, 0x10c00
	v_mov_b32_e32 v137, v82
	global_load_lds_dwordx4 v[132:133], off
	v_lshl_add_u64 v[132:133], v[130:131], 0, s[44:45]
	s_add_i32 m0, s2, 0x11000
	v_mov_b32_e32 v140, v98
	global_load_lds_dwordx4 v[132:133], off
	v_lshl_add_u64 v[132:133], v[130:131], 0, s[46:47]
	s_add_i32 m0, s2, 0x11400
	v_mov_b32_e32 v141, v82
	global_load_lds_dwordx4 v[132:133], off
	v_lshl_add_u64 v[132:133], v[130:131], 0, s[52:53]
	s_add_i32 m0, s2, 0x11800
	v_lshl_add_u64 v[130:131], v[130:131], 0, s[54:55]
	global_load_lds_dwordx4 v[132:133], off
	s_add_i32 m0, s2, 0x11c00
	v_bfe_u32 v132, v164, 4, 1
	global_load_lds_dwordx4 v[130:131], off
	v_and_b32_e32 v130, 31, v164
	v_lshlrev_b32_e32 v131, 1, v134
	v_bfe_u32 v134, v164, 3, 3
	v_and_or_b32 v131, v131, 2, v132
	v_and_b32_e32 v132, 4, v134
	v_lshlrev_b32_e32 v130, 2, v130
	v_lshl_or_b32 v138, v158, 13, v130
	v_lshlrev_b32_e32 v154, 9, v132
	v_or_b32_e32 v133, v210, v132
	v_and_b32_e32 v130, 15, v164
	v_or_b32_e32 v132, v138, v154
	v_lshlrev_b32_e32 v135, 3, v133
	v_lshl_or_b32 v139, v131, 11, v221
	v_cmp_eq_u32_e32 vcc, 0, v130
	s_waitcnt vmcnt(8)
	ds_read2_b32 v[130:131], v132 offset1:32
	ds_read2_b32 v[132:133], v132 offset0:64 offset1:96
	v_pk_add_f32 v[136:137], v[136:137], 0 op_sel_hi:[1,0]
	v_pk_add_f32 v[140:141], v[140:141], 0 op_sel_hi:[1,0]
	s_mov_b32 s2, s67
	s_waitcnt lgkmcnt(0)
	v_mov_b32_e32 v142, v130
	v_mov_b32_e32 v143, v132
	v_mov_b32_e32 v130, v131
	v_mov_b32_e32 v131, v132
	v_pk_fma_f32 v[186:187], v[142:143], s[2:3], v[136:137] op_sel_hi:[1,0,1]
	v_pk_fma_f32 v[188:189], v[130:131], s[2:3], v[140:141] op_sel_hi:[1,0,1]
	v_pk_mul_f32 v[144:145], v[142:143], s[2:3] op_sel_hi:[1,0]
	v_pk_mul_f32 v[142:143], v[186:187], v[186:187]
	v_pk_mul_f32 v[130:131], v[188:189], v[188:189]
	v_pk_mov_b32 v[136:137], v[136:137], v[142:143] op_sel:[1,0]
	v_pk_mov_b32 v[130:131], v[144:145], v[130:131] op_sel:[1,0]
	v_add_f32_e32 v178, 0, v66
	v_pk_add_f32 v[130:131], v[136:137], v[130:131]
	v_pk_add_f32 v[136:137], v[186:187], v[188:189]
	v_pk_mul_f32 v[140:141], v[186:187], v[188:189]
	v_fmac_f32_e32 v178, 0x3fd744fd, v133
	v_mov_b32_e32 v137, v141
	v_pk_add_f32 v[130:131], v[136:137], v[130:131]
	v_mul_f32_e32 v179, v178, v178
	v_pk_add_f32 v[130:131], v[130:131], v[178:179]
	v_add_u32_e32 v179, v139, v135
	s_nop 0
	v_mov_b32_dpp v132, v130 quad_perm:[1,0,3,2] row_mask:0xf bank_mask:0xf bound_ctrl:1
	v_mov_b32_dpp v133, v131 quad_perm:[1,0,3,2] row_mask:0xf bank_mask:0xf bound_ctrl:1
	v_pk_add_f32 v[130:131], v[130:131], v[132:133]
	s_nop 1
	v_mov_b32_dpp v132, v130 quad_perm:[2,3,0,1] row_mask:0xf bank_mask:0xf bound_ctrl:1
	v_mov_b32_dpp v133, v131 quad_perm:[2,3,0,1] row_mask:0xf bank_mask:0xf bound_ctrl:1
	v_pk_add_f32 v[130:131], v[130:131], v[132:133]
	s_nop 1
	v_mov_b32_dpp v132, v130 row_half_mirror row_mask:0xf bank_mask:0xf bound_ctrl:1
	v_mov_b32_dpp v133, v131 row_half_mirror row_mask:0xf bank_mask:0xf bound_ctrl:1
	v_pk_add_f32 v[130:131], v[130:131], v[132:133]
	s_nop 1
	v_mov_b32_dpp v132, v130 row_mirror row_mask:0xf bank_mask:0xf bound_ctrl:1
	v_mov_b32_dpp v133, v131 row_mirror row_mask:0xf bank_mask:0xf bound_ctrl:1
	s_and_saveexec_b64 s[6:7], vcc
	v_pk_add_f32 v[130:131], v[130:131], v[132:133]
	ds_write_b64 v179, v[130:131]
	s_or_b64 exec, exec, s[6:7]
	v_add_u32_e32 v168, v138, v154
	ds_read2_b32 v[130:131], v168 offset0:128 offset1:160
	ds_read2_b32 v[132:133], v168 offset0:192 offset1:224
	v_mov_b32_e32 v82, v115
	v_add_f32_e32 v152, 0, v67
	v_pk_add_f32 v[66:67], v[82:83], 0 op_sel_hi:[1,0]
	v_mov_b32_e32 v82, v99
	v_pk_add_f32 v[82:83], v[82:83], 0 op_sel_hi:[1,0]
	s_waitcnt lgkmcnt(1)
	v_mov_b32_e32 v98, v130
	s_waitcnt lgkmcnt(0)
;   DI void operator()(f32x16 (&acc)[2][4], int grow0, int gcol0, int lane, int w, char* lds) {
;     ...
;         for (int e = 0; e < 4; ++e) {
;           const int i = 4 * (2 * (ps & 1) + qq) + e;
;           const float* xr = (const float*)(xs + (8 * qq + 4 * hh + e) * 512) + l31;
;           float s1 = 0.f, s2 = 0.f;
; #pragma unroll
;           for (int nt = 0; nt < 4; ++nt) {
;             float v = (acc[mt][nt][i] + bia[nt]) * csc[nt];
;             float z = ALPHA * xr[nt * 32] + hs * v;
;             acc[mt][nt][i] = z; s1 += z; s2 += z * z;
;           }
;           s1 = row16_sum(s1); s2 = row16_sum(s2);
;           if ((lane & 15) == 0) { f32x2 sv = {s1, s2}; *(f32x2*)(redw + (mt * 32 + (i & 3) + 8 * (i >> 2)) * 2) = sv; }
	v_mov_b32_e32 v99, v132
	s_mov_b32 s2, s67
	v_mov_b32_e32 v130, v131
	v_mov_b32_e32 v131, v132
	v_pk_fma_f32 v[166:167], v[98:99], s[2:3], v[66:67] op_sel_hi:[1,0,1]
	v_pk_fma_f32 v[172:173], v[130:131], s[2:3], v[82:83] op_sel_hi:[1,0,1]
	v_pk_mul_f32 v[114:115], v[98:99], s[2:3] op_sel_hi:[1,0]
	v_pk_mul_f32 v[98:99], v[166:167], v[166:167]
	v_pk_mul_f32 v[82:83], v[172:173], v[172:173]
	v_pk_mov_b32 v[66:67], v[66:67], v[98:99] op_sel:[1,0]
	v_pk_mov_b32 v[82:83], v[114:115], v[82:83] op_sel:[1,0]
	v_pk_mul_f32 v[98:99], v[166:167], v[172:173]
	v_pk_add_f32 v[66:67], v[66:67], v[82:83]
	v_pk_add_f32 v[82:83], v[166:167], v[172:173]
	v_fmac_f32_e32 v152, 0x3fd744fd, v133
	v_mov_b32_e32 v83, v99
	v_pk_add_f32 v[66:67], v[82:83], v[66:67]
	v_mul_f32_e32 v153, v152, v152
	v_pk_add_f32 v[66:67], v[66:67], v[152:153]
	s_nop 1
	v_mov_b32_dpp v82, v66 quad_perm:[1,0,3,2] row_mask:0xf bank_mask:0xf bound_ctrl:1
	v_mov_b32_dpp v83, v67 quad_perm:[1,0,3,2] row_mask:0xf bank_mask:0xf bound_ctrl:1
	v_pk_add_f32 v[66:67], v[66:67], v[82:83]
	s_nop 1
	v_mov_b32_dpp v82, v66 quad_perm:[2,3,0,1] row_mask:0xf bank_mask:0xf bound_ctrl:1
	v_mov_b32_dpp v83, v67 quad_perm:[2,3,0,1] row_mask:0xf bank_mask:0xf bound_ctrl:1
	v_pk_add_f32 v[66:67], v[66:67], v[82:83]
	s_nop 1
	v_mov_b32_dpp v82, v66 row_half_mirror row_mask:0xf bank_mask:0xf bound_ctrl:1
	v_mov_b32_dpp v83, v67 row_half_mirror row_mask:0xf bank_mask:0xf bound_ctrl:1
	v_pk_add_f32 v[66:67], v[66:67], v[82:83]
	s_nop 1
	v_mov_b32_dpp v82, v66 row_mirror row_mask:0xf bank_mask:0xf bound_ctrl:1
	v_mov_b32_dpp v83, v67 row_mirror row_mask:0xf bank_mask:0xf bound_ctrl:1
	s_and_saveexec_b64 s[6:7], vcc
	v_readlane_b32 s63, v254, 51
	v_readlane_b32 s65, v254, 48
	v_readlane_b32 s70, v254, 52
	v_readlane_b32 s71, v255, 50
	v_pk_add_f32 v[66:67], v[66:67], v[82:83]
	ds_write_b64 v179, v[66:67] offset:8
	s_or_b64 exec, exec, s[6:7]
	v_add_u32_e32 v153, 0x400, v168
	ds_read2_b32 v[82:83], v153 offset1:32
	ds_read2_b32 v[98:99], v153 offset0:64 offset1:96
	v_mov_b32_e32 v114, v116
	v_mov_b32_e32 v115, v84
	v_mov_b32_e32 v130, v100
	v_mov_b32_e32 v131, v84
	v_pk_add_f32 v[114:115], v[114:115], 0 op_sel_hi:[1,0]
	v_pk_add_f32 v[130:131], v[130:131], 0 op_sel_hi:[1,0]
	s_waitcnt lgkmcnt(1)
	v_mov_b32_e32 v132, v82
	s_waitcnt lgkmcnt(0)
	v_mov_b32_e32 v133, v98
	s_mov_b32 s2, s67
	v_mov_b32_e32 v140, v83
	v_mov_b32_e32 v141, v98
	v_pk_fma_f32 v[82:83], v[132:133], s[2:3], v[114:115] op_sel_hi:[1,0,1]
	v_pk_fma_f32 v[150:151], v[140:141], s[2:3], v[130:131] op_sel_hi:[1,0,1]
	v_pk_mul_f32 v[136:137], v[132:133], s[2:3] op_sel_hi:[1,0]
	v_pk_mul_f32 v[132:133], v[82:83], v[82:83]
	v_pk_mul_f32 v[130:131], v[150:151], v[150:151]
	v_pk_mov_b32 v[114:115], v[114:115], v[132:133] op_sel:[1,0]
	v_pk_mov_b32 v[130:131], v[136:137], v[130:131] op_sel:[1,0]
	v_add_f32_e32 v66, 0, v68
	v_pk_add_f32 v[114:115], v[114:115], v[130:131]
	v_pk_add_f32 v[130:131], v[82:83], v[150:151]
	v_pk_mul_f32 v[132:133], v[82:83], v[150:151]
	v_fmac_f32_e32 v66, 0x3fd744fd, v99
	v_mov_b32_e32 v131, v133
	v_pk_add_f32 v[114:115], v[130:131], v[114:115]
	v_mul_f32_e32 v67, v66, v66
	v_pk_add_f32 v[98:99], v[114:115], v[66:67]
	s_nop 1
	v_mov_b32_dpp v114, v98 quad_perm:[1,0,3,2] row_mask:0xf bank_mask:0xf bound_ctrl:1
	v_mov_b32_dpp v115, v99 quad_perm:[1,0,3,2] row_mask:0xf bank_mask:0xf bound_ctrl:1
	v_pk_add_f32 v[98:99], v[98:99], v[114:115]
	s_nop 1
	v_mov_b32_dpp v114, v98 quad_perm:[2,3,0,1] row_mask:0xf bank_mask:0xf bound_ctrl:1
	v_mov_b32_dpp v115, v99 quad_perm:[2,3,0,1] row_mask:0xf bank_mask:0xf bound_ctrl:1
	v_pk_add_f32 v[98:99], v[98:99], v[114:115]
	s_nop 1
	v_mov_b32_dpp v114, v98 row_half_mirror row_mask:0xf bank_mask:0xf bound_ctrl:1
	v_mov_b32_dpp v115, v99 row_half_mirror row_mask:0xf bank_mask:0xf bound_ctrl:1
	v_pk_add_f32 v[98:99], v[98:99], v[114:115]
	s_nop 1
	v_mov_b32_dpp v114, v98 row_mirror row_mask:0xf bank_mask:0xf bound_ctrl:1
	v_mov_b32_dpp v115, v99 row_mirror row_mask:0xf bank_mask:0xf bound_ctrl:1
	s_and_saveexec_b64 s[6:7], vcc
	v_pk_add_f32 v[98:99], v[98:99], v[114:115]
	ds_write_b64 v179, v[98:99] offset:16
	s_or_b64 exec, exec, s[6:7]
	v_lshlrev_b32_e32 v139, 9, v134
	v_or_b32_e32 v146, 0x600, v139
	v_add_u32_e32 v151, v138, v146
	ds_read2_b32 v[98:99], v151 offset1:32
	ds_read2_b32 v[114:115], v151 offset0:64 offset1:96
	v_mov_b32_e32 v84, v117
	v_pk_add_f32 v[116:117], v[84:85], 0 op_sel_hi:[1,0]
	v_mov_b32_e32 v84, v101
	v_pk_add_f32 v[84:85], v[84:85], 0 op_sel_hi:[1,0]
	s_waitcnt lgkmcnt(1)
	v_mov_b32_e32 v100, v98
	s_waitcnt lgkmcnt(0)
;   DI void operator()(f32x16 (&acc)[2][4], int grow0, int gcol0, int lane, int w, char* lds) {
;     ...
;         for (int e = 0; e < 4; ++e) {
;           const int i = 4 * (2 * (ps & 1) + qq) + e;
;           const float* xr = (const float*)(xs + (8 * qq + 4 * hh + e) * 512) + l31;
;           float s1 = 0.f, s2 = 0.f;
; #pragma unroll
;           for (int nt = 0; nt < 4; ++nt) {
;             float v = (acc[mt][nt][i] + bia[nt]) * csc[nt];
;             float z = ALPHA * xr[nt * 32] + hs * v;
;             acc[mt][nt][i] = z; s1 += z; s2 += z * z;
;           }
;           s1 = row16_sum(s1); s2 = row16_sum(s2);
;           if ((lane & 15) == 0) { f32x2 sv = {s1, s2}; *(f32x2*)(redw + (mt * 32 + (i & 3) + 8 * (i >> 2)) * 2) = sv; }
	v_mov_b32_e32 v101, v114
	s_mov_b32 s2, s67
	v_mov_b32_e32 v132, v99
	v_mov_b32_e32 v133, v114
	v_pk_mul_f32 v[130:131], v[100:101], s[2:3] op_sel_hi:[1,0]
	v_pk_fma_f32 v[98:99], v[100:101], s[2:3], v[116:117] op_sel_hi:[1,0,1]
	v_pk_fma_f32 v[100:101], v[132:133], s[2:3], v[84:85] op_sel_hi:[1,0,1]
	v_pk_mul_f32 v[134:135], v[98:99], v[98:99]
	v_pk_mul_f32 v[84:85], v[100:101], v[100:101]
	v_pk_mov_b32 v[116:117], v[116:117], v[134:135] op_sel:[1,0]
	v_pk_mov_b32 v[84:85], v[130:131], v[84:85] op_sel:[1,0]
	v_add_f32_e32 v68, 0, v69
	v_pk_add_f32 v[84:85], v[116:117], v[84:85]
	v_pk_add_f32 v[116:117], v[98:99], v[100:101]
	v_pk_mul_f32 v[130:131], v[98:99], v[100:101]
	v_fmac_f32_e32 v68, 0x3fd744fd, v115
	v_mov_b32_e32 v117, v131
	v_pk_add_f32 v[84:85], v[116:117], v[84:85]
	v_mul_f32_e32 v69, v68, v68
	v_pk_add_f32 v[84:85], v[84:85], v[68:69]
	s_nop 1
	v_mov_b32_dpp v114, v84 quad_perm:[1,0,3,2] row_mask:0xf bank_mask:0xf bound_ctrl:1
	v_mov_b32_dpp v115, v85 quad_perm:[1,0,3,2] row_mask:0xf bank_mask:0xf bound_ctrl:1
	v_pk_add_f32 v[84:85], v[84:85], v[114:115]
	s_nop 1
	v_mov_b32_dpp v114, v84 quad_perm:[2,3,0,1] row_mask:0xf bank_mask:0xf bound_ctrl:1
	v_mov_b32_dpp v115, v85 quad_perm:[2,3,0,1] row_mask:0xf bank_mask:0xf bound_ctrl:1
	v_pk_add_f32 v[84:85], v[84:85], v[114:115]
	s_nop 1
	v_mov_b32_dpp v114, v84 row_half_mirror row_mask:0xf bank_mask:0xf bound_ctrl:1
	v_mov_b32_dpp v115, v85 row_half_mirror row_mask:0xf bank_mask:0xf bound_ctrl:1
	v_pk_add_f32 v[84:85], v[84:85], v[114:115]
	s_nop 1
	v_mov_b32_dpp v114, v84 row_mirror row_mask:0xf bank_mask:0xf bound_ctrl:1
	v_mov_b32_dpp v115, v85 row_mirror row_mask:0xf bank_mask:0xf bound_ctrl:1
	s_and_saveexec_b64 s[6:7], vcc
	v_pk_add_f32 v[84:85], v[84:85], v[114:115]
	ds_write_b64 v179, v[84:85] offset:24
	s_or_b64 exec, exec, s[6:7]
	v_add_u32_e32 v67, 0x1000, v168
	ds_read2_b32 v[114:115], v67 offset1:32
	ds_read2_b32 v[130:131], v67 offset0:64 offset1:96
	v_mov_b32_e32 v116, v118
	v_mov_b32_e32 v117, v86
	v_pk_add_f32 v[132:133], v[116:117], 0 op_sel_hi:[1,0]
	v_mov_b32_e32 v116, v102
	v_pk_add_f32 v[116:117], v[116:117], 0 op_sel_hi:[1,0]
	s_waitcnt lgkmcnt(1)
	v_mov_b32_e32 v134, v114
	s_waitcnt lgkmcnt(0)
	v_mov_b32_e32 v135, v130
	s_mov_b32 s2, s67
	v_mov_b32_e32 v140, v115
	v_mov_b32_e32 v141, v130
	v_pk_fma_f32 v[114:115], v[134:135], s[2:3], v[132:133] op_sel_hi:[1,0,1]
	v_pk_fma_f32 v[116:117], v[140:141], s[2:3], v[116:117] op_sel_hi:[1,0,1]
	v_pk_mul_f32 v[136:137], v[134:135], s[2:3] op_sel_hi:[1,0]
	v_pk_mul_f32 v[134:135], v[114:115], v[114:115]
	v_pk_mul_f32 v[140:141], v[116:117], v[116:117]
	v_pk_mov_b32 v[132:133], v[132:133], v[134:135] op_sel:[1,0]
	v_pk_mov_b32 v[134:135], v[136:137], v[140:141] op_sel:[1,0]
	v_add_f32_e32 v84, 0, v70
	v_pk_add_f32 v[132:133], v[132:133], v[134:135]
	v_pk_add_f32 v[134:135], v[114:115], v[116:117]
	v_pk_mul_f32 v[136:137], v[114:115], v[116:117]
	v_fmac_f32_e32 v84, 0x3fd744fd, v131
	v_mov_b32_e32 v135, v137
	v_pk_add_f32 v[132:133], v[134:135], v[132:133]
	v_mul_f32_e32 v85, v84, v84
	v_pk_add_f32 v[130:131], v[132:133], v[84:85]
	s_nop 1
	v_mov_b32_dpp v132, v130 quad_perm:[1,0,3,2] row_mask:0xf bank_mask:0xf bound_ctrl:1
	v_mov_b32_dpp v133, v131 quad_perm:[1,0,3,2] row_mask:0xf bank_mask:0xf bound_ctrl:1
	v_pk_add_f32 v[130:131], v[130:131], v[132:133]
	s_nop 1
	v_mov_b32_dpp v132, v130 quad_perm:[2,3,0,1] row_mask:0xf bank_mask:0xf bound_ctrl:1
	v_mov_b32_dpp v133, v131 quad_perm:[2,3,0,1] row_mask:0xf bank_mask:0xf bound_ctrl:1
	v_pk_add_f32 v[130:131], v[130:131], v[132:133]
	s_nop 1
	v_mov_b32_dpp v132, v130 row_half_mirror row_mask:0xf bank_mask:0xf bound_ctrl:1
	v_mov_b32_dpp v133, v131 row_half_mirror row_mask:0xf bank_mask:0xf bound_ctrl:1
	v_pk_add_f32 v[130:131], v[130:131], v[132:133]
	s_nop 1
	v_mov_b32_dpp v132, v130 row_mirror row_mask:0xf bank_mask:0xf bound_ctrl:1
	v_mov_b32_dpp v133, v131 row_mirror row_mask:0xf bank_mask:0xf bound_ctrl:1
	s_and_saveexec_b64 s[6:7], vcc
	v_pk_add_f32 v[130:131], v[130:131], v[132:133]
	ds_write_b64 v179, v[130:131] offset:64
	s_or_b64 exec, exec, s[6:7]
	ds_read2_b32 v[130:131], v67 offset0:128 offset1:160
	ds_read2_b32 v[132:133], v67 offset0:192 offset1:224
	v_mov_b32_e32 v86, v119
	v_pk_add_f32 v[134:135], v[86:87], 0 op_sel_hi:[1,0]
	v_mov_b32_e32 v86, v103
	v_pk_add_f32 v[86:87], v[86:87], 0 op_sel_hi:[1,0]
	s_waitcnt lgkmcnt(1)
	v_mov_b32_e32 v102, v130
	s_waitcnt lgkmcnt(0)
	v_mov_b32_e32 v103, v132
	s_mov_b32 s2, s67
	v_mov_b32_e32 v118, v131
	v_mov_b32_e32 v119, v132
	v_pk_mul_f32 v[136:137], v[102:103], s[2:3] op_sel_hi:[1,0]
	v_pk_fma_f32 v[102:103], v[102:103], s[2:3], v[134:135] op_sel_hi:[1,0,1]
	v_pk_fma_f32 v[118:119], v[118:119], s[2:3], v[86:87] op_sel_hi:[1,0,1]
	v_pk_mul_f32 v[130:131], v[102:103], v[102:103]
	v_pk_mul_f32 v[86:87], v[118:119], v[118:119]
	v_pk_mov_b32 v[130:131], v[134:135], v[130:131] op_sel:[1,0]
	v_pk_mov_b32 v[86:87], v[136:137], v[86:87] op_sel:[1,0]
	v_add_f32_e32 v70, 0, v71
	v_pk_add_f32 v[86:87], v[130:131], v[86:87]
	v_pk_add_f32 v[130:131], v[102:103], v[118:119]
	v_pk_mul_f32 v[134:135], v[102:103], v[118:119]
	v_fmac_f32_e32 v70, 0x3fd744fd, v133
	v_mov_b32_e32 v131, v135
	v_pk_add_f32 v[86:87], v[130:131], v[86:87]
	v_mul_f32_e32 v71, v70, v70
	v_pk_add_f32 v[86:87], v[86:87], v[70:71]
	s_nop 1
	v_mov_b32_dpp v130, v86 quad_perm:[1,0,3,2] row_mask:0xf bank_mask:0xf bound_ctrl:1
	v_mov_b32_dpp v131, v87 quad_perm:[1,0,3,2] row_mask:0xf bank_mask:0xf bound_ctrl:1
	v_pk_add_f32 v[86:87], v[86:87], v[130:131]
	s_nop 1
	v_mov_b32_dpp v130, v86 quad_perm:[2,3,0,1] row_mask:0xf bank_mask:0xf bound_ctrl:1
	v_mov_b32_dpp v131, v87 quad_perm:[2,3,0,1] row_mask:0xf bank_mask:0xf bound_ctrl:1
	v_pk_add_f32 v[86:87], v[86:87], v[130:131]
	s_nop 1
	v_mov_b32_dpp v130, v86 row_half_mirror row_mask:0xf bank_mask:0xf bound_ctrl:1
	v_mov_b32_dpp v131, v87 row_half_mirror row_mask:0xf bank_mask:0xf bound_ctrl:1
	v_pk_add_f32 v[86:87], v[86:87], v[130:131]
	s_nop 1
	v_mov_b32_dpp v130, v86 row_mirror row_mask:0xf bank_mask:0xf bound_ctrl:1
	v_mov_b32_dpp v131, v87 row_mirror row_mask:0xf bank_mask:0xf bound_ctrl:1
	s_and_saveexec_b64 s[6:7], vcc
	v_pk_add_f32 v[86:87], v[86:87], v[130:131]
	ds_write_b64 v179, v[86:87] offset:72
	s_or_b64 exec, exec, s[6:7]
	v_add_u32_e32 v69, 0x1400, v168
	ds_read2_b32 v[130:131], v69 offset1:32
	ds_read2_b32 v[134:135], v69 offset0:64 offset1:96
	v_mov_b32_e32 v132, v120
	v_mov_b32_e32 v133, v88
	v_pk_add_f32 v[136:137], v[132:133], 0 op_sel_hi:[1,0]
	v_mov_b32_e32 v132, v104
	v_pk_add_f32 v[132:133], v[132:133], 0 op_sel_hi:[1,0]
	s_waitcnt lgkmcnt(1)
;   DI void operator()(f32x16 (&acc)[2][4], int grow0, int gcol0, int lane, int w, char* lds) {
;     ...
;     for (int ps = 0; ps < 4; ++ps) {
;       const int mt = ps >> 1;
;       if (ps + 1 < 4) {
;         if (ps >= 1) asm volatile("s_waitcnt lgkmcnt(0)" ::: "memory");
;         xpass(ps + 1, grow0, gcol0, lane, w, lds);
;         if (ps >= 1) asm volatile("s_waitcnt vmcnt(8)" ::: "memory");
;       } else asm volatile("s_waitcnt vmcnt(0)" ::: "memory");
;       const char* xs = lds + (ps & 1) * 65536 + w * 8192;
; #pragma unroll
;       for (int qq = 0; qq < 2; ++qq)
; #pragma unroll
;         for (int e = 0; e < 4; ++e) {
;           const int i = 4 * (2 * (ps & 1) + qq) + e;
;           const float* xr = (const float*)(xs + (8 * qq + 4 * hh + e) * 512) + l31;
;           float s1 = 0.f, s2 = 0.f;
; #pragma unroll
;           for (int nt = 0; nt < 4; ++nt) {
;             float v = (acc[mt][nt][i] + bia[nt]) * csc[nt];
;             float z = ALPHA * xr[nt * 32] + hs * v;
;             acc[mt][nt][i] = z; s1 += z; s2 += z * z;
;           }
;           s1 = row16_sum(s1); s2 = row16_sum(s2);
;           if ((lane & 15) == 0) { f32x2 sv = {s1, s2}; *(f32x2*)(redw + (mt * 32 + (i & 3) + 8 * (i >> 2)) * 2) = sv; }
	v_mov_b32_e32 v140, v130
	s_waitcnt lgkmcnt(0)
	v_mov_b32_e32 v141, v134
	s_mov_b32 s2, s67
	v_mov_b32_e32 v144, v131
	v_mov_b32_e32 v145, v134
	v_pk_fma_f32 v[130:131], v[140:141], s[2:3], v[136:137] op_sel_hi:[1,0,1]
	v_pk_fma_f32 v[132:133], v[144:145], s[2:3], v[132:133] op_sel_hi:[1,0,1]
	v_pk_mul_f32 v[142:143], v[140:141], s[2:3] op_sel_hi:[1,0]
	v_pk_mul_f32 v[140:141], v[130:131], v[130:131]
	v_pk_mul_f32 v[144:145], v[132:133], v[132:133]
	v_pk_mov_b32 v[136:137], v[136:137], v[140:141] op_sel:[1,0]
	v_pk_mov_b32 v[140:141], v[142:143], v[144:145] op_sel:[1,0]
	v_add_f32_e32 v86, 0, v72
	v_pk_add_f32 v[136:137], v[136:137], v[140:141]
	v_pk_add_f32 v[140:141], v[130:131], v[132:133]
	v_pk_mul_f32 v[142:143], v[130:131], v[132:133]
	v_fmac_f32_e32 v86, 0x3fd744fd, v135
	v_mov_b32_e32 v141, v143
	v_pk_add_f32 v[136:137], v[140:141], v[136:137]
	v_mul_f32_e32 v87, v86, v86
	v_pk_add_f32 v[134:135], v[136:137], v[86:87]
	s_nop 1
	v_mov_b32_dpp v136, v134 quad_perm:[1,0,3,2] row_mask:0xf bank_mask:0xf bound_ctrl:1
	v_mov_b32_dpp v137, v135 quad_perm:[1,0,3,2] row_mask:0xf bank_mask:0xf bound_ctrl:1
	v_pk_add_f32 v[134:135], v[134:135], v[136:137]
	s_nop 1
	v_mov_b32_dpp v136, v134 quad_perm:[2,3,0,1] row_mask:0xf bank_mask:0xf bound_ctrl:1
	v_mov_b32_dpp v137, v135 quad_perm:[2,3,0,1] row_mask:0xf bank_mask:0xf bound_ctrl:1
	v_pk_add_f32 v[134:135], v[134:135], v[136:137]
	s_nop 1
	v_mov_b32_dpp v136, v134 row_half_mirror row_mask:0xf bank_mask:0xf bound_ctrl:1
	v_mov_b32_dpp v137, v135 row_half_mirror row_mask:0xf bank_mask:0xf bound_ctrl:1
	v_pk_add_f32 v[134:135], v[134:135], v[136:137]
	s_nop 1
	v_mov_b32_dpp v136, v134 row_mirror row_mask:0xf bank_mask:0xf bound_ctrl:1
	v_mov_b32_dpp v137, v135 row_mirror row_mask:0xf bank_mask:0xf bound_ctrl:1
	s_and_saveexec_b64 s[6:7], vcc
	v_pk_add_f32 v[134:135], v[134:135], v[136:137]
	ds_write_b64 v179, v[134:135] offset:80
	s_or_b64 exec, exec, s[6:7]
	v_or_b32_e32 v101, 0x1600, v139
	v_add_u32_e32 v71, v138, v101
	ds_read2_b32 v[134:135], v71 offset1:32
	ds_read2_b32 v[136:137], v71 offset0:64 offset1:96
	v_mov_b32_e32 v88, v121
	v_pk_add_f32 v[120:121], v[88:89], 0 op_sel_hi:[1,0]
	v_mov_b32_e32 v88, v105
	v_pk_add_f32 v[104:105], v[88:89], 0 op_sel_hi:[1,0]
	s_waitcnt lgkmcnt(1)
	v_mov_b32_e32 v88, v134
	s_waitcnt lgkmcnt(0)
	v_mov_b32_e32 v89, v136
	s_mov_b32 s2, s67
	v_mov_b32_e32 v134, v135
	v_mov_b32_e32 v135, v136
	v_pk_mul_f32 v[140:141], v[88:89], s[2:3] op_sel_hi:[1,0]
	v_pk_fma_f32 v[88:89], v[88:89], s[2:3], v[120:121] op_sel_hi:[1,0,1]
	v_pk_fma_f32 v[104:105], v[134:135], s[2:3], v[104:105] op_sel_hi:[1,0,1]
	v_pk_mul_f32 v[142:143], v[88:89], v[88:89]
	v_pk_mul_f32 v[134:135], v[104:105], v[104:105]
	v_pk_mov_b32 v[120:121], v[120:121], v[142:143] op_sel:[1,0]
	v_pk_mov_b32 v[134:135], v[140:141], v[134:135] op_sel:[1,0]
	v_add_f32_e32 v72, 0, v73
	v_pk_add_f32 v[120:121], v[120:121], v[134:135]
	v_pk_add_f32 v[134:135], v[88:89], v[104:105]
	v_pk_mul_f32 v[140:141], v[88:89], v[104:105]
	v_fmac_f32_e32 v72, 0x3fd744fd, v137
	v_mov_b32_e32 v135, v141
	v_pk_add_f32 v[120:121], v[134:135], v[120:121]
	v_mul_f32_e32 v73, v72, v72
	v_pk_add_f32 v[120:121], v[120:121], v[72:73]
	s_nop 1
	v_mov_b32_dpp v134, v120 quad_perm:[1,0,3,2] row_mask:0xf bank_mask:0xf bound_ctrl:1
	v_mov_b32_dpp v135, v121 quad_perm:[1,0,3,2] row_mask:0xf bank_mask:0xf bound_ctrl:1
	v_pk_add_f32 v[120:121], v[120:121], v[134:135]
	s_nop 1
	v_mov_b32_dpp v134, v120 quad_perm:[2,3,0,1] row_mask:0xf bank_mask:0xf bound_ctrl:1
	v_mov_b32_dpp v135, v121 quad_perm:[2,3,0,1] row_mask:0xf bank_mask:0xf bound_ctrl:1
	v_pk_add_f32 v[120:121], v[120:121], v[134:135]
	s_nop 1
	v_mov_b32_dpp v134, v120 row_half_mirror row_mask:0xf bank_mask:0xf bound_ctrl:1
	v_mov_b32_dpp v135, v121 row_half_mirror row_mask:0xf bank_mask:0xf bound_ctrl:1
	v_pk_add_f32 v[120:121], v[120:121], v[134:135]
	s_nop 1
	v_mov_b32_dpp v134, v120 row_mirror row_mask:0xf bank_mask:0xf bound_ctrl:1
	v_mov_b32_dpp v135, v121 row_mirror row_mask:0xf bank_mask:0xf bound_ctrl:1
	s_and_saveexec_b64 s[6:7], vcc
	v_pk_add_f32 v[120:121], v[120:121], v[134:135]
	ds_write_b64 v179, v[120:121] offset:88
	s_or_b64 exec, exec, s[6:7]
	v_or_b32_e32 v120, 32, v159
	v_ashrrev_i32_e32 v121, 31, v120
	v_lshlrev_b64 v[120:121], 12, v[120:121]
	v_readfirstlane_b32 s2, v158
	v_lshl_add_u64 v[120:121], s[10:11], 0, v[120:121]
	s_lshl_b32 s2, s2, 13
	v_lshl_add_u64 v[120:121], v[182:183], 2, v[120:121]
	s_waitcnt lgkmcnt(0)
	v_lshl_add_u64 v[120:121], v[120:121], 0, v[0:1]
	s_mov_b32 m0, s2
	s_mov_b64 s[6:7], 0x2000
	global_load_lds_dwordx4 v[120:121], off
	v_lshl_add_u64 v[134:135], v[120:121], 0, s[6:7]
	s_or_b32 m0, s2, 0x400
	s_mov_b64 s[6:7], 0x4000
	global_load_lds_dwordx4 v[134:135], off
	v_lshl_add_u64 v[134:135], v[120:121], 0, s[6:7]
	s_or_b32 m0, s2, 0x800
	s_mov_b64 s[6:7], 0x6000
	global_load_lds_dwordx4 v[134:135], off
	v_lshl_add_u64 v[134:135], v[120:121], 0, s[6:7]
	s_or_b32 m0, s2, 0xc00
	s_mov_b64 s[6:7], 0x8000
	global_load_lds_dwordx4 v[134:135], off
	v_lshl_add_u64 v[134:135], v[120:121], 0, s[6:7]
	s_or_b32 m0, s2, 0x1000
	s_mov_b64 s[6:7], 0xa000
	global_load_lds_dwordx4 v[134:135], off
	v_lshl_add_u64 v[134:135], v[120:121], 0, s[6:7]
	s_or_b32 m0, s2, 0x1400
	s_mov_b64 s[6:7], 0xc000
	global_load_lds_dwordx4 v[134:135], off
	v_lshl_add_u64 v[134:135], v[120:121], 0, s[6:7]
	s_or_b32 m0, s2, 0x1800
	s_mov_b64 s[6:7], 0xe000
	global_load_lds_dwordx4 v[134:135], off
	v_lshl_add_u64 v[120:121], v[120:121], 0, s[6:7]
	s_or_b32 m0, s2, 0x1c00
	v_add_u32_e32 v105, 0x10000, v138
	global_load_lds_dwordx4 v[120:121], off
	s_waitcnt vmcnt(8)
;   DI void operator()(f32x16 (&acc)[2][4], int grow0, int gcol0, int lane, int w, char* lds) {
;     ...
; #pragma unroll
;       for (int qq = 0; qq < 2; ++qq)
; #pragma unroll
;         for (int e = 0; e < 4; ++e) {
;           const int i = 4 * (2 * (ps & 1) + qq) + e;
;           const float* xr = (const float*)(xs + (8 * qq + 4 * hh + e) * 512) + l31;
;           float s1 = 0.f, s2 = 0.f;
; #pragma unroll
;           for (int nt = 0; nt < 4; ++nt) {
;             float v = (acc[mt][nt][i] + bia[nt]) * csc[nt];
;             float z = ALPHA * xr[nt * 32] + hs * v;
;             acc[mt][nt][i] = z; s1 += z; s2 += z * z;
;           }
;           s1 = row16_sum(s1); s2 = row16_sum(s2);
;           if ((lane & 15) == 0) { f32x2 sv = {s1, s2}; *(f32x2*)(redw + (mt * 32 + (i & 3) + 8 * (i >> 2)) * 2) = sv; }
	v_add_u32_e32 v73, v105, v154
	ds_read2_b32 v[134:135], v73 offset1:32
	ds_read2_b32 v[138:139], v73 offset0:64 offset1:96
	v_mov_b32_e32 v136, v122
	v_mov_b32_e32 v137, v90
	v_pk_add_f32 v[140:141], v[136:137], 0 op_sel_hi:[1,0]
	v_mov_b32_e32 v136, v106
	v_pk_add_f32 v[136:137], v[136:137], 0 op_sel_hi:[1,0]
	s_waitcnt lgkmcnt(0)
	v_mov_b32_e32 v142, v134
	v_mov_b32_e32 v143, v138
	s_mov_b32 s2, s67
	v_mov_b32_e32 v148, v135
	v_mov_b32_e32 v149, v138
	v_pk_fma_f32 v[134:135], v[142:143], s[2:3], v[140:141] op_sel_hi:[1,0,1]
	v_pk_fma_f32 v[136:137], v[148:149], s[2:3], v[136:137] op_sel_hi:[1,0,1]
	v_pk_mul_f32 v[144:145], v[142:143], s[2:3] op_sel_hi:[1,0]
	v_pk_mul_f32 v[142:143], v[134:135], v[134:135]
	v_pk_mul_f32 v[148:149], v[136:137], v[136:137]
	v_pk_mov_b32 v[140:141], v[140:141], v[142:143] op_sel:[1,0]
	v_pk_mov_b32 v[142:143], v[144:145], v[148:149] op_sel:[1,0]
	v_add_f32_e32 v120, 0, v74
	v_pk_add_f32 v[140:141], v[140:141], v[142:143]
	v_pk_add_f32 v[142:143], v[134:135], v[136:137]
	v_pk_mul_f32 v[144:145], v[134:135], v[136:137]
	v_fmac_f32_e32 v120, 0x3fd744fd, v139
	v_mov_b32_e32 v143, v145
	v_pk_add_f32 v[140:141], v[142:143], v[140:141]
	v_mul_f32_e32 v121, v120, v120
	v_pk_add_f32 v[138:139], v[140:141], v[120:121]
	s_nop 1
	v_mov_b32_dpp v140, v138 quad_perm:[1,0,3,2] row_mask:0xf bank_mask:0xf bound_ctrl:1
	v_mov_b32_dpp v141, v139 quad_perm:[1,0,3,2] row_mask:0xf bank_mask:0xf bound_ctrl:1
	v_pk_add_f32 v[138:139], v[138:139], v[140:141]
	s_nop 1
	v_mov_b32_dpp v140, v138 quad_perm:[2,3,0,1] row_mask:0xf bank_mask:0xf bound_ctrl:1
	v_mov_b32_dpp v141, v139 quad_perm:[2,3,0,1] row_mask:0xf bank_mask:0xf bound_ctrl:1
	v_pk_add_f32 v[138:139], v[138:139], v[140:141]
	s_nop 1
	v_mov_b32_dpp v140, v138 row_half_mirror row_mask:0xf bank_mask:0xf bound_ctrl:1
	v_mov_b32_dpp v141, v139 row_half_mirror row_mask:0xf bank_mask:0xf bound_ctrl:1
	v_pk_add_f32 v[138:139], v[138:139], v[140:141]
	s_nop 1
	v_mov_b32_dpp v140, v138 row_mirror row_mask:0xf bank_mask:0xf bound_ctrl:1
	v_mov_b32_dpp v141, v139 row_mirror row_mask:0xf bank_mask:0xf bound_ctrl:1
	s_and_saveexec_b64 s[6:7], vcc
	v_pk_add_f32 v[138:139], v[138:139], v[140:141]
	ds_write_b64 v179, v[138:139] offset:128
	s_or_b64 exec, exec, s[6:7]
	v_or_b32_e32 v74, 0x200, v154
	v_add_u32_e32 v85, v105, v74
	ds_read2_b32 v[138:139], v85 offset1:32
	ds_read2_b32 v[140:141], v85 offset0:64 offset1:96
	v_mov_b32_e32 v90, v123
	v_pk_add_f32 v[142:143], v[90:91], 0 op_sel_hi:[1,0]
	v_mov_b32_e32 v90, v107
	v_pk_add_f32 v[90:91], v[90:91], 0 op_sel_hi:[1,0]
	s_waitcnt lgkmcnt(1)
	v_mov_b32_e32 v106, v138
	s_waitcnt lgkmcnt(0)
	v_mov_b32_e32 v107, v140
	s_mov_b32 s2, s67
	v_mov_b32_e32 v122, v139
	v_mov_b32_e32 v123, v140
	v_pk_mul_f32 v[144:145], v[106:107], s[2:3] op_sel_hi:[1,0]
	v_pk_fma_f32 v[106:107], v[106:107], s[2:3], v[142:143] op_sel_hi:[1,0,1]
	v_pk_fma_f32 v[122:123], v[122:123], s[2:3], v[90:91] op_sel_hi:[1,0,1]
	v_pk_mul_f32 v[138:139], v[106:107], v[106:107]
	v_pk_mul_f32 v[90:91], v[122:123], v[122:123]
	v_pk_mov_b32 v[138:139], v[142:143], v[138:139] op_sel:[1,0]
	v_pk_mov_b32 v[90:91], v[144:145], v[90:91] op_sel:[1,0]
	v_add_f32_e32 v74, 0, v75
	v_pk_add_f32 v[90:91], v[138:139], v[90:91]
	v_pk_add_f32 v[138:139], v[106:107], v[122:123]
	v_pk_mul_f32 v[142:143], v[106:107], v[122:123]
	v_fmac_f32_e32 v74, 0x3fd744fd, v141
	v_mov_b32_e32 v139, v143
	v_pk_add_f32 v[90:91], v[138:139], v[90:91]
	v_mul_f32_e32 v75, v74, v74
	v_pk_add_f32 v[90:91], v[90:91], v[74:75]
	s_nop 1
	v_mov_b32_dpp v138, v90 quad_perm:[1,0,3,2] row_mask:0xf bank_mask:0xf bound_ctrl:1
	v_mov_b32_dpp v139, v91 quad_perm:[1,0,3,2] row_mask:0xf bank_mask:0xf bound_ctrl:1
	v_pk_add_f32 v[90:91], v[90:91], v[138:139]
	s_nop 1
	v_mov_b32_dpp v138, v90 quad_perm:[2,3,0,1] row_mask:0xf bank_mask:0xf bound_ctrl:1
	v_mov_b32_dpp v139, v91 quad_perm:[2,3,0,1] row_mask:0xf bank_mask:0xf bound_ctrl:1
	v_pk_add_f32 v[90:91], v[90:91], v[138:139]
	s_nop 1
	v_mov_b32_dpp v138, v90 row_half_mirror row_mask:0xf bank_mask:0xf bound_ctrl:1
	v_mov_b32_dpp v139, v91 row_half_mirror row_mask:0xf bank_mask:0xf bound_ctrl:1
	v_pk_add_f32 v[90:91], v[90:91], v[138:139]
	s_nop 1
	v_mov_b32_dpp v138, v90 row_mirror row_mask:0xf bank_mask:0xf bound_ctrl:1
	v_mov_b32_dpp v139, v91 row_mirror row_mask:0xf bank_mask:0xf bound_ctrl:1
	s_and_saveexec_b64 s[6:7], vcc
	v_pk_add_f32 v[90:91], v[90:91], v[138:139]
	ds_write_b64 v179, v[90:91] offset:136
	s_or_b64 exec, exec, s[6:7]
	v_or_b32_e32 v75, 0x400, v154
	v_add_u32_e32 v75, v105, v75
	ds_read2_b32 v[138:139], v75 offset1:32
	ds_read2_b32 v[142:143], v75 offset0:64 offset1:96
	v_mov_b32_e32 v140, v124
	v_mov_b32_e32 v141, v92
	v_pk_add_f32 v[144:145], v[140:141], 0 op_sel_hi:[1,0]
	v_mov_b32_e32 v140, v108
	v_pk_add_f32 v[140:141], v[140:141], 0 op_sel_hi:[1,0]
	s_waitcnt lgkmcnt(1)
	v_mov_b32_e32 v148, v138
	s_waitcnt lgkmcnt(0)
;   DI void operator()(f32x16 (&acc)[2][4], int grow0, int gcol0, int lane, int w, char* lds) {
;     ...
; #pragma unroll
;       for (int qq = 0; qq < 2; ++qq)
; #pragma unroll
;         for (int e = 0; e < 4; ++e) {
;           const int i = 4 * (2 * (ps & 1) + qq) + e;
;           const float* xr = (const float*)(xs + (8 * qq + 4 * hh + e) * 512) + l31;
;           float s1 = 0.f, s2 = 0.f;
; #pragma unroll
;           for (int nt = 0; nt < 4; ++nt) {
;             float v = (acc[mt][nt][i] + bia[nt]) * csc[nt];
;             float z = ALPHA * xr[nt * 32] + hs * v;
;             acc[mt][nt][i] = z; s1 += z; s2 += z * z;
;           }
;           s1 = row16_sum(s1); s2 = row16_sum(s2);
;           if ((lane & 15) == 0) { f32x2 sv = {s1, s2}; *(f32x2*)(redw + (mt * 32 + (i & 3) + 8 * (i >> 2)) * 2) = sv; }
	v_mov_b32_e32 v149, v142
	s_mov_b32 s2, s67
	v_mov_b32_e32 v160, v139
	v_mov_b32_e32 v161, v142
	v_pk_fma_f32 v[138:139], v[148:149], s[2:3], v[144:145] op_sel_hi:[1,0,1]
	v_pk_fma_f32 v[140:141], v[160:161], s[2:3], v[140:141] op_sel_hi:[1,0,1]
	v_pk_mul_f32 v[156:157], v[148:149], s[2:3] op_sel_hi:[1,0]
	v_pk_mul_f32 v[148:149], v[138:139], v[138:139]
	v_pk_mul_f32 v[160:161], v[140:141], v[140:141]
	v_pk_mov_b32 v[144:145], v[144:145], v[148:149] op_sel:[1,0]
	v_pk_mov_b32 v[148:149], v[156:157], v[160:161] op_sel:[1,0]
	v_add_f32_e32 v90, 0, v76
	v_pk_add_f32 v[144:145], v[144:145], v[148:149]
	v_pk_add_f32 v[148:149], v[138:139], v[140:141]
	v_pk_mul_f32 v[156:157], v[138:139], v[140:141]
	v_fmac_f32_e32 v90, 0x3fd744fd, v143
	v_mov_b32_e32 v149, v157
	v_pk_add_f32 v[144:145], v[148:149], v[144:145]
	v_mul_f32_e32 v91, v90, v90
	v_pk_add_f32 v[142:143], v[144:145], v[90:91]
	s_nop 1
	v_mov_b32_dpp v144, v142 quad_perm:[1,0,3,2] row_mask:0xf bank_mask:0xf bound_ctrl:1
	v_mov_b32_dpp v145, v143 quad_perm:[1,0,3,2] row_mask:0xf bank_mask:0xf bound_ctrl:1
	v_pk_add_f32 v[142:143], v[142:143], v[144:145]
	s_nop 1
	v_mov_b32_dpp v144, v142 quad_perm:[2,3,0,1] row_mask:0xf bank_mask:0xf bound_ctrl:1
	v_mov_b32_dpp v145, v143 quad_perm:[2,3,0,1] row_mask:0xf bank_mask:0xf bound_ctrl:1
	v_pk_add_f32 v[142:143], v[142:143], v[144:145]
	s_nop 1
	v_mov_b32_dpp v144, v142 row_half_mirror row_mask:0xf bank_mask:0xf bound_ctrl:1
	v_mov_b32_dpp v145, v143 row_half_mirror row_mask:0xf bank_mask:0xf bound_ctrl:1
	v_pk_add_f32 v[142:143], v[142:143], v[144:145]
	s_nop 1
	v_mov_b32_dpp v144, v142 row_mirror row_mask:0xf bank_mask:0xf bound_ctrl:1
	v_mov_b32_dpp v145, v143 row_mirror row_mask:0xf bank_mask:0xf bound_ctrl:1
	s_and_saveexec_b64 s[6:7], vcc
	v_pk_add_f32 v[142:143], v[142:143], v[144:145]
	ds_write_b64 v179, v[142:143] offset:144
	s_or_b64 exec, exec, s[6:7]
	v_add_u32_e32 v87, v105, v146
	ds_read2_b32 v[142:143], v87 offset1:32
	ds_read2_b32 v[144:145], v87 offset0:64 offset1:96
	v_mov_b32_e32 v92, v125
	v_pk_add_f32 v[146:147], v[92:93], 0 op_sel_hi:[1,0]
	v_mov_b32_e32 v92, v109
	v_pk_add_f32 v[92:93], v[92:93], 0 op_sel_hi:[1,0]
	s_waitcnt lgkmcnt(1)
	v_mov_b32_e32 v108, v142
	s_waitcnt lgkmcnt(0)
	v_mov_b32_e32 v109, v144
	s_mov_b32 s2, s67
	v_mov_b32_e32 v124, v143
	v_mov_b32_e32 v125, v144
	v_pk_mul_f32 v[148:149], v[108:109], s[2:3] op_sel_hi:[1,0]
	v_pk_fma_f32 v[108:109], v[108:109], s[2:3], v[146:147] op_sel_hi:[1,0,1]
	v_pk_fma_f32 v[124:125], v[124:125], s[2:3], v[92:93] op_sel_hi:[1,0,1]
	v_pk_mul_f32 v[142:143], v[108:109], v[108:109]
	v_pk_mul_f32 v[92:93], v[124:125], v[124:125]
	v_pk_mov_b32 v[142:143], v[146:147], v[142:143] op_sel:[1,0]
	v_pk_mov_b32 v[92:93], v[148:149], v[92:93] op_sel:[1,0]
	v_add_f32_e32 v76, 0, v77
	v_pk_add_f32 v[92:93], v[142:143], v[92:93]
	v_pk_add_f32 v[142:143], v[108:109], v[124:125]
	v_pk_mul_f32 v[146:147], v[108:109], v[124:125]
	v_fmac_f32_e32 v76, 0x3fd744fd, v145
	v_mov_b32_e32 v143, v147
	v_pk_add_f32 v[92:93], v[142:143], v[92:93]
	v_mul_f32_e32 v77, v76, v76
	v_pk_add_f32 v[92:93], v[92:93], v[76:77]
	s_nop 1
	v_mov_b32_dpp v142, v92 quad_perm:[1,0,3,2] row_mask:0xf bank_mask:0xf bound_ctrl:1
	v_mov_b32_dpp v143, v93 quad_perm:[1,0,3,2] row_mask:0xf bank_mask:0xf bound_ctrl:1
	v_pk_add_f32 v[92:93], v[92:93], v[142:143]
	s_nop 1
	v_mov_b32_dpp v142, v92 quad_perm:[2,3,0,1] row_mask:0xf bank_mask:0xf bound_ctrl:1
	v_mov_b32_dpp v143, v93 quad_perm:[2,3,0,1] row_mask:0xf bank_mask:0xf bound_ctrl:1
	v_pk_add_f32 v[92:93], v[92:93], v[142:143]
	s_nop 1
	v_mov_b32_dpp v142, v92 row_half_mirror row_mask:0xf bank_mask:0xf bound_ctrl:1
	v_mov_b32_dpp v143, v93 row_half_mirror row_mask:0xf bank_mask:0xf bound_ctrl:1
	v_pk_add_f32 v[92:93], v[92:93], v[142:143]
	s_nop 1
	v_mov_b32_dpp v142, v92 row_mirror row_mask:0xf bank_mask:0xf bound_ctrl:1
	v_mov_b32_dpp v143, v93 row_mirror row_mask:0xf bank_mask:0xf bound_ctrl:1
	s_and_saveexec_b64 s[6:7], vcc
	v_pk_add_f32 v[92:93], v[92:93], v[142:143]
	ds_write_b64 v179, v[92:93] offset:152
	s_or_b64 exec, exec, s[6:7]
	v_or_b32_e32 v77, 0x1000, v154
	v_add_u32_e32 v77, v105, v77
	ds_read2_b32 v[142:143], v77 offset1:32
	ds_read2_b32 v[146:147], v77 offset0:64 offset1:96
	v_mov_b32_e32 v144, v126
	v_mov_b32_e32 v145, v94
	v_pk_add_f32 v[148:149], v[144:145], 0 op_sel_hi:[1,0]
	v_mov_b32_e32 v144, v110
	v_pk_add_f32 v[144:145], v[144:145], 0 op_sel_hi:[1,0]
	s_waitcnt lgkmcnt(1)
	v_mov_b32_e32 v156, v142
	s_waitcnt lgkmcnt(0)
	v_mov_b32_e32 v157, v146
	s_mov_b32 s2, s67
	v_mov_b32_e32 v170, v143
	v_mov_b32_e32 v171, v146
	v_pk_fma_f32 v[142:143], v[156:157], s[2:3], v[148:149] op_sel_hi:[1,0,1]
	v_pk_fma_f32 v[144:145], v[170:171], s[2:3], v[144:145] op_sel_hi:[1,0,1]
	v_pk_mul_f32 v[160:161], v[156:157], s[2:3] op_sel_hi:[1,0]
	v_pk_mul_f32 v[156:157], v[142:143], v[142:143]
	v_pk_mul_f32 v[170:171], v[144:145], v[144:145]
	v_pk_mov_b32 v[148:149], v[148:149], v[156:157] op_sel:[1,0]
	v_pk_mov_b32 v[156:157], v[160:161], v[170:171] op_sel:[1,0]
	v_add_f32_e32 v92, 0, v78
	v_pk_add_f32 v[148:149], v[148:149], v[156:157]
	v_pk_add_f32 v[156:157], v[142:143], v[144:145]
	v_pk_mul_f32 v[160:161], v[142:143], v[144:145]
	v_fmac_f32_e32 v92, 0x3fd744fd, v147
	v_mov_b32_e32 v157, v161
	v_pk_add_f32 v[148:149], v[156:157], v[148:149]
	v_mul_f32_e32 v93, v92, v92
	v_pk_add_f32 v[146:147], v[148:149], v[92:93]
	s_nop 1
	v_mov_b32_dpp v148, v146 quad_perm:[1,0,3,2] row_mask:0xf bank_mask:0xf bound_ctrl:1
	v_mov_b32_dpp v149, v147 quad_perm:[1,0,3,2] row_mask:0xf bank_mask:0xf bound_ctrl:1
	v_pk_add_f32 v[146:147], v[146:147], v[148:149]
	s_nop 1
	v_mov_b32_dpp v148, v146 quad_perm:[2,3,0,1] row_mask:0xf bank_mask:0xf bound_ctrl:1
	v_mov_b32_dpp v149, v147 quad_perm:[2,3,0,1] row_mask:0xf bank_mask:0xf bound_ctrl:1
	v_pk_add_f32 v[146:147], v[146:147], v[148:149]
	s_nop 1
	v_mov_b32_dpp v148, v146 row_half_mirror row_mask:0xf bank_mask:0xf bound_ctrl:1
	v_mov_b32_dpp v149, v147 row_half_mirror row_mask:0xf bank_mask:0xf bound_ctrl:1
	v_pk_add_f32 v[146:147], v[146:147], v[148:149]
	s_nop 1
	v_mov_b32_dpp v148, v146 row_mirror row_mask:0xf bank_mask:0xf bound_ctrl:1
	v_mov_b32_dpp v149, v147 row_mirror row_mask:0xf bank_mask:0xf bound_ctrl:1
	s_and_saveexec_b64 s[6:7], vcc
	v_pk_add_f32 v[146:147], v[146:147], v[148:149]
	ds_write_b64 v179, v[146:147] offset:192
	s_or_b64 exec, exec, s[6:7]
	v_or_b32_e32 v78, 0x1200, v154
	v_add_u32_e32 v91, v105, v78
	ds_read2_b32 v[146:147], v91 offset1:32
	ds_read2_b32 v[148:149], v91 offset0:64 offset1:96
	v_mov_b32_e32 v94, v127
	v_pk_add_f32 v[156:157], v[94:95], 0 op_sel_hi:[1,0]
	v_mov_b32_e32 v94, v111
	v_pk_add_f32 v[94:95], v[94:95], 0 op_sel_hi:[1,0]
	s_waitcnt lgkmcnt(1)
;   DI void operator()(f32x16 (&acc)[2][4], int grow0, int gcol0, int lane, int w, char* lds) {
;     ...
;     for (int ps = 0; ps < 4; ++ps) {
;       const int mt = ps >> 1;
;       if (ps + 1 < 4) {
;         if (ps >= 1) asm volatile("s_waitcnt lgkmcnt(0)" ::: "memory");
;         xpass(ps + 1, grow0, gcol0, lane, w, lds);
;         if (ps >= 1) asm volatile("s_waitcnt vmcnt(8)" ::: "memory");
;       } else asm volatile("s_waitcnt vmcnt(0)" ::: "memory");
;       const char* xs = lds + (ps & 1) * 65536 + w * 8192;
; #pragma unroll
;       for (int qq = 0; qq < 2; ++qq)
; #pragma unroll
;         for (int e = 0; e < 4; ++e) {
;           const int i = 4 * (2 * (ps & 1) + qq) + e;
;           const float* xr = (const float*)(xs + (8 * qq + 4 * hh + e) * 512) + l31;
;           float s1 = 0.f, s2 = 0.f;
; #pragma unroll
;           for (int nt = 0; nt < 4; ++nt) {
;             float v = (acc[mt][nt][i] + bia[nt]) * csc[nt];
;             float z = ALPHA * xr[nt * 32] + hs * v;
;             acc[mt][nt][i] = z; s1 += z; s2 += z * z;
;           }
;           s1 = row16_sum(s1); s2 = row16_sum(s2);
;           if ((lane & 15) == 0) { f32x2 sv = {s1, s2}; *(f32x2*)(redw + (mt * 32 + (i & 3) + 8 * (i >> 2)) * 2) = sv; }
	v_mov_b32_e32 v110, v146
	s_waitcnt lgkmcnt(0)
	v_mov_b32_e32 v111, v148
	s_mov_b32 s2, s67
	v_mov_b32_e32 v126, v147
	v_mov_b32_e32 v127, v148
	v_pk_mul_f32 v[160:161], v[110:111], s[2:3] op_sel_hi:[1,0]
	v_pk_fma_f32 v[110:111], v[110:111], s[2:3], v[156:157] op_sel_hi:[1,0,1]
	v_pk_fma_f32 v[126:127], v[126:127], s[2:3], v[94:95] op_sel_hi:[1,0,1]
	v_pk_mul_f32 v[146:147], v[110:111], v[110:111]
	v_pk_mul_f32 v[94:95], v[126:127], v[126:127]
	v_pk_mov_b32 v[146:147], v[156:157], v[146:147] op_sel:[1,0]
	v_pk_mov_b32 v[94:95], v[160:161], v[94:95] op_sel:[1,0]
	v_add_f32_e32 v78, 0, v79
	v_pk_add_f32 v[94:95], v[146:147], v[94:95]
	v_pk_add_f32 v[146:147], v[110:111], v[126:127]
	v_pk_mul_f32 v[156:157], v[110:111], v[126:127]
	v_fmac_f32_e32 v78, 0x3fd744fd, v149
	v_mov_b32_e32 v147, v157
	v_pk_add_f32 v[94:95], v[146:147], v[94:95]
	v_mul_f32_e32 v79, v78, v78
	v_pk_add_f32 v[94:95], v[94:95], v[78:79]
	s_nop 1
	v_mov_b32_dpp v146, v94 quad_perm:[1,0,3,2] row_mask:0xf bank_mask:0xf bound_ctrl:1
	v_mov_b32_dpp v147, v95 quad_perm:[1,0,3,2] row_mask:0xf bank_mask:0xf bound_ctrl:1
	v_pk_add_f32 v[94:95], v[94:95], v[146:147]
	s_nop 1
	v_mov_b32_dpp v146, v94 quad_perm:[2,3,0,1] row_mask:0xf bank_mask:0xf bound_ctrl:1
	v_mov_b32_dpp v147, v95 quad_perm:[2,3,0,1] row_mask:0xf bank_mask:0xf bound_ctrl:1
	v_pk_add_f32 v[94:95], v[94:95], v[146:147]
	s_nop 1
	v_mov_b32_dpp v146, v94 row_half_mirror row_mask:0xf bank_mask:0xf bound_ctrl:1
	v_mov_b32_dpp v147, v95 row_half_mirror row_mask:0xf bank_mask:0xf bound_ctrl:1
	v_pk_add_f32 v[94:95], v[94:95], v[146:147]
	s_nop 1
	v_mov_b32_dpp v146, v94 row_mirror row_mask:0xf bank_mask:0xf bound_ctrl:1
	v_mov_b32_dpp v147, v95 row_mirror row_mask:0xf bank_mask:0xf bound_ctrl:1
	s_and_saveexec_b64 s[6:7], vcc
	v_pk_add_f32 v[94:95], v[94:95], v[146:147]
	ds_write_b64 v179, v[94:95] offset:200
	s_or_b64 exec, exec, s[6:7]
	v_or_b32_e32 v79, 0x1400, v154
	v_add_u32_e32 v79, v105, v79
	ds_read2_b32 v[146:147], v79 offset1:32
	ds_read2_b32 v[154:155], v79 offset0:64 offset1:96
	v_mov_b32_e32 v148, v128
	v_mov_b32_e32 v149, v96
	v_pk_add_f32 v[156:157], v[148:149], 0 op_sel_hi:[1,0]
	v_mov_b32_e32 v148, v112
	v_pk_add_f32 v[148:149], v[148:149], 0 op_sel_hi:[1,0]
	s_waitcnt lgkmcnt(1)
	v_mov_b32_e32 v160, v146
	s_waitcnt lgkmcnt(0)
	v_mov_b32_e32 v161, v154
	s_mov_b32 s2, s67
	v_mov_b32_e32 v174, v147
	v_mov_b32_e32 v175, v154
	v_pk_fma_f32 v[146:147], v[160:161], s[2:3], v[156:157] op_sel_hi:[1,0,1]
	v_pk_fma_f32 v[148:149], v[174:175], s[2:3], v[148:149] op_sel_hi:[1,0,1]
	v_pk_mul_f32 v[170:171], v[160:161], s[2:3] op_sel_hi:[1,0]
	v_pk_mul_f32 v[160:161], v[146:147], v[146:147]
	v_pk_mul_f32 v[174:175], v[148:149], v[148:149]
	v_pk_mov_b32 v[156:157], v[156:157], v[160:161] op_sel:[1,0]
	v_pk_mov_b32 v[160:161], v[170:171], v[174:175] op_sel:[1,0]
	v_add_f32_e32 v94, 0, v80
	v_pk_add_f32 v[156:157], v[156:157], v[160:161]
	v_pk_add_f32 v[160:161], v[146:147], v[148:149]
	v_pk_mul_f32 v[170:171], v[146:147], v[148:149]
	v_fmac_f32_e32 v94, 0x3fd744fd, v155
	v_mov_b32_e32 v161, v171
	v_pk_add_f32 v[156:157], v[160:161], v[156:157]
	v_mul_f32_e32 v95, v94, v94
	v_pk_add_f32 v[154:155], v[156:157], v[94:95]
	s_nop 1
	v_mov_b32_dpp v156, v154 quad_perm:[1,0,3,2] row_mask:0xf bank_mask:0xf bound_ctrl:1
	v_mov_b32_dpp v157, v155 quad_perm:[1,0,3,2] row_mask:0xf bank_mask:0xf bound_ctrl:1
	v_pk_add_f32 v[154:155], v[154:155], v[156:157]
	s_nop 1
	v_mov_b32_dpp v156, v154 quad_perm:[2,3,0,1] row_mask:0xf bank_mask:0xf bound_ctrl:1
	v_mov_b32_dpp v157, v155 quad_perm:[2,3,0,1] row_mask:0xf bank_mask:0xf bound_ctrl:1
	v_pk_add_f32 v[154:155], v[154:155], v[156:157]
	s_nop 1
	v_mov_b32_dpp v156, v154 row_half_mirror row_mask:0xf bank_mask:0xf bound_ctrl:1
	v_mov_b32_dpp v157, v155 row_half_mirror row_mask:0xf bank_mask:0xf bound_ctrl:1
	v_pk_add_f32 v[154:155], v[154:155], v[156:157]
	s_nop 1
	v_mov_b32_dpp v156, v154 row_mirror row_mask:0xf bank_mask:0xf bound_ctrl:1
	v_mov_b32_dpp v157, v155 row_mirror row_mask:0xf bank_mask:0xf bound_ctrl:1
	s_and_saveexec_b64 s[6:7], vcc
	v_pk_add_f32 v[154:155], v[154:155], v[156:157]
	ds_write_b64 v179, v[154:155] offset:208
	s_or_b64 exec, exec, s[6:7]
	v_add_u32_e32 v93, v105, v101
	ds_read2_b32 v[154:155], v93 offset1:32
	ds_read2_b32 v[156:157], v93 offset0:64 offset1:96
	v_mov_b32_e32 v96, v129
	v_pk_add_f32 v[128:129], v[96:97], 0 op_sel_hi:[1,0]
	v_mov_b32_e32 v96, v113
	v_pk_add_f32 v[112:113], v[96:97], 0 op_sel_hi:[1,0]
	s_waitcnt lgkmcnt(1)
	v_mov_b32_e32 v96, v154
	s_waitcnt lgkmcnt(0)
	v_mov_b32_e32 v97, v156
	s_mov_b32 s2, s67
	v_mov_b32_e32 v154, v155
	v_mov_b32_e32 v155, v156
	v_pk_mul_f32 v[160:161], v[96:97], s[2:3] op_sel_hi:[1,0]
	v_pk_fma_f32 v[96:97], v[96:97], s[2:3], v[128:129] op_sel_hi:[1,0,1]
	v_pk_fma_f32 v[112:113], v[154:155], s[2:3], v[112:113] op_sel_hi:[1,0,1]
	v_pk_mul_f32 v[170:171], v[96:97], v[96:97]
	v_pk_mul_f32 v[154:155], v[112:113], v[112:113]
	v_pk_mov_b32 v[128:129], v[128:129], v[170:171] op_sel:[1,0]
	v_pk_mov_b32 v[154:155], v[160:161], v[154:155] op_sel:[1,0]
	v_add_f32_e32 v80, 0, v81
	v_pk_add_f32 v[128:129], v[128:129], v[154:155]
	v_pk_add_f32 v[154:155], v[96:97], v[112:113]
	v_pk_mul_f32 v[160:161], v[96:97], v[112:113]
	v_fmac_f32_e32 v80, 0x3fd744fd, v157
	v_mov_b32_e32 v155, v161
	v_pk_add_f32 v[128:129], v[154:155], v[128:129]
	v_mul_f32_e32 v81, v80, v80
	v_pk_add_f32 v[128:129], v[128:129], v[80:81]
	s_nop 1
	v_mov_b32_dpp v154, v128 quad_perm:[1,0,3,2] row_mask:0xf bank_mask:0xf bound_ctrl:1
	v_mov_b32_dpp v155, v129 quad_perm:[1,0,3,2] row_mask:0xf bank_mask:0xf bound_ctrl:1
	v_pk_add_f32 v[128:129], v[128:129], v[154:155]
	s_nop 1
	v_mov_b32_dpp v154, v128 quad_perm:[2,3,0,1] row_mask:0xf bank_mask:0xf bound_ctrl:1
	v_mov_b32_dpp v155, v129 quad_perm:[2,3,0,1] row_mask:0xf bank_mask:0xf bound_ctrl:1
	v_pk_add_f32 v[128:129], v[128:129], v[154:155]
	s_nop 1
	v_mov_b32_dpp v154, v128 row_half_mirror row_mask:0xf bank_mask:0xf bound_ctrl:1
	v_mov_b32_dpp v155, v129 row_half_mirror row_mask:0xf bank_mask:0xf bound_ctrl:1
	v_pk_add_f32 v[128:129], v[128:129], v[154:155]
	s_nop 1
	v_mov_b32_dpp v154, v128 row_mirror row_mask:0xf bank_mask:0xf bound_ctrl:1
	v_mov_b32_dpp v155, v129 row_mirror row_mask:0xf bank_mask:0xf bound_ctrl:1
	s_and_saveexec_b64 s[6:7], vcc
	v_pk_add_f32 v[128:129], v[128:129], v[154:155]
	ds_write_b64 v179, v[128:129] offset:216
	s_or_b64 exec, exec, s[6:7]
	v_or_b32_e32 v128, 48, v159
	v_ashrrev_i32_e32 v129, 31, v128
	v_lshlrev_b64 v[128:129], 12, v[128:129]
	v_readfirstlane_b32 s2, v158
	v_lshl_add_u64 v[128:129], s[10:11], 0, v[128:129]
	s_lshl_b32 s2, s2, 13
	v_lshl_add_u64 v[128:129], v[182:183], 2, v[128:129]
	s_waitcnt lgkmcnt(0)
;   DI void operator()(f32x16 (&acc)[2][4], int grow0, int gcol0, int lane, int w, char* lds) {
;     ...
;     for (int ps = 0; ps < 4; ++ps) {
;       const int mt = ps >> 1;
;       if (ps + 1 < 4) {
;         if (ps >= 1) asm volatile("s_waitcnt lgkmcnt(0)" ::: "memory");
;         xpass(ps + 1, grow0, gcol0, lane, w, lds);
;         if (ps >= 1) asm volatile("s_waitcnt vmcnt(8)" ::: "memory");
;       } else asm volatile("s_waitcnt vmcnt(0)" ::: "memory");
;       const char* xs = lds + (ps & 1) * 65536 + w * 8192;
; #pragma unroll
;       for (int qq = 0; qq < 2; ++qq)
; #pragma unroll
;         for (int e = 0; e < 4; ++e) {
;           const int i = 4 * (2 * (ps & 1) + qq) + e;
;           const float* xr = (const float*)(xs + (8 * qq + 4 * hh + e) * 512) + l31;
;           float s1 = 0.f, s2 = 0.f;
; #pragma unroll
;           for (int nt = 0; nt < 4; ++nt) {
;             float v = (acc[mt][nt][i] + bia[nt]) * csc[nt];
;             float z = ALPHA * xr[nt * 32] + hs * v;
;             acc[mt][nt][i] = z; s1 += z; s2 += z * z;
;           }
;           s1 = row16_sum(s1); s2 = row16_sum(s2);
;           if ((lane & 15) == 0) { f32x2 sv = {s1, s2}; *(f32x2*)(redw + (mt * 32 + (i & 3) + 8 * (i >> 2)) * 2) = sv; }
	s_add_i32 m0, s2, 0x10000
	v_lshl_add_u64 v[128:129], v[128:129], 0, v[0:1]
	s_mov_b64 s[6:7], 0x2000
	global_load_lds_dwordx4 v[128:129], off
	v_lshl_add_u64 v[154:155], v[128:129], 0, s[6:7]
	s_add_i32 m0, s2, 0x10400
	s_mov_b64 s[6:7], 0x4000
	global_load_lds_dwordx4 v[154:155], off
	v_lshl_add_u64 v[154:155], v[128:129], 0, s[6:7]
	s_add_i32 m0, s2, 0x10800
	s_mov_b64 s[6:7], 0x6000
	global_load_lds_dwordx4 v[154:155], off
	v_lshl_add_u64 v[154:155], v[128:129], 0, s[6:7]
	s_add_i32 m0, s2, 0x10c00
	s_mov_b64 s[6:7], 0x8000
	global_load_lds_dwordx4 v[154:155], off
	v_lshl_add_u64 v[154:155], v[128:129], 0, s[6:7]
	s_add_i32 m0, s2, 0x11000
	s_mov_b64 s[6:7], 0xa000
	global_load_lds_dwordx4 v[154:155], off
	v_lshl_add_u64 v[154:155], v[128:129], 0, s[6:7]
	s_add_i32 m0, s2, 0x11400
	s_mov_b64 s[6:7], 0xc000
	global_load_lds_dwordx4 v[154:155], off
	v_lshl_add_u64 v[154:155], v[128:129], 0, s[6:7]
	s_add_i32 m0, s2, 0x11800
	s_mov_b64 s[6:7], 0xe000
	global_load_lds_dwordx4 v[154:155], off
	v_lshl_add_u64 v[128:129], v[128:129], 0, s[6:7]
	s_add_i32 m0, s2, 0x11c00
	v_mov_b32_e32 v156, v50
	global_load_lds_dwordx4 v[128:129], off
	s_waitcnt vmcnt(8)
	ds_read2_b32 v[154:155], v168 offset1:32
	ds_read2_b32 v[158:159], v168 offset0:64 offset1:96
	v_mov_b32_e32 v157, v18
	v_pk_add_f32 v[160:161], v[156:157], 0 op_sel_hi:[1,0]
	v_mov_b32_e32 v156, v34
	v_pk_add_f32 v[156:157], v[156:157], 0 op_sel_hi:[1,0]
	s_waitcnt lgkmcnt(0)
	v_mov_b32_e32 v170, v154
	v_mov_b32_e32 v171, v158
	s_mov_b32 s2, s67
	v_mov_b32_e32 v176, v155
	v_mov_b32_e32 v177, v158
	v_pk_fma_f32 v[154:155], v[170:171], s[2:3], v[160:161] op_sel_hi:[1,0,1]
	v_pk_fma_f32 v[156:157], v[176:177], s[2:3], v[156:157] op_sel_hi:[1,0,1]
	v_pk_mul_f32 v[174:175], v[170:171], s[2:3] op_sel_hi:[1,0]
	v_pk_mul_f32 v[170:171], v[154:155], v[154:155]
	v_pk_mul_f32 v[176:177], v[156:157], v[156:157]
	v_pk_mov_b32 v[160:161], v[160:161], v[170:171] op_sel:[1,0]
	v_pk_mov_b32 v[170:171], v[174:175], v[176:177] op_sel:[1,0]
	v_add_f32_e32 v128, 0, v2
	v_pk_add_f32 v[160:161], v[160:161], v[170:171]
	v_pk_add_f32 v[170:171], v[154:155], v[156:157]
	v_pk_mul_f32 v[174:175], v[154:155], v[156:157]
	v_fmac_f32_e32 v128, 0x3fd744fd, v159
	v_mov_b32_e32 v171, v175
	v_pk_add_f32 v[160:161], v[170:171], v[160:161]
	v_mul_f32_e32 v129, v128, v128
	v_pk_add_f32 v[158:159], v[160:161], v[128:129]
	s_nop 1
	v_mov_b32_dpp v160, v158 quad_perm:[1,0,3,2] row_mask:0xf bank_mask:0xf bound_ctrl:1
	v_mov_b32_dpp v161, v159 quad_perm:[1,0,3,2] row_mask:0xf bank_mask:0xf bound_ctrl:1
	v_pk_add_f32 v[158:159], v[158:159], v[160:161]
	s_nop 1
	v_mov_b32_dpp v160, v158 quad_perm:[2,3,0,1] row_mask:0xf bank_mask:0xf bound_ctrl:1
	v_mov_b32_dpp v161, v159 quad_perm:[2,3,0,1] row_mask:0xf bank_mask:0xf bound_ctrl:1
	v_pk_add_f32 v[158:159], v[158:159], v[160:161]
	s_nop 1
	v_mov_b32_dpp v160, v158 row_half_mirror row_mask:0xf bank_mask:0xf bound_ctrl:1
	v_mov_b32_dpp v161, v159 row_half_mirror row_mask:0xf bank_mask:0xf bound_ctrl:1
	v_pk_add_f32 v[158:159], v[158:159], v[160:161]
	s_nop 1
	v_mov_b32_dpp v160, v158 row_mirror row_mask:0xf bank_mask:0xf bound_ctrl:1
	v_mov_b32_dpp v161, v159 row_mirror row_mask:0xf bank_mask:0xf bound_ctrl:1
	s_and_saveexec_b64 s[6:7], vcc
	v_pk_add_f32 v[158:159], v[158:159], v[160:161]
	ds_write_b64 v179, v[158:159] offset:256
	s_or_b64 exec, exec, s[6:7]
	ds_read2_b32 v[158:159], v168 offset0:128 offset1:160
	ds_read2_b32 v[160:161], v168 offset0:192 offset1:224
	v_mov_b32_e32 v18, v51
	v_pk_add_f32 v[168:169], v[18:19], 0 op_sel_hi:[1,0]
	v_mov_b32_e32 v18, v35
	v_pk_add_f32 v[18:19], v[18:19], 0 op_sel_hi:[1,0]
	s_waitcnt lgkmcnt(1)
	v_mov_b32_e32 v34, v158
	s_waitcnt lgkmcnt(0)
	v_mov_b32_e32 v35, v160
	s_mov_b32 s2, s67
	v_mov_b32_e32 v50, v159
	v_mov_b32_e32 v51, v160
	v_pk_mul_f32 v[170:171], v[34:35], s[2:3] op_sel_hi:[1,0]
	v_pk_fma_f32 v[34:35], v[34:35], s[2:3], v[168:169] op_sel_hi:[1,0,1]
	v_pk_fma_f32 v[50:51], v[50:51], s[2:3], v[18:19] op_sel_hi:[1,0,1]
	v_pk_mul_f32 v[158:159], v[34:35], v[34:35]
	v_pk_mul_f32 v[18:19], v[50:51], v[50:51]
	v_pk_mov_b32 v[158:159], v[168:169], v[158:159] op_sel:[1,0]
	v_pk_mov_b32 v[18:19], v[170:171], v[18:19] op_sel:[1,0]
	v_add_f32_e32 v2, 0, v3
	v_pk_add_f32 v[18:19], v[158:159], v[18:19]
	v_pk_add_f32 v[158:159], v[34:35], v[50:51]
	v_pk_mul_f32 v[168:169], v[34:35], v[50:51]
	v_fmac_f32_e32 v2, 0x3fd744fd, v161
	v_mov_b32_e32 v159, v169
	v_pk_add_f32 v[18:19], v[158:159], v[18:19]
	v_mul_f32_e32 v3, v2, v2
	v_pk_add_f32 v[18:19], v[18:19], v[2:3]
	s_nop 1
	v_mov_b32_dpp v158, v18 quad_perm:[1,0,3,2] row_mask:0xf bank_mask:0xf bound_ctrl:1
	v_mov_b32_dpp v159, v19 quad_perm:[1,0,3,2] row_mask:0xf bank_mask:0xf bound_ctrl:1
	v_pk_add_f32 v[18:19], v[18:19], v[158:159]
	s_nop 1
	v_mov_b32_dpp v158, v18 quad_perm:[2,3,0,1] row_mask:0xf bank_mask:0xf bound_ctrl:1
	v_mov_b32_dpp v159, v19 quad_perm:[2,3,0,1] row_mask:0xf bank_mask:0xf bound_ctrl:1
	v_pk_add_f32 v[18:19], v[18:19], v[158:159]
	s_nop 1
	v_mov_b32_dpp v158, v18 row_half_mirror row_mask:0xf bank_mask:0xf bound_ctrl:1
	v_mov_b32_dpp v159, v19 row_half_mirror row_mask:0xf bank_mask:0xf bound_ctrl:1
	v_pk_add_f32 v[18:19], v[18:19], v[158:159]
	s_nop 1
	v_mov_b32_dpp v158, v18 row_mirror row_mask:0xf bank_mask:0xf bound_ctrl:1
	v_mov_b32_dpp v159, v19 row_mirror row_mask:0xf bank_mask:0xf bound_ctrl:1
	s_and_saveexec_b64 s[6:7], vcc
	v_pk_add_f32 v[18:19], v[18:19], v[158:159]
	ds_write_b64 v179, v[18:19] offset:264
	s_or_b64 exec, exec, s[6:7]
	ds_read2_b32 v[158:159], v153 offset1:32
	ds_read2_b32 v[168:169], v153 offset0:64 offset1:96
	v_mov_b32_e32 v160, v52
	v_mov_b32_e32 v161, v20
	v_pk_add_f32 v[170:171], v[160:161], 0 op_sel_hi:[1,0]
	v_mov_b32_e32 v160, v36
	v_pk_add_f32 v[160:161], v[160:161], 0 op_sel_hi:[1,0]
	s_waitcnt lgkmcnt(1)
;   DI void operator()(f32x16 (&acc)[2][4], int grow0, int gcol0, int lane, int w, char* lds) {
;     ...
; #pragma unroll
;       for (int qq = 0; qq < 2; ++qq)
; #pragma unroll
;         for (int e = 0; e < 4; ++e) {
;           const int i = 4 * (2 * (ps & 1) + qq) + e;
;           const float* xr = (const float*)(xs + (8 * qq + 4 * hh + e) * 512) + l31;
;           float s1 = 0.f, s2 = 0.f;
; #pragma unroll
;           for (int nt = 0; nt < 4; ++nt) {
;             float v = (acc[mt][nt][i] + bia[nt]) * csc[nt];
;             float z = ALPHA * xr[nt * 32] + hs * v;
;             acc[mt][nt][i] = z; s1 += z; s2 += z * z;
;           }
;           s1 = row16_sum(s1); s2 = row16_sum(s2);
;           if ((lane & 15) == 0) { f32x2 sv = {s1, s2}; *(f32x2*)(redw + (mt * 32 + (i & 3) + 8 * (i >> 2)) * 2) = sv; }
	v_mov_b32_e32 v174, v158
	s_waitcnt lgkmcnt(0)
	v_mov_b32_e32 v175, v168
	s_mov_b32 s2, s67
	v_mov_b32_e32 v180, v159
	v_mov_b32_e32 v181, v168
	v_pk_fma_f32 v[158:159], v[174:175], s[2:3], v[170:171] op_sel_hi:[1,0,1]
	v_pk_fma_f32 v[160:161], v[180:181], s[2:3], v[160:161] op_sel_hi:[1,0,1]
	v_pk_mul_f32 v[176:177], v[174:175], s[2:3] op_sel_hi:[1,0]
	v_pk_mul_f32 v[174:175], v[158:159], v[158:159]
	v_pk_mul_f32 v[180:181], v[160:161], v[160:161]
	v_pk_mov_b32 v[170:171], v[170:171], v[174:175] op_sel:[1,0]
	v_pk_mov_b32 v[174:175], v[176:177], v[180:181] op_sel:[1,0]
	v_add_f32_e32 v18, 0, v4
	v_pk_add_f32 v[170:171], v[170:171], v[174:175]
	v_pk_add_f32 v[174:175], v[158:159], v[160:161]
	v_pk_mul_f32 v[176:177], v[158:159], v[160:161]
	v_fmac_f32_e32 v18, 0x3fd744fd, v169
	v_mov_b32_e32 v175, v177
	v_pk_add_f32 v[170:171], v[174:175], v[170:171]
	v_mul_f32_e32 v19, v18, v18
	v_pk_add_f32 v[168:169], v[170:171], v[18:19]
	s_nop 1
	v_mov_b32_dpp v170, v168 quad_perm:[1,0,3,2] row_mask:0xf bank_mask:0xf bound_ctrl:1
	v_mov_b32_dpp v171, v169 quad_perm:[1,0,3,2] row_mask:0xf bank_mask:0xf bound_ctrl:1
	v_pk_add_f32 v[168:169], v[168:169], v[170:171]
	s_nop 1
	v_mov_b32_dpp v170, v168 quad_perm:[2,3,0,1] row_mask:0xf bank_mask:0xf bound_ctrl:1
	v_mov_b32_dpp v171, v169 quad_perm:[2,3,0,1] row_mask:0xf bank_mask:0xf bound_ctrl:1
	v_pk_add_f32 v[168:169], v[168:169], v[170:171]
	s_nop 1
	v_mov_b32_dpp v170, v168 row_half_mirror row_mask:0xf bank_mask:0xf bound_ctrl:1
	v_mov_b32_dpp v171, v169 row_half_mirror row_mask:0xf bank_mask:0xf bound_ctrl:1
	v_pk_add_f32 v[168:169], v[168:169], v[170:171]
	s_nop 1
	v_mov_b32_dpp v170, v168 row_mirror row_mask:0xf bank_mask:0xf bound_ctrl:1
	v_mov_b32_dpp v171, v169 row_mirror row_mask:0xf bank_mask:0xf bound_ctrl:1
	s_and_saveexec_b64 s[6:7], vcc
	v_pk_add_f32 v[168:169], v[168:169], v[170:171]
	ds_write_b64 v179, v[168:169] offset:272
	s_or_b64 exec, exec, s[6:7]
	ds_read2_b32 v[168:169], v151 offset1:32
	ds_read2_b32 v[170:171], v151 offset0:64 offset1:96
	v_mov_b32_e32 v20, v53
	v_pk_add_f32 v[174:175], v[20:21], 0 op_sel_hi:[1,0]
	v_mov_b32_e32 v20, v37
	v_pk_add_f32 v[20:21], v[20:21], 0 op_sel_hi:[1,0]
	s_waitcnt lgkmcnt(1)
	v_mov_b32_e32 v36, v168
	s_waitcnt lgkmcnt(0)
	v_mov_b32_e32 v37, v170
	s_mov_b32 s2, s67
	v_mov_b32_e32 v52, v169
	v_mov_b32_e32 v53, v170
	v_pk_mul_f32 v[176:177], v[36:37], s[2:3] op_sel_hi:[1,0]
	v_pk_fma_f32 v[36:37], v[36:37], s[2:3], v[174:175] op_sel_hi:[1,0,1]
	v_pk_fma_f32 v[52:53], v[52:53], s[2:3], v[20:21] op_sel_hi:[1,0,1]
	v_pk_mul_f32 v[168:169], v[36:37], v[36:37]
	v_pk_mul_f32 v[20:21], v[52:53], v[52:53]
	v_pk_mov_b32 v[168:169], v[174:175], v[168:169] op_sel:[1,0]
	v_pk_mov_b32 v[20:21], v[176:177], v[20:21] op_sel:[1,0]
	v_add_f32_e32 v4, 0, v5
	v_pk_add_f32 v[20:21], v[168:169], v[20:21]
	v_pk_add_f32 v[168:169], v[36:37], v[52:53]
	v_pk_mul_f32 v[174:175], v[36:37], v[52:53]
	v_fmac_f32_e32 v4, 0x3fd744fd, v171
	v_mov_b32_e32 v169, v175
	v_pk_add_f32 v[20:21], v[168:169], v[20:21]
	v_mul_f32_e32 v5, v4, v4
	v_pk_add_f32 v[20:21], v[20:21], v[4:5]
	s_nop 1
	v_mov_b32_dpp v168, v20 quad_perm:[1,0,3,2] row_mask:0xf bank_mask:0xf bound_ctrl:1
	v_mov_b32_dpp v169, v21 quad_perm:[1,0,3,2] row_mask:0xf bank_mask:0xf bound_ctrl:1
	v_pk_add_f32 v[20:21], v[20:21], v[168:169]
	s_nop 1
	v_mov_b32_dpp v168, v20 quad_perm:[2,3,0,1] row_mask:0xf bank_mask:0xf bound_ctrl:1
	v_mov_b32_dpp v169, v21 quad_perm:[2,3,0,1] row_mask:0xf bank_mask:0xf bound_ctrl:1
	v_pk_add_f32 v[20:21], v[20:21], v[168:169]
	s_nop 1
	v_mov_b32_dpp v168, v20 row_half_mirror row_mask:0xf bank_mask:0xf bound_ctrl:1
	v_mov_b32_dpp v169, v21 row_half_mirror row_mask:0xf bank_mask:0xf bound_ctrl:1
	v_pk_add_f32 v[20:21], v[20:21], v[168:169]
	s_nop 1
	v_mov_b32_dpp v168, v20 row_mirror row_mask:0xf bank_mask:0xf bound_ctrl:1
	v_mov_b32_dpp v169, v21 row_mirror row_mask:0xf bank_mask:0xf bound_ctrl:1
	s_and_saveexec_b64 s[6:7], vcc
	v_pk_add_f32 v[20:21], v[20:21], v[168:169]
	ds_write_b64 v179, v[20:21] offset:280
	s_or_b64 exec, exec, s[6:7]
	ds_read2_b32 v[168:169], v67 offset1:32
	ds_read2_b32 v[174:175], v67 offset0:64 offset1:96
	v_mov_b32_e32 v170, v54
	v_mov_b32_e32 v171, v22
	v_pk_add_f32 v[176:177], v[170:171], 0 op_sel_hi:[1,0]
	v_mov_b32_e32 v170, v38
	v_pk_add_f32 v[170:171], v[170:171], 0 op_sel_hi:[1,0]
	s_waitcnt lgkmcnt(1)
	v_mov_b32_e32 v180, v168
	s_waitcnt lgkmcnt(0)
	v_mov_b32_e32 v181, v174
	s_mov_b32 s2, s67
	v_mov_b32_e32 v190, v169
	v_mov_b32_e32 v191, v174
	v_pk_fma_f32 v[168:169], v[180:181], s[2:3], v[176:177] op_sel_hi:[1,0,1]
	v_pk_fma_f32 v[170:171], v[190:191], s[2:3], v[170:171] op_sel_hi:[1,0,1]
	v_pk_mul_f32 v[184:185], v[180:181], s[2:3] op_sel_hi:[1,0]
	v_pk_mul_f32 v[180:181], v[168:169], v[168:169]
	v_pk_mul_f32 v[190:191], v[170:171], v[170:171]
	v_pk_mov_b32 v[176:177], v[176:177], v[180:181] op_sel:[1,0]
	v_pk_mov_b32 v[180:181], v[184:185], v[190:191] op_sel:[1,0]
	v_add_f32_e32 v20, 0, v6
	v_pk_add_f32 v[176:177], v[176:177], v[180:181]
	v_pk_add_f32 v[180:181], v[168:169], v[170:171]
	v_pk_mul_f32 v[184:185], v[168:169], v[170:171]
	v_fmac_f32_e32 v20, 0x3fd744fd, v175
	v_mov_b32_e32 v181, v185
	v_pk_add_f32 v[176:177], v[180:181], v[176:177]
	v_mul_f32_e32 v21, v20, v20
	v_pk_add_f32 v[174:175], v[176:177], v[20:21]
	s_nop 1
	v_mov_b32_dpp v176, v174 quad_perm:[1,0,3,2] row_mask:0xf bank_mask:0xf bound_ctrl:1
	v_mov_b32_dpp v177, v175 quad_perm:[1,0,3,2] row_mask:0xf bank_mask:0xf bound_ctrl:1
	v_pk_add_f32 v[174:175], v[174:175], v[176:177]
	s_nop 1
	v_mov_b32_dpp v176, v174 quad_perm:[2,3,0,1] row_mask:0xf bank_mask:0xf bound_ctrl:1
	v_mov_b32_dpp v177, v175 quad_perm:[2,3,0,1] row_mask:0xf bank_mask:0xf bound_ctrl:1
	v_pk_add_f32 v[174:175], v[174:175], v[176:177]
	s_nop 1
	v_mov_b32_dpp v176, v174 row_half_mirror row_mask:0xf bank_mask:0xf bound_ctrl:1
	v_mov_b32_dpp v177, v175 row_half_mirror row_mask:0xf bank_mask:0xf bound_ctrl:1
	v_pk_add_f32 v[174:175], v[174:175], v[176:177]
	s_nop 1
	v_mov_b32_dpp v176, v174 row_mirror row_mask:0xf bank_mask:0xf bound_ctrl:1
	v_mov_b32_dpp v177, v175 row_mirror row_mask:0xf bank_mask:0xf bound_ctrl:1
	s_and_saveexec_b64 s[6:7], vcc
	v_pk_add_f32 v[174:175], v[174:175], v[176:177]
	ds_write_b64 v179, v[174:175] offset:320
	s_or_b64 exec, exec, s[6:7]
	ds_read2_b32 v[174:175], v67 offset0:128 offset1:160
	ds_read2_b32 v[176:177], v67 offset0:192 offset1:224
	v_mov_b32_e32 v22, v55
	v_pk_add_f32 v[180:181], v[22:23], 0 op_sel_hi:[1,0]
	v_mov_b32_e32 v22, v39
	v_pk_add_f32 v[22:23], v[22:23], 0 op_sel_hi:[1,0]
	s_waitcnt lgkmcnt(1)
;   DI void operator()(f32x16 (&acc)[2][4], int grow0, int gcol0, int lane, int w, char* lds) {
;     ...
; #pragma unroll
;       for (int qq = 0; qq < 2; ++qq)
; #pragma unroll
;         for (int e = 0; e < 4; ++e) {
;           const int i = 4 * (2 * (ps & 1) + qq) + e;
;           const float* xr = (const float*)(xs + (8 * qq + 4 * hh + e) * 512) + l31;
;           float s1 = 0.f, s2 = 0.f;
; #pragma unroll
;           for (int nt = 0; nt < 4; ++nt) {
;             float v = (acc[mt][nt][i] + bia[nt]) * csc[nt];
;             float z = ALPHA * xr[nt * 32] + hs * v;
;             acc[mt][nt][i] = z; s1 += z; s2 += z * z;
;           }
;           s1 = row16_sum(s1); s2 = row16_sum(s2);
;           if ((lane & 15) == 0) { f32x2 sv = {s1, s2}; *(f32x2*)(redw + (mt * 32 + (i & 3) + 8 * (i >> 2)) * 2) = sv; }
	v_mov_b32_e32 v38, v174
	s_waitcnt lgkmcnt(0)
	v_mov_b32_e32 v39, v176
	s_mov_b32 s2, s67
	v_mov_b32_e32 v54, v175
	v_mov_b32_e32 v55, v176
	v_pk_mul_f32 v[184:185], v[38:39], s[2:3] op_sel_hi:[1,0]
	v_pk_fma_f32 v[38:39], v[38:39], s[2:3], v[180:181] op_sel_hi:[1,0,1]
	v_pk_fma_f32 v[54:55], v[54:55], s[2:3], v[22:23] op_sel_hi:[1,0,1]
	v_pk_mul_f32 v[174:175], v[38:39], v[38:39]
	v_pk_mul_f32 v[22:23], v[54:55], v[54:55]
	v_pk_mov_b32 v[174:175], v[180:181], v[174:175] op_sel:[1,0]
	v_pk_mov_b32 v[22:23], v[184:185], v[22:23] op_sel:[1,0]
	v_add_f32_e32 v6, 0, v7
	v_pk_add_f32 v[22:23], v[174:175], v[22:23]
	v_pk_add_f32 v[174:175], v[38:39], v[54:55]
	v_pk_mul_f32 v[180:181], v[38:39], v[54:55]
	v_fmac_f32_e32 v6, 0x3fd744fd, v177
	v_mov_b32_e32 v175, v181
	v_pk_add_f32 v[22:23], v[174:175], v[22:23]
	v_mul_f32_e32 v7, v6, v6
	v_pk_add_f32 v[22:23], v[22:23], v[6:7]
	s_nop 1
	v_mov_b32_dpp v174, v22 quad_perm:[1,0,3,2] row_mask:0xf bank_mask:0xf bound_ctrl:1
	v_mov_b32_dpp v175, v23 quad_perm:[1,0,3,2] row_mask:0xf bank_mask:0xf bound_ctrl:1
	v_pk_add_f32 v[22:23], v[22:23], v[174:175]
	s_nop 1
	v_mov_b32_dpp v174, v22 quad_perm:[2,3,0,1] row_mask:0xf bank_mask:0xf bound_ctrl:1
	v_mov_b32_dpp v175, v23 quad_perm:[2,3,0,1] row_mask:0xf bank_mask:0xf bound_ctrl:1
	v_pk_add_f32 v[22:23], v[22:23], v[174:175]
	s_nop 1
	v_mov_b32_dpp v174, v22 row_half_mirror row_mask:0xf bank_mask:0xf bound_ctrl:1
	v_mov_b32_dpp v175, v23 row_half_mirror row_mask:0xf bank_mask:0xf bound_ctrl:1
	v_pk_add_f32 v[22:23], v[22:23], v[174:175]
	s_nop 1
	v_mov_b32_dpp v174, v22 row_mirror row_mask:0xf bank_mask:0xf bound_ctrl:1
	v_mov_b32_dpp v175, v23 row_mirror row_mask:0xf bank_mask:0xf bound_ctrl:1
	s_and_saveexec_b64 s[6:7], vcc
	v_pk_add_f32 v[22:23], v[22:23], v[174:175]
	ds_write_b64 v179, v[22:23] offset:328
	s_or_b64 exec, exec, s[6:7]
	ds_read2_b32 v[174:175], v69 offset1:32
	ds_read2_b32 v[180:181], v69 offset0:64 offset1:96
	v_mov_b32_e32 v176, v56
	v_mov_b32_e32 v177, v24
	v_pk_add_f32 v[184:185], v[176:177], 0 op_sel_hi:[1,0]
	v_mov_b32_e32 v176, v40
	v_pk_add_f32 v[176:177], v[176:177], 0 op_sel_hi:[1,0]
	s_waitcnt lgkmcnt(1)
	v_mov_b32_e32 v190, v174
	s_waitcnt lgkmcnt(0)
	v_mov_b32_e32 v191, v180
	s_mov_b32 s2, s67
	v_mov_b32_e32 v194, v175
	v_mov_b32_e32 v195, v180
	v_pk_fma_f32 v[174:175], v[190:191], s[2:3], v[184:185] op_sel_hi:[1,0,1]
	v_pk_fma_f32 v[176:177], v[194:195], s[2:3], v[176:177] op_sel_hi:[1,0,1]
	v_pk_mul_f32 v[192:193], v[190:191], s[2:3] op_sel_hi:[1,0]
	v_pk_mul_f32 v[190:191], v[174:175], v[174:175]
	v_pk_mul_f32 v[194:195], v[176:177], v[176:177]
	v_pk_mov_b32 v[184:185], v[184:185], v[190:191] op_sel:[1,0]
	v_pk_mov_b32 v[190:191], v[192:193], v[194:195] op_sel:[1,0]
	v_add_f32_e32 v22, 0, v8
	v_pk_add_f32 v[184:185], v[184:185], v[190:191]
	v_pk_add_f32 v[190:191], v[174:175], v[176:177]
	v_pk_mul_f32 v[192:193], v[174:175], v[176:177]
	v_fmac_f32_e32 v22, 0x3fd744fd, v181
	v_mov_b32_e32 v191, v193
	v_pk_add_f32 v[184:185], v[190:191], v[184:185]
	v_mul_f32_e32 v23, v22, v22
	v_pk_add_f32 v[180:181], v[184:185], v[22:23]
	s_nop 1
	v_mov_b32_dpp v184, v180 quad_perm:[1,0,3,2] row_mask:0xf bank_mask:0xf bound_ctrl:1
	v_mov_b32_dpp v185, v181 quad_perm:[1,0,3,2] row_mask:0xf bank_mask:0xf bound_ctrl:1
	v_pk_add_f32 v[180:181], v[180:181], v[184:185]
	s_nop 1
	v_mov_b32_dpp v184, v180 quad_perm:[2,3,0,1] row_mask:0xf bank_mask:0xf bound_ctrl:1
	v_mov_b32_dpp v185, v181 quad_perm:[2,3,0,1] row_mask:0xf bank_mask:0xf bound_ctrl:1
	v_pk_add_f32 v[180:181], v[180:181], v[184:185]
	s_nop 1
	v_mov_b32_dpp v184, v180 row_half_mirror row_mask:0xf bank_mask:0xf bound_ctrl:1
	v_mov_b32_dpp v185, v181 row_half_mirror row_mask:0xf bank_mask:0xf bound_ctrl:1
	v_pk_add_f32 v[180:181], v[180:181], v[184:185]
	s_nop 1
	v_mov_b32_dpp v184, v180 row_mirror row_mask:0xf bank_mask:0xf bound_ctrl:1
	v_mov_b32_dpp v185, v181 row_mirror row_mask:0xf bank_mask:0xf bound_ctrl:1
	s_and_saveexec_b64 s[6:7], vcc
	v_pk_add_f32 v[180:181], v[180:181], v[184:185]
	ds_write_b64 v179, v[180:181] offset:336
	s_or_b64 exec, exec, s[6:7]
	ds_read2_b32 v[180:181], v71 offset1:32
	ds_read2_b32 v[184:185], v71 offset0:64 offset1:96
	v_mov_b32_e32 v24, v57
	v_pk_add_f32 v[190:191], v[24:25], 0 op_sel_hi:[1,0]
	v_mov_b32_e32 v24, v41
	v_pk_add_f32 v[24:25], v[24:25], 0 op_sel_hi:[1,0]
	s_waitcnt lgkmcnt(1)
	v_mov_b32_e32 v40, v180
	s_waitcnt lgkmcnt(0)
	v_mov_b32_e32 v41, v184
	s_mov_b32 s2, s67
	v_mov_b32_e32 v56, v181
	v_mov_b32_e32 v57, v184
	v_pk_mul_f32 v[192:193], v[40:41], s[2:3] op_sel_hi:[1,0]
	v_pk_fma_f32 v[40:41], v[40:41], s[2:3], v[190:191] op_sel_hi:[1,0,1]
	v_pk_fma_f32 v[56:57], v[56:57], s[2:3], v[24:25] op_sel_hi:[1,0,1]
	v_pk_mul_f32 v[180:181], v[40:41], v[40:41]
	v_pk_mul_f32 v[24:25], v[56:57], v[56:57]
	v_pk_mov_b32 v[180:181], v[190:191], v[180:181] op_sel:[1,0]
	v_pk_mov_b32 v[24:25], v[192:193], v[24:25] op_sel:[1,0]
	v_add_f32_e32 v8, 0, v9
	v_pk_add_f32 v[24:25], v[180:181], v[24:25]
	v_pk_add_f32 v[180:181], v[40:41], v[56:57]
	v_pk_mul_f32 v[190:191], v[40:41], v[56:57]
	v_fmac_f32_e32 v8, 0x3fd744fd, v185
	v_mov_b32_e32 v181, v191
	v_pk_add_f32 v[24:25], v[180:181], v[24:25]
	v_mul_f32_e32 v9, v8, v8
	v_pk_add_f32 v[24:25], v[24:25], v[8:9]
	s_nop 1
	v_mov_b32_dpp v180, v24 quad_perm:[1,0,3,2] row_mask:0xf bank_mask:0xf bound_ctrl:1
	v_mov_b32_dpp v181, v25 quad_perm:[1,0,3,2] row_mask:0xf bank_mask:0xf bound_ctrl:1
	v_pk_add_f32 v[24:25], v[24:25], v[180:181]
	s_nop 1
	v_mov_b32_dpp v180, v24 quad_perm:[2,3,0,1] row_mask:0xf bank_mask:0xf bound_ctrl:1
	v_mov_b32_dpp v181, v25 quad_perm:[2,3,0,1] row_mask:0xf bank_mask:0xf bound_ctrl:1
	v_pk_add_f32 v[24:25], v[24:25], v[180:181]
	s_nop 1
	v_mov_b32_dpp v180, v24 row_half_mirror row_mask:0xf bank_mask:0xf bound_ctrl:1
	v_mov_b32_dpp v181, v25 row_half_mirror row_mask:0xf bank_mask:0xf bound_ctrl:1
	v_pk_add_f32 v[24:25], v[24:25], v[180:181]
	s_nop 1
	v_mov_b32_dpp v180, v24 row_mirror row_mask:0xf bank_mask:0xf bound_ctrl:1
	v_mov_b32_dpp v181, v25 row_mirror row_mask:0xf bank_mask:0xf bound_ctrl:1
	s_and_saveexec_b64 s[6:7], vcc
	v_pk_add_f32 v[24:25], v[24:25], v[180:181]
	ds_write_b64 v179, v[24:25] offset:344
	s_or_b64 exec, exec, s[6:7]
	s_waitcnt vmcnt(0)
;   DI void operator()(f32x16 (&acc)[2][4], int grow0, int gcol0, int lane, int w, char* lds) {
;     ...
; #pragma unroll
;       for (int qq = 0; qq < 2; ++qq)
; #pragma unroll
;         for (int e = 0; e < 4; ++e) {
;           const int i = 4 * (2 * (ps & 1) + qq) + e;
;           const float* xr = (const float*)(xs + (8 * qq + 4 * hh + e) * 512) + l31;
;           float s1 = 0.f, s2 = 0.f;
; #pragma unroll
;           for (int nt = 0; nt < 4; ++nt) {
;             float v = (acc[mt][nt][i] + bia[nt]) * csc[nt];
;             float z = ALPHA * xr[nt * 32] + hs * v;
;             acc[mt][nt][i] = z; s1 += z; s2 += z * z;
;           }
;           s1 = row16_sum(s1); s2 = row16_sum(s2);
;           if ((lane & 15) == 0) { f32x2 sv = {s1, s2}; *(f32x2*)(redw + (mt * 32 + (i & 3) + 8 * (i >> 2)) * 2) = sv; }
	ds_read2_b32 v[184:185], v73 offset1:32
	ds_read2_b32 v[192:193], v73 offset0:64 offset1:96
	v_add_f32_e32 v181, 0, v42
	v_mov_b32_e32 v190, v58
	v_mov_b32_e32 v191, v26
	s_waitcnt lgkmcnt(1)
	v_fmac_f32_e32 v181, 0x3fd744fd, v185
	v_pk_add_f32 v[194:195], v[190:191], 0 op_sel_hi:[1,0]
	s_waitcnt lgkmcnt(0)
	v_mov_b32_e32 v185, v192
	s_mov_b32 s2, s67
	v_pk_fma_f32 v[190:191], v[184:185], s[2:3], v[194:195] op_sel_hi:[1,0,1]
	v_mov_b32_e32 v180, v192
	v_pk_mul_f32 v[184:185], v[190:191], v[190:191]
	v_mov_b32_e32 v196, v165
	v_mov_b32_e32 v197, v181
	v_pk_mov_b32 v[184:185], v[194:195], v[184:185] op_sel:[1,0]
	v_add_f32_e32 v24, 0, v10
	v_pk_fma_f32 v[184:185], v[180:181], v[196:197], v[184:185]
	v_fmac_f32_e32 v24, 0x3fd744fd, v193
	v_pk_mov_b32 v[194:195], v[180:181], v[184:185] op_sel:[1,0]
	v_mul_f32_e32 v25, v24, v24
	v_pk_add_f32 v[196:197], v[190:191], v[194:195]
	v_pk_mul_f32 v[194:195], v[190:191], v[194:195]
	s_nop 0
	v_mov_b32_e32 v197, v195
	v_pk_add_f32 v[194:195], v[184:185], v[196:197]
	s_nop 0
	v_pk_add_f32 v[192:193], v[194:195], v[24:25]
	s_nop 1
	v_mov_b32_dpp v194, v192 quad_perm:[1,0,3,2] row_mask:0xf bank_mask:0xf bound_ctrl:1
	v_mov_b32_dpp v195, v193 quad_perm:[1,0,3,2] row_mask:0xf bank_mask:0xf bound_ctrl:1
	v_pk_add_f32 v[192:193], v[192:193], v[194:195]
	s_nop 1
	v_mov_b32_dpp v194, v192 quad_perm:[2,3,0,1] row_mask:0xf bank_mask:0xf bound_ctrl:1
	v_mov_b32_dpp v195, v193 quad_perm:[2,3,0,1] row_mask:0xf bank_mask:0xf bound_ctrl:1
	v_pk_add_f32 v[192:193], v[192:193], v[194:195]
	s_nop 1
	v_mov_b32_dpp v194, v192 row_half_mirror row_mask:0xf bank_mask:0xf bound_ctrl:1
	v_mov_b32_dpp v195, v193 row_half_mirror row_mask:0xf bank_mask:0xf bound_ctrl:1
	v_pk_add_f32 v[192:193], v[192:193], v[194:195]
	s_nop 1
	v_mov_b32_dpp v194, v192 row_mirror row_mask:0xf bank_mask:0xf bound_ctrl:1
	v_mov_b32_dpp v195, v193 row_mirror row_mask:0xf bank_mask:0xf bound_ctrl:1
	s_and_saveexec_b64 s[6:7], vcc
	v_pk_add_f32 v[192:193], v[192:193], v[194:195]
	ds_write_b64 v179, v[192:193] offset:384
	s_or_b64 exec, exec, s[6:7]
	ds_read2_b32 v[192:193], v85 offset1:32
	ds_read2_b32 v[194:195], v85 offset0:64 offset1:96
	v_mov_b32_e32 v26, v59
	v_pk_add_f32 v[196:197], v[26:27], 0 op_sel_hi:[1,0]
	v_mov_b32_e32 v26, v43
	v_pk_add_f32 v[26:27], v[26:27], 0 op_sel_hi:[1,0]
	s_waitcnt lgkmcnt(1)
	v_mov_b32_e32 v42, v192
	s_waitcnt lgkmcnt(0)
	v_mov_b32_e32 v43, v194
	s_mov_b32 s2, s67
	v_mov_b32_e32 v58, v193
	v_mov_b32_e32 v59, v194
	v_pk_mul_f32 v[198:199], v[42:43], s[2:3] op_sel_hi:[1,0]
	v_pk_fma_f32 v[42:43], v[42:43], s[2:3], v[196:197] op_sel_hi:[1,0,1]
	v_pk_fma_f32 v[58:59], v[58:59], s[2:3], v[26:27] op_sel_hi:[1,0,1]
	v_pk_mul_f32 v[192:193], v[42:43], v[42:43]
	v_pk_mul_f32 v[26:27], v[58:59], v[58:59]
	v_pk_mov_b32 v[192:193], v[196:197], v[192:193] op_sel:[1,0]
	v_pk_mov_b32 v[26:27], v[198:199], v[26:27] op_sel:[1,0]
	v_add_f32_e32 v10, 0, v11
	v_pk_add_f32 v[26:27], v[192:193], v[26:27]
	v_pk_add_f32 v[192:193], v[42:43], v[58:59]
	v_pk_mul_f32 v[196:197], v[42:43], v[58:59]
	v_fmac_f32_e32 v10, 0x3fd744fd, v195
	v_mov_b32_e32 v193, v197
	v_pk_add_f32 v[26:27], v[192:193], v[26:27]
	v_mul_f32_e32 v11, v10, v10
	v_pk_add_f32 v[26:27], v[26:27], v[10:11]
	s_nop 1
	v_mov_b32_dpp v192, v26 quad_perm:[1,0,3,2] row_mask:0xf bank_mask:0xf bound_ctrl:1
	v_mov_b32_dpp v193, v27 quad_perm:[1,0,3,2] row_mask:0xf bank_mask:0xf bound_ctrl:1
	v_pk_add_f32 v[26:27], v[26:27], v[192:193]
	s_nop 1
	v_mov_b32_dpp v192, v26 quad_perm:[2,3,0,1] row_mask:0xf bank_mask:0xf bound_ctrl:1
	v_mov_b32_dpp v193, v27 quad_perm:[2,3,0,1] row_mask:0xf bank_mask:0xf bound_ctrl:1
	v_pk_add_f32 v[26:27], v[26:27], v[192:193]
	s_nop 1
	v_mov_b32_dpp v192, v26 row_half_mirror row_mask:0xf bank_mask:0xf bound_ctrl:1
	v_mov_b32_dpp v193, v27 row_half_mirror row_mask:0xf bank_mask:0xf bound_ctrl:1
	v_pk_add_f32 v[26:27], v[26:27], v[192:193]
	s_nop 1
	v_mov_b32_dpp v192, v26 row_mirror row_mask:0xf bank_mask:0xf bound_ctrl:1
	v_mov_b32_dpp v193, v27 row_mirror row_mask:0xf bank_mask:0xf bound_ctrl:1
	s_and_saveexec_b64 s[6:7], vcc
	v_pk_add_f32 v[26:27], v[26:27], v[192:193]
	ds_write_b64 v179, v[26:27] offset:392
	s_or_b64 exec, exec, s[6:7]
	ds_read2_b32 v[192:193], v75 offset1:32
	ds_read2_b32 v[196:197], v75 offset0:64 offset1:96
	v_mov_b32_e32 v194, v60
	v_mov_b32_e32 v195, v28
	v_pk_add_f32 v[198:199], v[194:195], 0 op_sel_hi:[1,0]
	v_mov_b32_e32 v194, v44
	v_pk_add_f32 v[194:195], v[194:195], 0 op_sel_hi:[1,0]
	s_waitcnt lgkmcnt(1)
	v_mov_b32_e32 v202, v192
	s_waitcnt lgkmcnt(0)
	v_mov_b32_e32 v203, v196
	s_mov_b32 s2, s67
	v_mov_b32_e32 v206, v193
	v_mov_b32_e32 v207, v196
	v_pk_fma_f32 v[192:193], v[202:203], s[2:3], v[198:199] op_sel_hi:[1,0,1]
	v_pk_fma_f32 v[194:195], v[206:207], s[2:3], v[194:195] op_sel_hi:[1,0,1]
	v_pk_mul_f32 v[204:205], v[202:203], s[2:3] op_sel_hi:[1,0]
	v_pk_mul_f32 v[202:203], v[192:193], v[192:193]
	v_pk_mul_f32 v[206:207], v[194:195], v[194:195]
	v_pk_mov_b32 v[198:199], v[198:199], v[202:203] op_sel:[1,0]
	v_pk_mov_b32 v[202:203], v[204:205], v[206:207] op_sel:[1,0]
	v_add_f32_e32 v26, 0, v12
	v_pk_add_f32 v[198:199], v[198:199], v[202:203]
	v_pk_add_f32 v[202:203], v[192:193], v[194:195]
	v_pk_mul_f32 v[204:205], v[192:193], v[194:195]
	v_fmac_f32_e32 v26, 0x3fd744fd, v197
	v_mov_b32_e32 v203, v205
	v_pk_add_f32 v[198:199], v[202:203], v[198:199]
	v_mul_f32_e32 v27, v26, v26
	v_pk_add_f32 v[196:197], v[198:199], v[26:27]
	s_nop 1
	v_mov_b32_dpp v198, v196 quad_perm:[1,0,3,2] row_mask:0xf bank_mask:0xf bound_ctrl:1
	v_mov_b32_dpp v199, v197 quad_perm:[1,0,3,2] row_mask:0xf bank_mask:0xf bound_ctrl:1
	v_pk_add_f32 v[196:197], v[196:197], v[198:199]
	s_nop 1
	v_mov_b32_dpp v198, v196 quad_perm:[2,3,0,1] row_mask:0xf bank_mask:0xf bound_ctrl:1
	v_mov_b32_dpp v199, v197 quad_perm:[2,3,0,1] row_mask:0xf bank_mask:0xf bound_ctrl:1
	v_pk_add_f32 v[196:197], v[196:197], v[198:199]
	s_nop 1
	v_mov_b32_dpp v198, v196 row_half_mirror row_mask:0xf bank_mask:0xf bound_ctrl:1
	v_mov_b32_dpp v199, v197 row_half_mirror row_mask:0xf bank_mask:0xf bound_ctrl:1
	v_pk_add_f32 v[196:197], v[196:197], v[198:199]
	s_nop 1
	v_mov_b32_dpp v198, v196 row_mirror row_mask:0xf bank_mask:0xf bound_ctrl:1
	v_mov_b32_dpp v199, v197 row_mirror row_mask:0xf bank_mask:0xf bound_ctrl:1
	s_and_saveexec_b64 s[6:7], vcc
	v_pk_add_f32 v[196:197], v[196:197], v[198:199]
	ds_write_b64 v179, v[196:197] offset:400
	s_or_b64 exec, exec, s[6:7]
	ds_read2_b32 v[196:197], v87 offset1:32
	ds_read2_b32 v[198:199], v87 offset0:64 offset1:96
	v_mov_b32_e32 v28, v61
	v_pk_add_f32 v[202:203], v[28:29], 0 op_sel_hi:[1,0]
	v_mov_b32_e32 v28, v45
	v_pk_add_f32 v[28:29], v[28:29], 0 op_sel_hi:[1,0]
	s_waitcnt lgkmcnt(1)
;   DI void operator()(f32x16 (&acc)[2][4], int grow0, int gcol0, int lane, int w, char* lds) {
;     ...
; #pragma unroll
;       for (int qq = 0; qq < 2; ++qq)
; #pragma unroll
;         for (int e = 0; e < 4; ++e) {
;           const int i = 4 * (2 * (ps & 1) + qq) + e;
;           const float* xr = (const float*)(xs + (8 * qq + 4 * hh + e) * 512) + l31;
;           float s1 = 0.f, s2 = 0.f;
; #pragma unroll
;           for (int nt = 0; nt < 4; ++nt) {
;             float v = (acc[mt][nt][i] + bia[nt]) * csc[nt];
;             float z = ALPHA * xr[nt * 32] + hs * v;
;             acc[mt][nt][i] = z; s1 += z; s2 += z * z;
;           }
;           s1 = row16_sum(s1); s2 = row16_sum(s2);
;           if ((lane & 15) == 0) { f32x2 sv = {s1, s2}; *(f32x2*)(redw + (mt * 32 + (i & 3) + 8 * (i >> 2)) * 2) = sv; }
	v_mov_b32_e32 v44, v196
	s_waitcnt lgkmcnt(0)
	v_mov_b32_e32 v45, v198
	s_mov_b32 s2, s67
	v_mov_b32_e32 v60, v197
	v_mov_b32_e32 v61, v198
	v_pk_mul_f32 v[204:205], v[44:45], s[2:3] op_sel_hi:[1,0]
	v_pk_fma_f32 v[44:45], v[44:45], s[2:3], v[202:203] op_sel_hi:[1,0,1]
	v_pk_fma_f32 v[60:61], v[60:61], s[2:3], v[28:29] op_sel_hi:[1,0,1]
	v_pk_mul_f32 v[196:197], v[44:45], v[44:45]
	v_pk_mul_f32 v[28:29], v[60:61], v[60:61]
	v_pk_mov_b32 v[196:197], v[202:203], v[196:197] op_sel:[1,0]
	v_pk_mov_b32 v[28:29], v[204:205], v[28:29] op_sel:[1,0]
	v_add_f32_e32 v12, 0, v13
	v_pk_add_f32 v[28:29], v[196:197], v[28:29]
	v_pk_add_f32 v[196:197], v[44:45], v[60:61]
	v_pk_mul_f32 v[202:203], v[44:45], v[60:61]
	v_fmac_f32_e32 v12, 0x3fd744fd, v199
	v_mov_b32_e32 v197, v203
	v_pk_add_f32 v[28:29], v[196:197], v[28:29]
	v_mul_f32_e32 v13, v12, v12
	v_pk_add_f32 v[28:29], v[28:29], v[12:13]
	s_nop 1
	v_mov_b32_dpp v196, v28 quad_perm:[1,0,3,2] row_mask:0xf bank_mask:0xf bound_ctrl:1
	v_mov_b32_dpp v197, v29 quad_perm:[1,0,3,2] row_mask:0xf bank_mask:0xf bound_ctrl:1
	v_pk_add_f32 v[28:29], v[28:29], v[196:197]
	s_nop 1
	v_mov_b32_dpp v196, v28 quad_perm:[2,3,0,1] row_mask:0xf bank_mask:0xf bound_ctrl:1
	v_mov_b32_dpp v197, v29 quad_perm:[2,3,0,1] row_mask:0xf bank_mask:0xf bound_ctrl:1
	v_pk_add_f32 v[28:29], v[28:29], v[196:197]
	s_nop 1
	v_mov_b32_dpp v196, v28 row_half_mirror row_mask:0xf bank_mask:0xf bound_ctrl:1
	v_mov_b32_dpp v197, v29 row_half_mirror row_mask:0xf bank_mask:0xf bound_ctrl:1
	v_pk_add_f32 v[28:29], v[28:29], v[196:197]
	s_nop 1
	v_mov_b32_dpp v196, v28 row_mirror row_mask:0xf bank_mask:0xf bound_ctrl:1
	v_mov_b32_dpp v197, v29 row_mirror row_mask:0xf bank_mask:0xf bound_ctrl:1
	s_and_saveexec_b64 s[6:7], vcc
	v_pk_add_f32 v[28:29], v[28:29], v[196:197]
	ds_write_b64 v179, v[28:29] offset:408
	s_or_b64 exec, exec, s[6:7]
	ds_read2_b32 v[196:197], v77 offset1:32
	ds_read2_b32 v[202:203], v77 offset0:64 offset1:96
	v_mov_b32_e32 v198, v62
	v_mov_b32_e32 v199, v30
	v_pk_add_f32 v[204:205], v[198:199], 0 op_sel_hi:[1,0]
	v_mov_b32_e32 v198, v46
	v_pk_add_f32 v[198:199], v[198:199], 0 op_sel_hi:[1,0]
	s_waitcnt lgkmcnt(1)
	v_mov_b32_e32 v206, v196
	s_waitcnt lgkmcnt(0)
	v_mov_b32_e32 v207, v202
	s_mov_b32 s2, s67
	v_mov_b32_e32 v212, v197
	v_mov_b32_e32 v213, v202
	v_pk_fma_f32 v[196:197], v[206:207], s[2:3], v[204:205] op_sel_hi:[1,0,1]
	v_pk_fma_f32 v[198:199], v[212:213], s[2:3], v[198:199] op_sel_hi:[1,0,1]
	v_pk_mul_f32 v[208:209], v[206:207], s[2:3] op_sel_hi:[1,0]
	v_pk_mul_f32 v[206:207], v[196:197], v[196:197]
	v_pk_mul_f32 v[212:213], v[198:199], v[198:199]
	v_pk_mov_b32 v[204:205], v[204:205], v[206:207] op_sel:[1,0]
	v_pk_mov_b32 v[206:207], v[208:209], v[212:213] op_sel:[1,0]
	v_add_f32_e32 v28, 0, v14
	v_pk_add_f32 v[204:205], v[204:205], v[206:207]
	v_pk_add_f32 v[206:207], v[196:197], v[198:199]
	v_pk_mul_f32 v[208:209], v[196:197], v[198:199]
	v_fmac_f32_e32 v28, 0x3fd744fd, v203
	v_mov_b32_e32 v207, v209
	v_pk_add_f32 v[204:205], v[206:207], v[204:205]
	v_mul_f32_e32 v29, v28, v28
	v_pk_add_f32 v[202:203], v[204:205], v[28:29]
	s_nop 1
	v_mov_b32_dpp v204, v202 quad_perm:[1,0,3,2] row_mask:0xf bank_mask:0xf bound_ctrl:1
	v_mov_b32_dpp v205, v203 quad_perm:[1,0,3,2] row_mask:0xf bank_mask:0xf bound_ctrl:1
	v_pk_add_f32 v[202:203], v[202:203], v[204:205]
	s_nop 1
	v_mov_b32_dpp v204, v202 quad_perm:[2,3,0,1] row_mask:0xf bank_mask:0xf bound_ctrl:1
	v_mov_b32_dpp v205, v203 quad_perm:[2,3,0,1] row_mask:0xf bank_mask:0xf bound_ctrl:1
	v_pk_add_f32 v[202:203], v[202:203], v[204:205]
	s_nop 1
	v_mov_b32_dpp v204, v202 row_half_mirror row_mask:0xf bank_mask:0xf bound_ctrl:1
	v_mov_b32_dpp v205, v203 row_half_mirror row_mask:0xf bank_mask:0xf bound_ctrl:1
	v_pk_add_f32 v[202:203], v[202:203], v[204:205]
	s_nop 1
	v_mov_b32_dpp v204, v202 row_mirror row_mask:0xf bank_mask:0xf bound_ctrl:1
	v_mov_b32_dpp v205, v203 row_mirror row_mask:0xf bank_mask:0xf bound_ctrl:1
	s_and_saveexec_b64 s[6:7], vcc
	v_pk_add_f32 v[202:203], v[202:203], v[204:205]
	ds_write_b64 v179, v[202:203] offset:448
	s_or_b64 exec, exec, s[6:7]
	ds_read2_b32 v[202:203], v91 offset1:32
	ds_read2_b32 v[204:205], v91 offset0:64 offset1:96
	v_mov_b32_e32 v30, v63
	v_pk_add_f32 v[206:207], v[30:31], 0 op_sel_hi:[1,0]
	v_mov_b32_e32 v30, v47
	v_pk_add_f32 v[30:31], v[30:31], 0 op_sel_hi:[1,0]
	s_waitcnt lgkmcnt(1)
	v_mov_b32_e32 v46, v202
	s_waitcnt lgkmcnt(0)
	v_mov_b32_e32 v47, v204
	s_mov_b32 s2, s67
	v_mov_b32_e32 v62, v203
	v_mov_b32_e32 v63, v204
	v_pk_mul_f32 v[208:209], v[46:47], s[2:3] op_sel_hi:[1,0]
	v_pk_fma_f32 v[46:47], v[46:47], s[2:3], v[206:207] op_sel_hi:[1,0,1]
	v_pk_fma_f32 v[62:63], v[62:63], s[2:3], v[30:31] op_sel_hi:[1,0,1]
	v_pk_mul_f32 v[202:203], v[46:47], v[46:47]
	v_pk_mul_f32 v[30:31], v[62:63], v[62:63]
	v_pk_mov_b32 v[202:203], v[206:207], v[202:203] op_sel:[1,0]
	v_pk_mov_b32 v[30:31], v[208:209], v[30:31] op_sel:[1,0]
	v_add_f32_e32 v14, 0, v15
	v_pk_add_f32 v[30:31], v[202:203], v[30:31]
	v_pk_add_f32 v[202:203], v[46:47], v[62:63]
	v_pk_mul_f32 v[206:207], v[46:47], v[62:63]
	v_fmac_f32_e32 v14, 0x3fd744fd, v205
	v_mov_b32_e32 v203, v207
	v_pk_add_f32 v[30:31], v[202:203], v[30:31]
	v_mul_f32_e32 v15, v14, v14
	v_pk_add_f32 v[30:31], v[30:31], v[14:15]
	s_nop 1
	v_mov_b32_dpp v202, v30 quad_perm:[1,0,3,2] row_mask:0xf bank_mask:0xf bound_ctrl:1
	v_mov_b32_dpp v203, v31 quad_perm:[1,0,3,2] row_mask:0xf bank_mask:0xf bound_ctrl:1
	v_pk_add_f32 v[30:31], v[30:31], v[202:203]
	s_nop 1
	v_mov_b32_dpp v202, v30 quad_perm:[2,3,0,1] row_mask:0xf bank_mask:0xf bound_ctrl:1
	v_mov_b32_dpp v203, v31 quad_perm:[2,3,0,1] row_mask:0xf bank_mask:0xf bound_ctrl:1
	v_pk_add_f32 v[30:31], v[30:31], v[202:203]
	s_nop 1
	v_mov_b32_dpp v202, v30 row_half_mirror row_mask:0xf bank_mask:0xf bound_ctrl:1
	v_mov_b32_dpp v203, v31 row_half_mirror row_mask:0xf bank_mask:0xf bound_ctrl:1
	v_pk_add_f32 v[30:31], v[30:31], v[202:203]
	s_nop 1
	v_mov_b32_dpp v202, v30 row_mirror row_mask:0xf bank_mask:0xf bound_ctrl:1
	v_mov_b32_dpp v203, v31 row_mirror row_mask:0xf bank_mask:0xf bound_ctrl:1
	s_and_saveexec_b64 s[6:7], vcc
	v_pk_add_f32 v[30:31], v[30:31], v[202:203]
	ds_write_b64 v179, v[30:31] offset:456
	s_or_b64 exec, exec, s[6:7]
	ds_read2_b32 v[202:203], v79 offset1:32
	ds_read2_b32 v[206:207], v79 offset0:64 offset1:96
	v_mov_b32_e32 v204, v64
	v_mov_b32_e32 v205, v32
	v_pk_add_f32 v[208:209], v[204:205], 0 op_sel_hi:[1,0]
	v_mov_b32_e32 v204, v48
	v_pk_add_f32 v[204:205], v[204:205], 0 op_sel_hi:[1,0]
	s_waitcnt lgkmcnt(1)
; DI void ag_st64(u64_t* p, u64_t v) { __hip_atomic_store(p, v, __ATOMIC_RELAXED, __HIP_MEMORY_SCOPE_AGENT); }
;   DI void operator()(f32x16 (&acc)[2][4], int grow0, int gcol0, int lane, int w, char* lds) {
;     ...
;           for (int nt = 0; nt < 4; ++nt) {
;             float v = (acc[mt][nt][i] + bia[nt]) * csc[nt];
;             float z = ALPHA * xr[nt * 32] + hs * v;
;             acc[mt][nt][i] = z; s1 += z; s2 += z * z;
;           }
;           s1 = row16_sum(s1); s2 = row16_sum(s2);
;           if ((lane & 15) == 0) { f32x2 sv = {s1, s2}; *(f32x2*)(redw + (mt * 32 + (i & 3) + 8 * (i >> 2)) * 2) = sv; }
;         }
;     }
;     __syncthreads();
;     u64_t* myslots = xstat + ((size_t)pm * 256) * 4;
;     if (tid < 256) {
;       float s1 = (red[tid * 2] + red[(256 + tid) * 2]) + (red[(512 + tid) * 2] + red[(768 + tid) * 2]);
;       float s2 = (red[tid * 2 + 1] + red[(256 + tid) * 2 + 1]) + (red[(512 + tid) * 2 + 1] + red[(768 + tid) * 2 + 1]);
;       ag_st64(myslots + tid * 4 + pn, ((u64_t)__float_as_uint(s2) << 32) | (u64_t)__float_as_uint(s1));
	v_mov_b32_e32 v212, v202
	s_waitcnt lgkmcnt(0)
	v_mov_b32_e32 v213, v206
	s_mov_b32 s2, s67
	v_mov_b32_e32 v226, v203
	v_mov_b32_e32 v227, v206
	v_pk_fma_f32 v[202:203], v[212:213], s[2:3], v[208:209] op_sel_hi:[1,0,1]
	v_pk_fma_f32 v[204:205], v[226:227], s[2:3], v[204:205] op_sel_hi:[1,0,1]
	v_pk_mul_f32 v[214:215], v[212:213], s[2:3] op_sel_hi:[1,0]
	v_pk_mul_f32 v[212:213], v[202:203], v[202:203]
	v_pk_mul_f32 v[226:227], v[204:205], v[204:205]
	v_pk_mov_b32 v[208:209], v[208:209], v[212:213] op_sel:[1,0]
	v_pk_mov_b32 v[212:213], v[214:215], v[226:227] op_sel:[1,0]
	v_add_f32_e32 v30, 0, v16
	v_pk_add_f32 v[208:209], v[208:209], v[212:213]
	v_pk_add_f32 v[212:213], v[202:203], v[204:205]
	v_pk_mul_f32 v[214:215], v[202:203], v[204:205]
	v_fmac_f32_e32 v30, 0x3fd744fd, v207
	v_mov_b32_e32 v213, v215
	v_pk_add_f32 v[208:209], v[212:213], v[208:209]
	v_mul_f32_e32 v31, v30, v30
	v_pk_add_f32 v[206:207], v[208:209], v[30:31]
	s_nop 1
	v_mov_b32_dpp v208, v206 quad_perm:[1,0,3,2] row_mask:0xf bank_mask:0xf bound_ctrl:1
	v_mov_b32_dpp v209, v207 quad_perm:[1,0,3,2] row_mask:0xf bank_mask:0xf bound_ctrl:1
	v_pk_add_f32 v[206:207], v[206:207], v[208:209]
	s_nop 1
	v_mov_b32_dpp v208, v206 quad_perm:[2,3,0,1] row_mask:0xf bank_mask:0xf bound_ctrl:1
	v_mov_b32_dpp v209, v207 quad_perm:[2,3,0,1] row_mask:0xf bank_mask:0xf bound_ctrl:1
	v_pk_add_f32 v[206:207], v[206:207], v[208:209]
	s_nop 1
	v_mov_b32_dpp v208, v206 row_half_mirror row_mask:0xf bank_mask:0xf bound_ctrl:1
	v_mov_b32_dpp v209, v207 row_half_mirror row_mask:0xf bank_mask:0xf bound_ctrl:1
	v_pk_add_f32 v[206:207], v[206:207], v[208:209]
	s_nop 1
	v_mov_b32_dpp v208, v206 row_mirror row_mask:0xf bank_mask:0xf bound_ctrl:1
	v_mov_b32_dpp v209, v207 row_mirror row_mask:0xf bank_mask:0xf bound_ctrl:1
	s_and_saveexec_b64 s[6:7], vcc
	v_pk_add_f32 v[206:207], v[206:207], v[208:209]
	ds_write_b64 v179, v[206:207] offset:464
	s_or_b64 exec, exec, s[6:7]
	ds_read2_b32 v[206:207], v93 offset1:32
	ds_read2_b32 v[208:209], v93 offset0:64 offset1:96
	v_mov_b32_e32 v32, v65
	v_pk_add_f32 v[64:65], v[32:33], 0 op_sel_hi:[1,0]
	v_mov_b32_e32 v32, v49
	v_pk_add_f32 v[48:49], v[32:33], 0 op_sel_hi:[1,0]
	s_waitcnt lgkmcnt(1)
	v_mov_b32_e32 v32, v206
	s_waitcnt lgkmcnt(0)
	v_mov_b32_e32 v33, v208
	s_mov_b32 s2, s67
	v_mov_b32_e32 v206, v207
	v_mov_b32_e32 v207, v208
	v_pk_mul_f32 v[212:213], v[32:33], s[2:3] op_sel_hi:[1,0]
	v_pk_fma_f32 v[32:33], v[32:33], s[2:3], v[64:65] op_sel_hi:[1,0,1]
	v_pk_fma_f32 v[48:49], v[206:207], s[2:3], v[48:49] op_sel_hi:[1,0,1]
	v_pk_mul_f32 v[214:215], v[32:33], v[32:33]
	v_pk_mul_f32 v[206:207], v[48:49], v[48:49]
	v_pk_mov_b32 v[64:65], v[64:65], v[214:215] op_sel:[1,0]
	v_pk_mov_b32 v[206:207], v[212:213], v[206:207] op_sel:[1,0]
	v_add_f32_e32 v16, 0, v17
	v_pk_add_f32 v[64:65], v[64:65], v[206:207]
	v_pk_add_f32 v[206:207], v[32:33], v[48:49]
	v_pk_mul_f32 v[212:213], v[32:33], v[48:49]
	v_fmac_f32_e32 v16, 0x3fd744fd, v209
	v_mov_b32_e32 v207, v213
	v_pk_add_f32 v[64:65], v[206:207], v[64:65]
	v_mul_f32_e32 v17, v16, v16
	v_pk_add_f32 v[64:65], v[64:65], v[16:17]
	s_nop 1
	v_mov_b32_dpp v206, v64 quad_perm:[1,0,3,2] row_mask:0xf bank_mask:0xf bound_ctrl:1
	v_mov_b32_dpp v207, v65 quad_perm:[1,0,3,2] row_mask:0xf bank_mask:0xf bound_ctrl:1
	v_pk_add_f32 v[64:65], v[64:65], v[206:207]
	s_nop 1
	v_mov_b32_dpp v206, v64 quad_perm:[2,3,0,1] row_mask:0xf bank_mask:0xf bound_ctrl:1
	v_mov_b32_dpp v207, v65 quad_perm:[2,3,0,1] row_mask:0xf bank_mask:0xf bound_ctrl:1
	v_pk_add_f32 v[64:65], v[64:65], v[206:207]
	s_nop 1
	v_mov_b32_dpp v206, v64 row_half_mirror row_mask:0xf bank_mask:0xf bound_ctrl:1
	v_mov_b32_dpp v207, v65 row_half_mirror row_mask:0xf bank_mask:0xf bound_ctrl:1
	v_pk_add_f32 v[64:65], v[64:65], v[206:207]
	s_nop 1
	v_mov_b32_dpp v206, v64 row_mirror row_mask:0xf bank_mask:0xf bound_ctrl:1
	v_mov_b32_dpp v207, v65 row_mirror row_mask:0xf bank_mask:0xf bound_ctrl:1
	s_and_saveexec_b64 s[6:7], vcc
	v_pk_add_f32 v[64:65], v[64:65], v[206:207]
	ds_write_b64 v179, v[64:65] offset:472
	s_or_b64 exec, exec, s[6:7]
	v_ashrrev_i32_e32 v206, 8, v163
	v_ashrrev_i32_e32 v207, 31, v206
	v_lshlrev_b64 v[64:65], 13, v[206:207]
	v_lshl_add_u64 v[64:65], s[8:9], 0, v[64:65]
	v_cmp_gt_i32_e64 s[40:41], s60, v164
	v_ashrrev_i32_e32 v201, 31, v200
	s_waitcnt lgkmcnt(0)
	s_barrier
	s_and_saveexec_b64 s[6:7], s[40:41]
	s_cbranch_execz .LBB0_599
	v_lshl_add_u32 v0, v164, 3, v221
	ds_read2st64_b64 v[212:215], v0 offset1:4
	ds_read2st64_b64 v[226:229], v0 offset0:8 offset1:12
	v_ashrrev_i32_e32 v208, 8, v182
	v_ashrrev_i32_e32 v209, 31, v208
	s_waitcnt lgkmcnt(1)
	v_mov_b32_e32 v230, v212
	s_waitcnt lgkmcnt(0)
	v_mov_b32_e32 v231, v226
	v_mov_b32_e32 v232, v214
	v_mov_b32_e32 v233, v228
	v_mov_b32_e32 v226, v213
	v_mov_b32_e32 v228, v215
	v_pk_add_f32 v[230:231], v[230:231], v[232:233]
	v_pk_add_f32 v[212:213], v[226:227], v[228:229]
	v_pk_add_f32 v[230:231], v[230:231], v[230:231] op_sel:[0,1] op_sel_hi:[1,0]
	v_pk_add_f32 v[212:213], v[212:213], v[212:213] op_sel:[0,1] op_sel_hi:[1,0]
	v_lshl_add_u64 v[214:215], v[200:201], 3, v[64:65]
	v_lshl_add_u64 v[208:209], v[208:209], 3, v[214:215]
	v_mov_b32_e32 v231, v212
	global_store_dwordx2 v[208:209], v[230:231], off sc1
